# strategy 4: one static s_setprio 1 for the younger wave half (waves 4-7) around each GEMM main loop, per-segment priority flips deleted
# speedup vs baseline: 1.0084x; 1.0084x over previous
.LBB0_445:
	s_add_u32 s56, s62, 0xb0080
	s_addc_u32 s57, s63, 0
	s_add_u32 s62, s60, 0x100
	v_mov_b32_e32 v2, 0
	s_addc_u32 s63, s61, 0
	s_mov_b32 s84, -2
	s_waitcnt lgkmcnt(0)
	s_add_i32 s22, 0, 0x10000
	s_add_i32 s23, 0, 0x14000
	v_add_u32_e32 v134, s22, v191
	v_add_u32_e32 v182, s23, v191
	ds_read_b128 v[114:117], v134
	ds_read_b128 v[126:129], v134 offset:1024
	ds_read_b128 v[130:133], v134 offset:2048
	ds_read_b128 v[134:137], v134 offset:3072
	ds_read_b128 v[146:149], v182
	ds_read_b128 v[150:153], v182 offset:1024
	ds_read_b128 v[158:161], v182 offset:2048
	ds_read_b128 v[182:185], v182 offset:3072
	ds_read_b128 v[186:189], v193
	ds_read_b128 v[194:197], v193 offset:1024
	ds_read_b128 v[198:201], v193 offset:2048
	ds_read_b128 v[214:217], v193 offset:3072
	ds_read_b128 v[218:221], v193 offset:4096
	ds_read_b128 v[222:225], v193 offset:5120
	ds_read_b128 v[226:229], v193 offset:6144
	ds_read_b128 v[230:233], v193 offset:7168
	s_mov_b64 s[12:13], 0xb0000
	s_mov_b64 s[86:87], 0x108000
	s_mov_b64 s[96:97], 0x58080
	s_mov_b64 vcc, 0xb0080
	s_mov_b64 s[0:1], 0x108080
	s_cmp_eq_u64 s[40:41], 0
	s_cbranch_scc0 .Lpr_446
	s_setprio 1

.Lmid1_446:
	s_add_i32 s22, 0, 0x10000
	s_add_i32 s23, 0, 0x14000
	s_add_u32 s20, s56, 0xfff50080
	s_addc_u32 s21, s57, -1
	s_cmp_eq_u32 s84, 40
	s_cselect_b32 s61, s49, s21
	s_cselect_b32 s60, s48, s20
	s_cselect_b32 s21, s51, s63
	s_cselect_b32 s20, s50, s62
	s_add_i32 m0, s47, 0xc000
	v_lshl_add_u64 v[162:163], s[56:57], 0, v[156:157]
	global_load_lds_dwordx4 v[162:163], off
	v_lshl_add_u64 v[162:163], v[162:163], 0, s[2:3]
	s_add_i32 m0, s47, 0xe000
	s_nop 0
	global_load_lds_dwordx4 v[162:163], off
	s_waitcnt vmcnt(8)
	s_waitcnt lgkmcnt(0)
	s_barrier
	s_waitcnt lgkmcnt(0)
	v_mfma_f32_16x16x32_bf16 v[142:145], v[114:117], v[186:189], 0
	v_mfma_f32_16x16x32_bf16 v[142:145], v[126:129], v[194:197], v[142:145]
	v_mfma_f32_16x16x32_bf16 v[138:141], v[130:133], v[186:189], 0
	v_mfma_f32_16x16x32_bf16 v[138:141], v[134:137], v[194:197], v[138:141]
	v_mfma_f32_16x16x32_bf16 v[110:113], v[114:117], v[198:201], 0
	v_mfma_f32_16x16x32_bf16 v[110:113], v[126:129], v[214:217], v[110:113]
	v_mfma_f32_16x16x32_bf16 v[106:109], v[130:133], v[198:201], 0
	v_mfma_f32_16x16x32_bf16 v[106:109], v[134:137], v[214:217], v[106:109]
	v_mfma_f32_16x16x32_bf16 v[94:97], v[114:117], v[218:221], 0
	v_mfma_f32_16x16x32_bf16 v[94:97], v[126:129], v[222:225], v[94:97]
	v_mfma_f32_16x16x32_bf16 v[90:93], v[130:133], v[218:221], 0
	v_mfma_f32_16x16x32_bf16 v[90:93], v[134:137], v[222:225], v[90:93]
	v_mfma_f32_16x16x32_bf16 v[78:81], v[114:117], v[226:229], 0
	v_mfma_f32_16x16x32_bf16 v[78:81], v[126:129], v[230:233], v[78:81]
	v_mfma_f32_16x16x32_bf16 v[74:77], v[130:133], v[226:229], 0
	v_mfma_f32_16x16x32_bf16 v[74:77], v[134:137], v[230:233], v[74:77]
	v_mfma_f32_16x16x32_bf16 v[122:125], v[146:149], v[186:189], 0
	v_mfma_f32_16x16x32_bf16 v[122:125], v[150:153], v[194:197], v[122:125]
	v_mfma_f32_16x16x32_bf16 v[118:121], v[158:161], v[186:189], 0
	v_mfma_f32_16x16x32_bf16 v[118:121], v[182:185], v[194:197], v[118:121]
	v_mfma_f32_16x16x32_bf16 v[102:105], v[146:149], v[198:201], 0
	v_mfma_f32_16x16x32_bf16 v[102:105], v[150:153], v[214:217], v[102:105]
	v_mfma_f32_16x16x32_bf16 v[98:101], v[158:161], v[198:201], 0
	v_mfma_f32_16x16x32_bf16 v[98:101], v[182:185], v[214:217], v[98:101]
	v_mfma_f32_16x16x32_bf16 v[86:89], v[146:149], v[218:221], 0
	v_mfma_f32_16x16x32_bf16 v[86:89], v[150:153], v[222:225], v[86:89]
	v_mfma_f32_16x16x32_bf16 v[82:85], v[158:161], v[218:221], 0
	v_mfma_f32_16x16x32_bf16 v[82:85], v[182:185], v[222:225], v[82:85]
	v_mfma_f32_16x16x32_bf16 v[70:73], v[146:149], v[226:229], 0
	v_mfma_f32_16x16x32_bf16 v[70:73], v[150:153], v[230:233], v[70:73]
	v_mfma_f32_16x16x32_bf16 v[66:69], v[158:161], v[226:229], 0
	v_mfma_f32_16x16x32_bf16 v[66:69], v[182:185], v[230:233], v[66:69]
	s_barrier
	ds_read_b128 v[186:189], v193 offset:16384
	ds_read_b128 v[194:197], v193 offset:17408
	ds_read_b128 v[198:201], v193 offset:18432
	ds_read_b128 v[214:217], v193 offset:19456
	ds_read_b128 v[218:221], v193 offset:20480
	ds_read_b128 v[222:225], v193 offset:21504
	ds_read_b128 v[226:229], v193 offset:22528
	ds_read_b128 v[230:233], v193 offset:23552
	v_lshl_add_u64 v[162:163], s[20:21], 0, v[0:1]
	s_add_i32 s20, s22, s46
	s_mov_b32 m0, s20
	s_nop 0
	s_nop 0
	global_load_lds_dwordx4 v[162:163], off
	v_lshl_add_u64 v[202:203], v[162:163], 0, s[2:3]
	s_add_i32 m0, s20, 0x2000
	s_add_i32 s20, s23, s46
	global_load_lds_dwordx4 v[202:203], off
	v_lshl_add_u64 v[202:203], v[162:163], 0, s[12:13]
	s_mov_b32 m0, s20
	s_nop 0
	global_load_lds_dwordx4 v[202:203], off
	v_lshl_add_u64 v[202:203], v[162:163], 0, s[86:87]
	s_add_i32 m0, s20, 0x2000
	s_nop 0
	global_load_lds_dwordx4 v[202:203], off
	v_lshl_add_u64 v[202:203], s[60:61], 0, v[154:155]
	s_mov_b32 m0, s47
	v_lshl_add_u64 v[234:235], v[202:203], 0, s[2:3]
	global_load_lds_dwordx4 v[202:203], off
	s_mov_b32 m0, s68
	s_nop 0
	global_load_lds_dwordx4 v[234:235], off
	s_waitcnt vmcnt(8)
	s_waitcnt lgkmcnt(0)
	s_barrier
	s_waitcnt lgkmcnt(0)
	v_mfma_f32_16x16x32_bf16 v[62:65], v[114:117], v[186:189], 0
	v_mfma_f32_16x16x32_bf16 v[62:65], v[126:129], v[194:197], v[62:65]
	v_mfma_f32_16x16x32_bf16 v[58:61], v[130:133], v[186:189], 0
	v_mfma_f32_16x16x32_bf16 v[58:61], v[134:137], v[194:197], v[58:61]
	v_mfma_f32_16x16x32_bf16 v[46:49], v[114:117], v[198:201], 0
	v_mfma_f32_16x16x32_bf16 v[46:49], v[126:129], v[214:217], v[46:49]
	v_mfma_f32_16x16x32_bf16 v[42:45], v[130:133], v[198:201], 0
	v_mfma_f32_16x16x32_bf16 v[42:45], v[134:137], v[214:217], v[42:45]
	v_mfma_f32_16x16x32_bf16 v[30:33], v[114:117], v[218:221], 0
	v_mfma_f32_16x16x32_bf16 v[30:33], v[126:129], v[222:225], v[30:33]
	v_mfma_f32_16x16x32_bf16 v[26:29], v[130:133], v[218:221], 0
	v_mfma_f32_16x16x32_bf16 v[26:29], v[134:137], v[222:225], v[26:29]
	v_mfma_f32_16x16x32_bf16 v[14:17], v[114:117], v[226:229], 0
	v_mfma_f32_16x16x32_bf16 v[14:17], v[126:129], v[230:233], v[14:17]
	v_mfma_f32_16x16x32_bf16 v[10:13], v[130:133], v[226:229], 0
	v_mfma_f32_16x16x32_bf16 v[10:13], v[134:137], v[230:233], v[10:13]
	v_mfma_f32_16x16x32_bf16 v[54:57], v[146:149], v[186:189], 0
	v_mfma_f32_16x16x32_bf16 v[54:57], v[150:153], v[194:197], v[54:57]
	v_mfma_f32_16x16x32_bf16 v[50:53], v[158:161], v[186:189], 0
	v_mfma_f32_16x16x32_bf16 v[50:53], v[182:185], v[194:197], v[50:53]
	v_mfma_f32_16x16x32_bf16 v[38:41], v[146:149], v[198:201], 0
	v_mfma_f32_16x16x32_bf16 v[38:41], v[150:153], v[214:217], v[38:41]
	v_mfma_f32_16x16x32_bf16 v[34:37], v[158:161], v[198:201], 0
	v_mfma_f32_16x16x32_bf16 v[34:37], v[182:185], v[214:217], v[34:37]
	v_mfma_f32_16x16x32_bf16 v[22:25], v[146:149], v[218:221], 0
	v_mfma_f32_16x16x32_bf16 v[22:25], v[150:153], v[222:225], v[22:25]
	v_mfma_f32_16x16x32_bf16 v[18:21], v[158:161], v[218:221], 0
	v_mfma_f32_16x16x32_bf16 v[18:21], v[182:185], v[222:225], v[18:21]
	v_mfma_f32_16x16x32_bf16 v[6:9], v[146:149], v[226:229], 0
	v_mfma_f32_16x16x32_bf16 v[6:9], v[150:153], v[230:233], v[6:9]
	v_mfma_f32_16x16x32_bf16 v[2:5], v[158:161], v[226:229], 0
	v_mfma_f32_16x16x32_bf16 v[2:5], v[182:185], v[230:233], v[2:5]
	s_barrier
	s_add_i32 s20, 0, 0x18000
	s_add_i32 s21, 0, 0x1c000
	v_add_u32_e32 v134, s20, v191
	v_add_u32_e32 v182, s21, v191
	ds_read_b128 v[114:117], v134
	ds_read_b128 v[126:129], v134 offset:1024
	ds_read_b128 v[130:133], v134 offset:2048
	ds_read_b128 v[134:137], v134 offset:3072
	ds_read_b128 v[146:149], v182
	ds_read_b128 v[150:153], v182 offset:1024
	ds_read_b128 v[158:161], v182 offset:2048
	ds_read_b128 v[182:185], v182 offset:3072
	ds_read_b128 v[186:189], v193 offset:32768
	ds_read_b128 v[194:197], v193 offset:33792
	ds_read_b128 v[198:201], v193 offset:34816
	ds_read_b128 v[214:217], v193 offset:35840
	ds_read_b128 v[218:221], v193 offset:36864
	ds_read_b128 v[222:225], v193 offset:37888
	ds_read_b128 v[226:229], v193 offset:38912
	ds_read_b128 v[230:233], v193 offset:39936
	s_mov_b32 m0, s69
	v_lshl_add_u64 v[234:235], v[202:203], 0, s[12:13]
	global_load_lds_dwordx4 v[234:235], off
	v_lshl_add_u64 v[234:235], v[202:203], 0, s[86:87]
	s_mov_b32 m0, s76
	s_nop 0
	global_load_lds_dwordx4 v[234:235], off
	s_waitcnt vmcnt(8)
	s_waitcnt lgkmcnt(0)
	s_barrier
	s_waitcnt lgkmcnt(0)
	v_mfma_f32_16x16x32_bf16 v[142:145], v[114:117], v[186:189], v[142:145]
	v_mfma_f32_16x16x32_bf16 v[142:145], v[126:129], v[194:197], v[142:145]
	v_mfma_f32_16x16x32_bf16 v[138:141], v[130:133], v[186:189], v[138:141]
	v_mfma_f32_16x16x32_bf16 v[138:141], v[134:137], v[194:197], v[138:141]
	v_mfma_f32_16x16x32_bf16 v[110:113], v[114:117], v[198:201], v[110:113]
	v_mfma_f32_16x16x32_bf16 v[110:113], v[126:129], v[214:217], v[110:113]
	v_mfma_f32_16x16x32_bf16 v[106:109], v[130:133], v[198:201], v[106:109]
	v_mfma_f32_16x16x32_bf16 v[106:109], v[134:137], v[214:217], v[106:109]
	v_mfma_f32_16x16x32_bf16 v[94:97], v[114:117], v[218:221], v[94:97]
	v_mfma_f32_16x16x32_bf16 v[94:97], v[126:129], v[222:225], v[94:97]
	v_mfma_f32_16x16x32_bf16 v[90:93], v[130:133], v[218:221], v[90:93]
	v_mfma_f32_16x16x32_bf16 v[90:93], v[134:137], v[222:225], v[90:93]
	v_mfma_f32_16x16x32_bf16 v[78:81], v[114:117], v[226:229], v[78:81]
	v_mfma_f32_16x16x32_bf16 v[78:81], v[126:129], v[230:233], v[78:81]
	v_mfma_f32_16x16x32_bf16 v[74:77], v[130:133], v[226:229], v[74:77]
	v_mfma_f32_16x16x32_bf16 v[74:77], v[134:137], v[230:233], v[74:77]
	v_mfma_f32_16x16x32_bf16 v[122:125], v[146:149], v[186:189], v[122:125]
	v_mfma_f32_16x16x32_bf16 v[122:125], v[150:153], v[194:197], v[122:125]
	v_mfma_f32_16x16x32_bf16 v[118:121], v[158:161], v[186:189], v[118:121]
	v_mfma_f32_16x16x32_bf16 v[118:121], v[182:185], v[194:197], v[118:121]
	v_mfma_f32_16x16x32_bf16 v[102:105], v[146:149], v[198:201], v[102:105]
	v_mfma_f32_16x16x32_bf16 v[102:105], v[150:153], v[214:217], v[102:105]
	v_mfma_f32_16x16x32_bf16 v[98:101], v[158:161], v[198:201], v[98:101]
	v_mfma_f32_16x16x32_bf16 v[98:101], v[182:185], v[214:217], v[98:101]
	v_mfma_f32_16x16x32_bf16 v[86:89], v[146:149], v[218:221], v[86:89]
	v_mfma_f32_16x16x32_bf16 v[86:89], v[150:153], v[222:225], v[86:89]
	v_mfma_f32_16x16x32_bf16 v[82:85], v[158:161], v[218:221], v[82:85]
	v_mfma_f32_16x16x32_bf16 v[82:85], v[182:185], v[222:225], v[82:85]
	v_mfma_f32_16x16x32_bf16 v[70:73], v[146:149], v[226:229], v[70:73]
	v_mfma_f32_16x16x32_bf16 v[70:73], v[150:153], v[230:233], v[70:73]
	v_mfma_f32_16x16x32_bf16 v[66:69], v[158:161], v[226:229], v[66:69]
	v_mfma_f32_16x16x32_bf16 v[66:69], v[182:185], v[230:233], v[66:69]
	s_barrier
	ds_read_b128 v[186:189], v193 offset:49152
	ds_read_b128 v[194:197], v193 offset:50176
	ds_read_b128 v[198:201], v193 offset:51200
	ds_read_b128 v[214:217], v193 offset:52224
	ds_read_b128 v[218:221], v193 offset:53248
	ds_read_b128 v[222:225], v193 offset:54272
	ds_read_b128 v[226:229], v193 offset:55296
	ds_read_b128 v[230:233], v193 offset:56320
	s_add_i32 s20, s20, s46
	s_mov_b32 m0, s20
	v_lshl_add_u64 v[234:235], v[162:163], 0, s[34:35]
	global_load_lds_dwordx4 v[234:235], off
	v_lshl_add_u64 v[234:235], v[162:163], 0, s[96:97]
	s_add_i32 m0, s20, 0x2000
	s_add_i32 s20, s21, s46
	global_load_lds_dwordx4 v[234:235], off
	v_lshl_add_u64 v[234:235], v[162:163], 0, vcc
	s_mov_b32 m0, s20
	v_lshl_add_u64 v[162:163], v[162:163], 0, s[0:1]
	global_load_lds_dwordx4 v[234:235], off
	s_add_i32 m0, s20, 0x2000
	s_nop 0
	global_load_lds_dwordx4 v[162:163], off
	v_lshl_add_u64 v[162:163], v[202:203], 0, s[34:35]
	s_mov_b32 m0, s77
	s_nop 0
	global_load_lds_dwordx4 v[162:163], off
	v_lshl_add_u64 v[162:163], v[202:203], 0, s[96:97]
	s_mov_b32 m0, s78
	s_nop 0
	global_load_lds_dwordx4 v[162:163], off
	s_waitcnt vmcnt(8)
	s_waitcnt lgkmcnt(0)
	s_barrier
	s_waitcnt lgkmcnt(0)
	v_mfma_f32_16x16x32_bf16 v[62:65], v[114:117], v[186:189], v[62:65]
	v_mfma_f32_16x16x32_bf16 v[62:65], v[126:129], v[194:197], v[62:65]
	v_mfma_f32_16x16x32_bf16 v[58:61], v[130:133], v[186:189], v[58:61]
	v_mfma_f32_16x16x32_bf16 v[58:61], v[134:137], v[194:197], v[58:61]
	v_mfma_f32_16x16x32_bf16 v[46:49], v[114:117], v[198:201], v[46:49]
	v_mfma_f32_16x16x32_bf16 v[46:49], v[126:129], v[214:217], v[46:49]
	v_mfma_f32_16x16x32_bf16 v[42:45], v[130:133], v[198:201], v[42:45]
	v_mfma_f32_16x16x32_bf16 v[42:45], v[134:137], v[214:217], v[42:45]
	v_mfma_f32_16x16x32_bf16 v[30:33], v[114:117], v[218:221], v[30:33]
	v_mfma_f32_16x16x32_bf16 v[30:33], v[126:129], v[222:225], v[30:33]
	v_mfma_f32_16x16x32_bf16 v[26:29], v[130:133], v[218:221], v[26:29]
	v_mfma_f32_16x16x32_bf16 v[26:29], v[134:137], v[222:225], v[26:29]
	v_mfma_f32_16x16x32_bf16 v[14:17], v[114:117], v[226:229], v[14:17]
	v_mfma_f32_16x16x32_bf16 v[14:17], v[126:129], v[230:233], v[14:17]
	v_mfma_f32_16x16x32_bf16 v[10:13], v[130:133], v[226:229], v[10:13]
	v_mfma_f32_16x16x32_bf16 v[10:13], v[134:137], v[230:233], v[10:13]
	s_add_i32 s84, s84, 2
	s_add_u32 s56, s56, 0x100
	s_addc_u32 s57, s57, 0
	s_add_u32 s62, s62, 0x100
	s_addc_u32 s63, s63, 0
	v_mfma_f32_16x16x32_bf16 v[54:57], v[146:149], v[186:189], v[54:57]
	v_mfma_f32_16x16x32_bf16 v[54:57], v[150:153], v[194:197], v[54:57]
	v_mfma_f32_16x16x32_bf16 v[50:53], v[158:161], v[186:189], v[50:53]
	v_mfma_f32_16x16x32_bf16 v[50:53], v[182:185], v[194:197], v[50:53]
	v_mfma_f32_16x16x32_bf16 v[38:41], v[146:149], v[198:201], v[38:41]
	v_mfma_f32_16x16x32_bf16 v[38:41], v[150:153], v[214:217], v[38:41]
	v_mfma_f32_16x16x32_bf16 v[34:37], v[158:161], v[198:201], v[34:37]
	v_mfma_f32_16x16x32_bf16 v[34:37], v[182:185], v[214:217], v[34:37]
	v_mfma_f32_16x16x32_bf16 v[22:25], v[146:149], v[218:221], v[22:25]
	v_mfma_f32_16x16x32_bf16 v[22:25], v[150:153], v[222:225], v[22:25]
	v_mfma_f32_16x16x32_bf16 v[18:21], v[158:161], v[218:221], v[18:21]
	v_mfma_f32_16x16x32_bf16 v[18:21], v[182:185], v[222:225], v[18:21]
	v_mfma_f32_16x16x32_bf16 v[6:9], v[146:149], v[226:229], v[6:9]
	v_mfma_f32_16x16x32_bf16 v[6:9], v[150:153], v[230:233], v[6:9]
	v_mfma_f32_16x16x32_bf16 v[2:5], v[158:161], v[226:229], v[2:5]
	v_mfma_f32_16x16x32_bf16 v[2:5], v[182:185], v[230:233], v[2:5]
	s_barrier
	s_branch .LBB0_446
	.p2alignl 6, 3212836864
.LBB0_446:
	s_add_i32 s22, 0, 0x10000
	s_add_i32 s23, 0, 0x14000
	v_add_u32_e32 v134, s22, v191
	v_add_u32_e32 v162, s23, v191
	ds_read_b128 v[114:117], v134
	ds_read_b128 v[126:129], v134 offset:1024
	ds_read_b128 v[130:133], v134 offset:2048
	ds_read_b128 v[134:137], v134 offset:3072
	ds_read_b128 v[146:149], v162
	ds_read_b128 v[150:153], v162 offset:1024
	ds_read_b128 v[158:161], v162 offset:2048
	ds_read_b128 v[182:185], v162 offset:3072
	ds_read_b128 v[186:189], v193
	ds_read_b128 v[194:197], v193 offset:1024
	ds_read_b128 v[198:201], v193 offset:2048
	ds_read_b128 v[214:217], v193 offset:3072
	ds_read_b128 v[218:221], v193 offset:4096
	ds_read_b128 v[222:225], v193 offset:5120
	ds_read_b128 v[226:229], v193 offset:6144
	ds_read_b128 v[230:233], v193 offset:7168
	s_add_u32 s20, s56, 0xfff50080
	s_addc_u32 s21, s57, -1
	s_cmp_eq_u32 s84, 40
	s_cselect_b32 s61, s49, s21
	s_cselect_b32 s60, s48, s20
	s_cselect_b32 s21, s51, s63
	s_cselect_b32 s20, s50, s62
	s_add_i32 m0, s47, 0xc000
	v_lshl_add_u64 v[162:163], s[56:57], 0, v[156:157]
	global_load_lds_dwordx4 v[162:163], off
	v_lshl_add_u64 v[162:163], v[162:163], 0, s[2:3]
	s_add_i32 m0, s47, 0xe000
	s_nop 0
	global_load_lds_dwordx4 v[162:163], off
	s_waitcnt vmcnt(8)
	s_waitcnt lgkmcnt(0)
	s_barrier
	s_waitcnt lgkmcnt(0)
	v_mfma_f32_16x16x32_bf16 v[142:145], v[114:117], v[186:189], v[142:145]
	v_mfma_f32_16x16x32_bf16 v[142:145], v[126:129], v[194:197], v[142:145]
	v_mfma_f32_16x16x32_bf16 v[138:141], v[130:133], v[186:189], v[138:141]
	v_mfma_f32_16x16x32_bf16 v[138:141], v[134:137], v[194:197], v[138:141]
	v_mfma_f32_16x16x32_bf16 v[110:113], v[114:117], v[198:201], v[110:113]
	v_mfma_f32_16x16x32_bf16 v[110:113], v[126:129], v[214:217], v[110:113]
	v_mfma_f32_16x16x32_bf16 v[106:109], v[130:133], v[198:201], v[106:109]
	v_mfma_f32_16x16x32_bf16 v[106:109], v[134:137], v[214:217], v[106:109]
	v_mfma_f32_16x16x32_bf16 v[94:97], v[114:117], v[218:221], v[94:97]
	v_mfma_f32_16x16x32_bf16 v[94:97], v[126:129], v[222:225], v[94:97]
	v_mfma_f32_16x16x32_bf16 v[90:93], v[130:133], v[218:221], v[90:93]
	v_mfma_f32_16x16x32_bf16 v[90:93], v[134:137], v[222:225], v[90:93]
	v_mfma_f32_16x16x32_bf16 v[78:81], v[114:117], v[226:229], v[78:81]
	v_mfma_f32_16x16x32_bf16 v[78:81], v[126:129], v[230:233], v[78:81]
	v_mfma_f32_16x16x32_bf16 v[74:77], v[130:133], v[226:229], v[74:77]
	v_mfma_f32_16x16x32_bf16 v[74:77], v[134:137], v[230:233], v[74:77]
	v_mfma_f32_16x16x32_bf16 v[122:125], v[146:149], v[186:189], v[122:125]
	v_mfma_f32_16x16x32_bf16 v[122:125], v[150:153], v[194:197], v[122:125]
	v_mfma_f32_16x16x32_bf16 v[118:121], v[158:161], v[186:189], v[118:121]
	v_mfma_f32_16x16x32_bf16 v[118:121], v[182:185], v[194:197], v[118:121]
	v_mfma_f32_16x16x32_bf16 v[102:105], v[146:149], v[198:201], v[102:105]
	v_mfma_f32_16x16x32_bf16 v[102:105], v[150:153], v[214:217], v[102:105]
	v_mfma_f32_16x16x32_bf16 v[98:101], v[158:161], v[198:201], v[98:101]
	v_mfma_f32_16x16x32_bf16 v[98:101], v[182:185], v[214:217], v[98:101]
	v_mfma_f32_16x16x32_bf16 v[86:89], v[146:149], v[218:221], v[86:89]
	v_mfma_f32_16x16x32_bf16 v[86:89], v[150:153], v[222:225], v[86:89]
	v_mfma_f32_16x16x32_bf16 v[82:85], v[158:161], v[218:221], v[82:85]
	v_mfma_f32_16x16x32_bf16 v[82:85], v[182:185], v[222:225], v[82:85]
	v_mfma_f32_16x16x32_bf16 v[70:73], v[146:149], v[226:229], v[70:73]
	v_mfma_f32_16x16x32_bf16 v[70:73], v[150:153], v[230:233], v[70:73]
	v_mfma_f32_16x16x32_bf16 v[66:69], v[158:161], v[226:229], v[66:69]
	v_mfma_f32_16x16x32_bf16 v[66:69], v[182:185], v[230:233], v[66:69]
	s_barrier
	ds_read_b128 v[186:189], v193 offset:16384
	ds_read_b128 v[194:197], v193 offset:17408
	ds_read_b128 v[198:201], v193 offset:18432
	ds_read_b128 v[214:217], v193 offset:19456
	ds_read_b128 v[218:221], v193 offset:20480
	ds_read_b128 v[222:225], v193 offset:21504
	ds_read_b128 v[226:229], v193 offset:22528
	ds_read_b128 v[230:233], v193 offset:23552
	v_lshl_add_u64 v[162:163], s[20:21], 0, v[0:1]
	s_add_i32 s20, s22, s46
	s_mov_b32 m0, s20
	s_nop 0
	s_nop 0
	global_load_lds_dwordx4 v[162:163], off
	v_lshl_add_u64 v[202:203], v[162:163], 0, s[2:3]
	s_add_i32 m0, s20, 0x2000
	s_add_i32 s20, s23, s46
	global_load_lds_dwordx4 v[202:203], off
	v_lshl_add_u64 v[202:203], v[162:163], 0, s[12:13]
	s_mov_b32 m0, s20
	s_nop 0
	global_load_lds_dwordx4 v[202:203], off
	v_lshl_add_u64 v[202:203], v[162:163], 0, s[86:87]
	s_add_i32 m0, s20, 0x2000
	s_nop 0
	global_load_lds_dwordx4 v[202:203], off
	v_lshl_add_u64 v[202:203], s[60:61], 0, v[154:155]
	s_mov_b32 m0, s47
	v_lshl_add_u64 v[234:235], v[202:203], 0, s[2:3]
	global_load_lds_dwordx4 v[202:203], off
	s_mov_b32 m0, s68
	s_nop 0
	global_load_lds_dwordx4 v[234:235], off
	s_waitcnt vmcnt(8)
	s_waitcnt lgkmcnt(0)
	s_barrier
	s_waitcnt lgkmcnt(0)
	v_mfma_f32_16x16x32_bf16 v[62:65], v[114:117], v[186:189], v[62:65]
	v_mfma_f32_16x16x32_bf16 v[62:65], v[126:129], v[194:197], v[62:65]
	v_mfma_f32_16x16x32_bf16 v[58:61], v[130:133], v[186:189], v[58:61]
	v_mfma_f32_16x16x32_bf16 v[58:61], v[134:137], v[194:197], v[58:61]
	v_mfma_f32_16x16x32_bf16 v[46:49], v[114:117], v[198:201], v[46:49]
	v_mfma_f32_16x16x32_bf16 v[46:49], v[126:129], v[214:217], v[46:49]
	v_mfma_f32_16x16x32_bf16 v[42:45], v[130:133], v[198:201], v[42:45]
	v_mfma_f32_16x16x32_bf16 v[42:45], v[134:137], v[214:217], v[42:45]
	v_mfma_f32_16x16x32_bf16 v[30:33], v[114:117], v[218:221], v[30:33]
	v_mfma_f32_16x16x32_bf16 v[30:33], v[126:129], v[222:225], v[30:33]
	v_mfma_f32_16x16x32_bf16 v[26:29], v[130:133], v[218:221], v[26:29]
	v_mfma_f32_16x16x32_bf16 v[26:29], v[134:137], v[222:225], v[26:29]
	v_mfma_f32_16x16x32_bf16 v[14:17], v[114:117], v[226:229], v[14:17]
	v_mfma_f32_16x16x32_bf16 v[14:17], v[126:129], v[230:233], v[14:17]
	v_mfma_f32_16x16x32_bf16 v[10:13], v[130:133], v[226:229], v[10:13]
	v_mfma_f32_16x16x32_bf16 v[10:13], v[134:137], v[230:233], v[10:13]
	v_mfma_f32_16x16x32_bf16 v[54:57], v[146:149], v[186:189], v[54:57]
	v_mfma_f32_16x16x32_bf16 v[54:57], v[150:153], v[194:197], v[54:57]
	v_mfma_f32_16x16x32_bf16 v[50:53], v[158:161], v[186:189], v[50:53]
	v_mfma_f32_16x16x32_bf16 v[50:53], v[182:185], v[194:197], v[50:53]
	v_mfma_f32_16x16x32_bf16 v[38:41], v[146:149], v[198:201], v[38:41]
	v_mfma_f32_16x16x32_bf16 v[38:41], v[150:153], v[214:217], v[38:41]
	v_mfma_f32_16x16x32_bf16 v[34:37], v[158:161], v[198:201], v[34:37]
	v_mfma_f32_16x16x32_bf16 v[34:37], v[182:185], v[214:217], v[34:37]
	v_mfma_f32_16x16x32_bf16 v[22:25], v[146:149], v[218:221], v[22:25]
	v_mfma_f32_16x16x32_bf16 v[22:25], v[150:153], v[222:225], v[22:25]
	v_mfma_f32_16x16x32_bf16 v[18:21], v[158:161], v[218:221], v[18:21]
	v_mfma_f32_16x16x32_bf16 v[18:21], v[182:185], v[222:225], v[18:21]
	v_mfma_f32_16x16x32_bf16 v[6:9], v[146:149], v[226:229], v[6:9]
	v_mfma_f32_16x16x32_bf16 v[6:9], v[150:153], v[230:233], v[6:9]
	v_mfma_f32_16x16x32_bf16 v[2:5], v[158:161], v[226:229], v[2:5]
	v_mfma_f32_16x16x32_bf16 v[2:5], v[182:185], v[230:233], v[2:5]
	s_barrier
	s_add_i32 s20, 0, 0x18000
	s_add_i32 s21, 0, 0x1c000
	v_add_u32_e32 v134, s20, v191
	v_add_u32_e32 v182, s21, v191
	ds_read_b128 v[114:117], v134
	ds_read_b128 v[126:129], v134 offset:1024
	ds_read_b128 v[130:133], v134 offset:2048
	ds_read_b128 v[134:137], v134 offset:3072
	ds_read_b128 v[146:149], v182
	ds_read_b128 v[150:153], v182 offset:1024
	ds_read_b128 v[158:161], v182 offset:2048
	ds_read_b128 v[182:185], v182 offset:3072
	ds_read_b128 v[186:189], v193 offset:32768
	ds_read_b128 v[194:197], v193 offset:33792
	ds_read_b128 v[198:201], v193 offset:34816
	ds_read_b128 v[214:217], v193 offset:35840
	ds_read_b128 v[218:221], v193 offset:36864
	ds_read_b128 v[222:225], v193 offset:37888
	ds_read_b128 v[226:229], v193 offset:38912
	ds_read_b128 v[230:233], v193 offset:39936
	s_mov_b32 m0, s69
	v_lshl_add_u64 v[234:235], v[202:203], 0, s[12:13]
	global_load_lds_dwordx4 v[234:235], off
	v_lshl_add_u64 v[234:235], v[202:203], 0, s[86:87]
	s_mov_b32 m0, s76
	s_nop 0
	global_load_lds_dwordx4 v[234:235], off
	s_waitcnt vmcnt(8)
	s_waitcnt lgkmcnt(0)
	s_barrier
	s_waitcnt lgkmcnt(0)
	v_mfma_f32_16x16x32_bf16 v[142:145], v[114:117], v[186:189], v[142:145]
	v_mfma_f32_16x16x32_bf16 v[142:145], v[126:129], v[194:197], v[142:145]
	v_mfma_f32_16x16x32_bf16 v[138:141], v[130:133], v[186:189], v[138:141]
	v_mfma_f32_16x16x32_bf16 v[138:141], v[134:137], v[194:197], v[138:141]
	v_mfma_f32_16x16x32_bf16 v[110:113], v[114:117], v[198:201], v[110:113]
	v_mfma_f32_16x16x32_bf16 v[110:113], v[126:129], v[214:217], v[110:113]
	v_mfma_f32_16x16x32_bf16 v[106:109], v[130:133], v[198:201], v[106:109]
	v_mfma_f32_16x16x32_bf16 v[106:109], v[134:137], v[214:217], v[106:109]
	v_mfma_f32_16x16x32_bf16 v[94:97], v[114:117], v[218:221], v[94:97]
	v_mfma_f32_16x16x32_bf16 v[94:97], v[126:129], v[222:225], v[94:97]
	v_mfma_f32_16x16x32_bf16 v[90:93], v[130:133], v[218:221], v[90:93]
	v_mfma_f32_16x16x32_bf16 v[90:93], v[134:137], v[222:225], v[90:93]
	v_mfma_f32_16x16x32_bf16 v[78:81], v[114:117], v[226:229], v[78:81]
	v_mfma_f32_16x16x32_bf16 v[78:81], v[126:129], v[230:233], v[78:81]
	v_mfma_f32_16x16x32_bf16 v[74:77], v[130:133], v[226:229], v[74:77]
	v_mfma_f32_16x16x32_bf16 v[74:77], v[134:137], v[230:233], v[74:77]
	v_mfma_f32_16x16x32_bf16 v[122:125], v[146:149], v[186:189], v[122:125]
	v_mfma_f32_16x16x32_bf16 v[122:125], v[150:153], v[194:197], v[122:125]
	v_mfma_f32_16x16x32_bf16 v[118:121], v[158:161], v[186:189], v[118:121]
	v_mfma_f32_16x16x32_bf16 v[118:121], v[182:185], v[194:197], v[118:121]
	v_mfma_f32_16x16x32_bf16 v[102:105], v[146:149], v[198:201], v[102:105]
	v_mfma_f32_16x16x32_bf16 v[102:105], v[150:153], v[214:217], v[102:105]
	v_mfma_f32_16x16x32_bf16 v[98:101], v[158:161], v[198:201], v[98:101]
	v_mfma_f32_16x16x32_bf16 v[98:101], v[182:185], v[214:217], v[98:101]
	v_mfma_f32_16x16x32_bf16 v[86:89], v[146:149], v[218:221], v[86:89]
	v_mfma_f32_16x16x32_bf16 v[86:89], v[150:153], v[222:225], v[86:89]
	v_mfma_f32_16x16x32_bf16 v[82:85], v[158:161], v[218:221], v[82:85]
	v_mfma_f32_16x16x32_bf16 v[82:85], v[182:185], v[222:225], v[82:85]
	v_mfma_f32_16x16x32_bf16 v[70:73], v[146:149], v[226:229], v[70:73]
	v_mfma_f32_16x16x32_bf16 v[70:73], v[150:153], v[230:233], v[70:73]
	v_mfma_f32_16x16x32_bf16 v[66:69], v[158:161], v[226:229], v[66:69]
	v_mfma_f32_16x16x32_bf16 v[66:69], v[182:185], v[230:233], v[66:69]
	s_barrier
	ds_read_b128 v[186:189], v193 offset:49152
	ds_read_b128 v[194:197], v193 offset:50176
	ds_read_b128 v[198:201], v193 offset:51200
	ds_read_b128 v[214:217], v193 offset:52224
	ds_read_b128 v[218:221], v193 offset:53248
	ds_read_b128 v[222:225], v193 offset:54272
	ds_read_b128 v[226:229], v193 offset:55296
	ds_read_b128 v[230:233], v193 offset:56320
	s_add_i32 s20, s20, s46
	s_mov_b32 m0, s20
	v_lshl_add_u64 v[234:235], v[162:163], 0, s[34:35]
	global_load_lds_dwordx4 v[234:235], off
	v_lshl_add_u64 v[234:235], v[162:163], 0, s[96:97]
	s_add_i32 m0, s20, 0x2000
	s_add_i32 s20, s21, s46
	global_load_lds_dwordx4 v[234:235], off
	v_lshl_add_u64 v[234:235], v[162:163], 0, vcc
	s_mov_b32 m0, s20
	v_lshl_add_u64 v[162:163], v[162:163], 0, s[0:1]
	global_load_lds_dwordx4 v[234:235], off
	s_add_i32 m0, s20, 0x2000
	s_nop 0
	global_load_lds_dwordx4 v[162:163], off
	v_lshl_add_u64 v[162:163], v[202:203], 0, s[34:35]
	s_mov_b32 m0, s77
	s_nop 0
	global_load_lds_dwordx4 v[162:163], off
	v_lshl_add_u64 v[162:163], v[202:203], 0, s[96:97]
	s_mov_b32 m0, s78
	s_nop 0
	global_load_lds_dwordx4 v[162:163], off
	s_waitcnt vmcnt(8)
	s_waitcnt lgkmcnt(0)
	s_barrier
	s_waitcnt lgkmcnt(0)
	v_mfma_f32_16x16x32_bf16 v[62:65], v[114:117], v[186:189], v[62:65]
	v_mfma_f32_16x16x32_bf16 v[62:65], v[126:129], v[194:197], v[62:65]
	v_mfma_f32_16x16x32_bf16 v[58:61], v[130:133], v[186:189], v[58:61]
	v_mfma_f32_16x16x32_bf16 v[58:61], v[134:137], v[194:197], v[58:61]
	v_mfma_f32_16x16x32_bf16 v[46:49], v[114:117], v[198:201], v[46:49]
	v_mfma_f32_16x16x32_bf16 v[46:49], v[126:129], v[214:217], v[46:49]
	v_mfma_f32_16x16x32_bf16 v[42:45], v[130:133], v[198:201], v[42:45]
	v_mfma_f32_16x16x32_bf16 v[42:45], v[134:137], v[214:217], v[42:45]
	v_mfma_f32_16x16x32_bf16 v[30:33], v[114:117], v[218:221], v[30:33]
	v_mfma_f32_16x16x32_bf16 v[30:33], v[126:129], v[222:225], v[30:33]
	v_mfma_f32_16x16x32_bf16 v[26:29], v[130:133], v[218:221], v[26:29]
	v_mfma_f32_16x16x32_bf16 v[26:29], v[134:137], v[222:225], v[26:29]
	v_mfma_f32_16x16x32_bf16 v[14:17], v[114:117], v[226:229], v[14:17]
	v_mfma_f32_16x16x32_bf16 v[14:17], v[126:129], v[230:233], v[14:17]
	v_mfma_f32_16x16x32_bf16 v[10:13], v[130:133], v[226:229], v[10:13]
	v_mfma_f32_16x16x32_bf16 v[10:13], v[134:137], v[230:233], v[10:13]
	s_add_i32 s84, s84, 2
	s_add_u32 s56, s56, 0x100
	s_addc_u32 s57, s57, 0
	s_add_u32 s62, s62, 0x100
	s_addc_u32 s63, s63, 0
	v_mfma_f32_16x16x32_bf16 v[54:57], v[146:149], v[186:189], v[54:57]
	v_mfma_f32_16x16x32_bf16 v[54:57], v[150:153], v[194:197], v[54:57]
	v_mfma_f32_16x16x32_bf16 v[50:53], v[158:161], v[186:189], v[50:53]
	v_mfma_f32_16x16x32_bf16 v[50:53], v[182:185], v[194:197], v[50:53]
	v_mfma_f32_16x16x32_bf16 v[38:41], v[146:149], v[198:201], v[38:41]
	v_mfma_f32_16x16x32_bf16 v[38:41], v[150:153], v[214:217], v[38:41]
	v_mfma_f32_16x16x32_bf16 v[34:37], v[158:161], v[198:201], v[34:37]
	v_mfma_f32_16x16x32_bf16 v[34:37], v[182:185], v[214:217], v[34:37]
	v_mfma_f32_16x16x32_bf16 v[22:25], v[146:149], v[218:221], v[22:25]
	v_mfma_f32_16x16x32_bf16 v[22:25], v[150:153], v[222:225], v[22:25]
	v_mfma_f32_16x16x32_bf16 v[18:21], v[158:161], v[218:221], v[18:21]
	v_mfma_f32_16x16x32_bf16 v[18:21], v[182:185], v[222:225], v[18:21]
	v_mfma_f32_16x16x32_bf16 v[6:9], v[146:149], v[226:229], v[6:9]
	v_mfma_f32_16x16x32_bf16 v[6:9], v[150:153], v[230:233], v[6:9]
	v_mfma_f32_16x16x32_bf16 v[2:5], v[158:161], v[226:229], v[2:5]
	v_mfma_f32_16x16x32_bf16 v[2:5], v[182:185], v[230:233], v[2:5]
	s_barrier
	s_cmp_gt_u32 s84, 41
	s_cbranch_scc0 .LBB0_446
	s_setprio 0
	s_and_b64 vcc, exec, s[40:41]
	s_cbranch_vccz .LBB0_449
	s_barrier

.LBB0_487:
	s_ashr_i32 s57, s56, 31
	s_lshl_b64 s[20:21], s[56:57], 19
	s_add_u32 s60, s94, s20
	s_addc_u32 s61, s95, s21
	s_and_b64 s[20:21], s[54:55], exec
	s_cselect_b32 s57, s61, s69
	s_cselect_b32 s86, s60, s68
	s_ashr_i32 s51, s50, 31
	s_lshl_b64 s[20:21], s[50:51], 19
	s_add_u32 s62, s15, s20
	s_addc_u32 s63, s42, s21
	s_and_b64 s[20:21], s[54:55], exec
	s_cselect_b32 s51, s63, s77
	s_cselect_b32 s87, s62, s76
	s_add_u32 s68, s68, 0x40080
	s_addc_u32 s69, s69, 0
	s_add_u32 s91, s76, 0x100
	v_mov_b32_e32 v2, 0
	s_addc_u32 s96, s77, 0
	s_mov_b32 s97, -2
	s_add_i32 s22, 0, 0x10000
	v_add_u32_e32 v152, s22, v139
	s_add_i32 s23, 0, 0x14000
	ds_read_b128 v[134:137], v152
	ds_read_b128 v[144:147], v152 offset:1024
	ds_read_b128 v[148:151], v152 offset:2048
	ds_read_b128 v[152:155], v152 offset:3072
	v_add_u32_e32 v186, s23, v139
	ds_read_b128 v[156:159], v186
	ds_read_b128 v[160:163], v186 offset:1024
	ds_read_b128 v[182:185], v186 offset:2048
	ds_read_b128 v[186:189], v186 offset:3072
	ds_read_b128 v[190:193], v142
	ds_read_b128 v[194:197], v142 offset:1024
	ds_read_b128 v[198:201], v142 offset:2048
	ds_read_b128 v[214:217], v142 offset:3072
	ds_read_b128 v[218:221], v142 offset:4096
	ds_read_b128 v[222:225], v142 offset:5120
	ds_read_b128 v[226:229], v142 offset:6144
	ds_read_b128 v[230:233], v142 offset:7168
	s_cmp_eq_u64 s[48:49], 0
	s_cbranch_scc0 .Lpr_488
	s_setprio 1

.Lmid1_488:
	s_add_i32 s22, 0, 0x10000
	s_add_i32 s23, 0, 0x14000
	s_add_u32 s20, s68, 0xfffc0080
	s_addc_u32 s21, s69, -1
	s_cmp_eq_u32 s97, 12
	s_cselect_b32 s77, s57, s21
	s_cselect_b32 s76, s86, s20
	s_cselect_b32 s21, s51, s96
	s_cselect_b32 s20, s87, s91
	s_add_i32 m0, s43, 0xc000
	v_lshl_add_u64 v[202:203], s[68:69], 0, v[132:133]
	global_load_lds_dwordx4 v[202:203], off
	v_lshl_add_u64 v[202:203], v[202:203], 0, s[72:73]
	s_add_i32 m0, s43, 0xe000
	s_nop 0
	global_load_lds_dwordx4 v[202:203], off
	s_waitcnt vmcnt(8)
	s_waitcnt lgkmcnt(0)
	s_barrier
	s_waitcnt lgkmcnt(0)
	v_mfma_f32_16x16x32_bf16 v[126:129], v[134:137], v[190:193], 0
	v_mfma_f32_16x16x32_bf16 v[126:129], v[144:147], v[194:197], v[126:129]
	v_mfma_f32_16x16x32_bf16 v[114:117], v[148:151], v[190:193], 0
	v_mfma_f32_16x16x32_bf16 v[114:117], v[152:155], v[194:197], v[114:117]
	v_mfma_f32_16x16x32_bf16 v[110:113], v[134:137], v[198:201], 0
	v_mfma_f32_16x16x32_bf16 v[110:113], v[144:147], v[214:217], v[110:113]
	v_mfma_f32_16x16x32_bf16 v[98:101], v[148:151], v[198:201], 0
	v_mfma_f32_16x16x32_bf16 v[98:101], v[152:155], v[214:217], v[98:101]
	v_mfma_f32_16x16x32_bf16 v[94:97], v[134:137], v[218:221], 0
	v_mfma_f32_16x16x32_bf16 v[94:97], v[144:147], v[222:225], v[94:97]
	v_mfma_f32_16x16x32_bf16 v[82:85], v[148:151], v[218:221], 0
	v_mfma_f32_16x16x32_bf16 v[82:85], v[152:155], v[222:225], v[82:85]
	v_mfma_f32_16x16x32_bf16 v[78:81], v[134:137], v[226:229], 0
	v_mfma_f32_16x16x32_bf16 v[78:81], v[144:147], v[230:233], v[78:81]
	v_mfma_f32_16x16x32_bf16 v[66:69], v[148:151], v[226:229], 0
	v_mfma_f32_16x16x32_bf16 v[66:69], v[152:155], v[230:233], v[66:69]
	v_mfma_f32_16x16x32_bf16 v[122:125], v[156:159], v[190:193], 0
	v_mfma_f32_16x16x32_bf16 v[122:125], v[160:163], v[194:197], v[122:125]
	v_mfma_f32_16x16x32_bf16 v[118:121], v[182:185], v[190:193], 0
	v_mfma_f32_16x16x32_bf16 v[118:121], v[186:189], v[194:197], v[118:121]
	v_mfma_f32_16x16x32_bf16 v[106:109], v[156:159], v[198:201], 0
	v_mfma_f32_16x16x32_bf16 v[106:109], v[160:163], v[214:217], v[106:109]
	v_mfma_f32_16x16x32_bf16 v[102:105], v[182:185], v[198:201], 0
	v_mfma_f32_16x16x32_bf16 v[102:105], v[186:189], v[214:217], v[102:105]
	v_mfma_f32_16x16x32_bf16 v[90:93], v[156:159], v[218:221], 0
	v_mfma_f32_16x16x32_bf16 v[90:93], v[160:163], v[222:225], v[90:93]
	v_mfma_f32_16x16x32_bf16 v[86:89], v[182:185], v[218:221], 0
	v_mfma_f32_16x16x32_bf16 v[86:89], v[186:189], v[222:225], v[86:89]
	v_mfma_f32_16x16x32_bf16 v[74:77], v[156:159], v[226:229], 0
	v_mfma_f32_16x16x32_bf16 v[74:77], v[160:163], v[230:233], v[74:77]
	v_mfma_f32_16x16x32_bf16 v[70:73], v[182:185], v[226:229], 0
	v_mfma_f32_16x16x32_bf16 v[70:73], v[186:189], v[230:233], v[70:73]
	s_barrier
	ds_read_b128 v[190:193], v142 offset:16384
	ds_read_b128 v[194:197], v142 offset:17408
	ds_read_b128 v[198:201], v142 offset:18432
	ds_read_b128 v[214:217], v142 offset:19456
	ds_read_b128 v[218:221], v142 offset:20480
	ds_read_b128 v[222:225], v142 offset:21504
	ds_read_b128 v[226:229], v142 offset:22528
	ds_read_b128 v[230:233], v142 offset:23552
	v_lshl_add_u64 v[202:203], s[20:21], 0, v[0:1]
	s_add_i32 s20, s22, s14
	s_mov_b32 m0, s20
	s_nop 0
	s_nop 0
	global_load_lds_dwordx4 v[202:203], off
	v_lshl_add_u64 v[234:235], v[202:203], 0, s[72:73]
	s_add_i32 m0, s20, 0x2000
	s_add_i32 s20, s23, s14
	global_load_lds_dwordx4 v[234:235], off
	v_lshl_add_u64 v[234:235], v[202:203], 0, s[28:29]
	s_mov_b32 m0, s20
	s_nop 0
	global_load_lds_dwordx4 v[234:235], off
	v_lshl_add_u64 v[234:235], v[202:203], 0, s[82:83]
	s_add_i32 m0, s20, 0x2000
	s_nop 0
	global_load_lds_dwordx4 v[234:235], off
	v_lshl_add_u64 v[234:235], s[76:77], 0, v[130:131]
	s_mov_b32 m0, s43
	v_lshl_add_u64 v[236:237], v[234:235], 0, s[72:73]
	global_load_lds_dwordx4 v[234:235], off
	s_mov_b32 m0, s46
	s_nop 0
	global_load_lds_dwordx4 v[236:237], off
	s_waitcnt vmcnt(8)
	s_waitcnt lgkmcnt(0)
	s_barrier
	s_waitcnt lgkmcnt(0)
	v_mfma_f32_16x16x32_bf16 v[62:65], v[134:137], v[190:193], 0
	v_mfma_f32_16x16x32_bf16 v[62:65], v[144:147], v[194:197], v[62:65]
	v_mfma_f32_16x16x32_bf16 v[50:53], v[148:151], v[190:193], 0
	v_mfma_f32_16x16x32_bf16 v[50:53], v[152:155], v[194:197], v[50:53]
	v_mfma_f32_16x16x32_bf16 v[46:49], v[134:137], v[198:201], 0
	v_mfma_f32_16x16x32_bf16 v[46:49], v[144:147], v[214:217], v[46:49]
	v_mfma_f32_16x16x32_bf16 v[34:37], v[148:151], v[198:201], 0
	v_mfma_f32_16x16x32_bf16 v[34:37], v[152:155], v[214:217], v[34:37]
	v_mfma_f32_16x16x32_bf16 v[30:33], v[134:137], v[218:221], 0
	v_mfma_f32_16x16x32_bf16 v[30:33], v[144:147], v[222:225], v[30:33]
	v_mfma_f32_16x16x32_bf16 v[18:21], v[148:151], v[218:221], 0
	v_mfma_f32_16x16x32_bf16 v[18:21], v[152:155], v[222:225], v[18:21]
	v_mfma_f32_16x16x32_bf16 v[14:17], v[134:137], v[226:229], 0
	v_mfma_f32_16x16x32_bf16 v[14:17], v[144:147], v[230:233], v[14:17]
	v_mfma_f32_16x16x32_bf16 v[6:9], v[148:151], v[226:229], 0
	v_mfma_f32_16x16x32_bf16 v[6:9], v[152:155], v[230:233], v[6:9]
	v_mfma_f32_16x16x32_bf16 v[58:61], v[156:159], v[190:193], 0
	v_mfma_f32_16x16x32_bf16 v[58:61], v[160:163], v[194:197], v[58:61]
	v_mfma_f32_16x16x32_bf16 v[54:57], v[182:185], v[190:193], 0
	v_mfma_f32_16x16x32_bf16 v[54:57], v[186:189], v[194:197], v[54:57]
	v_mfma_f32_16x16x32_bf16 v[42:45], v[156:159], v[198:201], 0
	v_mfma_f32_16x16x32_bf16 v[42:45], v[160:163], v[214:217], v[42:45]
	v_mfma_f32_16x16x32_bf16 v[38:41], v[182:185], v[198:201], 0
	v_mfma_f32_16x16x32_bf16 v[38:41], v[186:189], v[214:217], v[38:41]
	v_mfma_f32_16x16x32_bf16 v[26:29], v[156:159], v[218:221], 0
	v_mfma_f32_16x16x32_bf16 v[26:29], v[160:163], v[222:225], v[26:29]
	v_mfma_f32_16x16x32_bf16 v[22:25], v[182:185], v[218:221], 0
	v_mfma_f32_16x16x32_bf16 v[22:25], v[186:189], v[222:225], v[22:25]
	v_mfma_f32_16x16x32_bf16 v[10:13], v[156:159], v[226:229], 0
	v_mfma_f32_16x16x32_bf16 v[10:13], v[160:163], v[230:233], v[10:13]
	v_mfma_f32_16x16x32_bf16 v[2:5], v[182:185], v[226:229], 0
	v_mfma_f32_16x16x32_bf16 v[2:5], v[186:189], v[230:233], v[2:5]
	s_barrier
	s_add_i32 s20, 0, 0x18000
	v_add_u32_e32 v143, s20, v139
	s_add_i32 s21, 0, 0x1c000
	ds_read_b128 v[134:137], v143
	ds_read_b128 v[144:147], v143 offset:1024
	ds_read_b128 v[148:151], v143 offset:2048
	ds_read_b128 v[152:155], v143 offset:3072
	v_add_u32_e32 v143, s21, v139
	ds_read_b128 v[156:159], v143
	ds_read_b128 v[160:163], v143 offset:1024
	ds_read_b128 v[182:185], v143 offset:2048
	ds_read_b128 v[186:189], v143 offset:3072
	ds_read_b128 v[190:193], v142 offset:32768
	ds_read_b128 v[194:197], v142 offset:33792
	ds_read_b128 v[198:201], v142 offset:34816
	ds_read_b128 v[214:217], v142 offset:35840
	ds_read_b128 v[218:221], v142 offset:36864
	ds_read_b128 v[222:225], v142 offset:37888
	ds_read_b128 v[226:229], v142 offset:38912
	ds_read_b128 v[230:233], v142 offset:39936
	s_mov_b32 m0, s47
	v_lshl_add_u64 v[236:237], v[234:235], 0, s[28:29]
	global_load_lds_dwordx4 v[236:237], off
	v_lshl_add_u64 v[236:237], v[234:235], 0, s[82:83]
	s_mov_b32 m0, s78
	s_nop 0
	global_load_lds_dwordx4 v[236:237], off
	s_waitcnt vmcnt(8)
	s_waitcnt lgkmcnt(0)
	s_barrier
	s_waitcnt lgkmcnt(0)
	v_mfma_f32_16x16x32_bf16 v[126:129], v[134:137], v[190:193], v[126:129]
	v_mfma_f32_16x16x32_bf16 v[126:129], v[144:147], v[194:197], v[126:129]
	v_mfma_f32_16x16x32_bf16 v[114:117], v[148:151], v[190:193], v[114:117]
	v_mfma_f32_16x16x32_bf16 v[114:117], v[152:155], v[194:197], v[114:117]
	v_mfma_f32_16x16x32_bf16 v[110:113], v[134:137], v[198:201], v[110:113]
	v_mfma_f32_16x16x32_bf16 v[110:113], v[144:147], v[214:217], v[110:113]
	v_mfma_f32_16x16x32_bf16 v[98:101], v[148:151], v[198:201], v[98:101]
	v_mfma_f32_16x16x32_bf16 v[98:101], v[152:155], v[214:217], v[98:101]
	v_mfma_f32_16x16x32_bf16 v[94:97], v[134:137], v[218:221], v[94:97]
	v_mfma_f32_16x16x32_bf16 v[94:97], v[144:147], v[222:225], v[94:97]
	v_mfma_f32_16x16x32_bf16 v[82:85], v[148:151], v[218:221], v[82:85]
	v_mfma_f32_16x16x32_bf16 v[82:85], v[152:155], v[222:225], v[82:85]
	v_mfma_f32_16x16x32_bf16 v[78:81], v[134:137], v[226:229], v[78:81]
	v_mfma_f32_16x16x32_bf16 v[78:81], v[144:147], v[230:233], v[78:81]
	v_mfma_f32_16x16x32_bf16 v[66:69], v[148:151], v[226:229], v[66:69]
	v_mfma_f32_16x16x32_bf16 v[66:69], v[152:155], v[230:233], v[66:69]
	v_mfma_f32_16x16x32_bf16 v[122:125], v[156:159], v[190:193], v[122:125]
	v_mfma_f32_16x16x32_bf16 v[122:125], v[160:163], v[194:197], v[122:125]
	v_mfma_f32_16x16x32_bf16 v[118:121], v[182:185], v[190:193], v[118:121]
	v_mfma_f32_16x16x32_bf16 v[118:121], v[186:189], v[194:197], v[118:121]
	v_mfma_f32_16x16x32_bf16 v[106:109], v[156:159], v[198:201], v[106:109]
	v_mfma_f32_16x16x32_bf16 v[106:109], v[160:163], v[214:217], v[106:109]
	v_mfma_f32_16x16x32_bf16 v[102:105], v[182:185], v[198:201], v[102:105]
	v_mfma_f32_16x16x32_bf16 v[102:105], v[186:189], v[214:217], v[102:105]
	v_mfma_f32_16x16x32_bf16 v[90:93], v[156:159], v[218:221], v[90:93]
	v_mfma_f32_16x16x32_bf16 v[90:93], v[160:163], v[222:225], v[90:93]
	v_mfma_f32_16x16x32_bf16 v[86:89], v[182:185], v[218:221], v[86:89]
	v_mfma_f32_16x16x32_bf16 v[86:89], v[186:189], v[222:225], v[86:89]
	v_mfma_f32_16x16x32_bf16 v[74:77], v[156:159], v[226:229], v[74:77]
	v_mfma_f32_16x16x32_bf16 v[74:77], v[160:163], v[230:233], v[74:77]
	v_mfma_f32_16x16x32_bf16 v[70:73], v[182:185], v[226:229], v[70:73]
	v_mfma_f32_16x16x32_bf16 v[70:73], v[186:189], v[230:233], v[70:73]
	s_barrier
	ds_read_b128 v[190:193], v142 offset:49152
	ds_read_b128 v[194:197], v142 offset:50176
	ds_read_b128 v[198:201], v142 offset:51200
	ds_read_b128 v[214:217], v142 offset:52224
	ds_read_b128 v[218:221], v142 offset:53248
	ds_read_b128 v[222:225], v142 offset:54272
	ds_read_b128 v[226:229], v142 offset:55296
	ds_read_b128 v[230:233], v142 offset:56320
	s_add_i32 s20, s20, s14
	s_mov_b32 m0, s20
	v_lshl_add_u64 v[236:237], v[202:203], 0, s[34:35]
	global_load_lds_dwordx4 v[236:237], off
	v_lshl_add_u64 v[236:237], v[202:203], 0, s[38:39]
	s_add_i32 m0, s20, 0x2000
	s_add_i32 s20, s21, s14
	global_load_lds_dwordx4 v[236:237], off
	v_lshl_add_u64 v[236:237], v[202:203], 0, s[44:45]
	s_mov_b32 m0, s20
	v_lshl_add_u64 v[202:203], v[202:203], 0, s[10:11]
	global_load_lds_dwordx4 v[236:237], off
	s_add_i32 m0, s20, 0x2000
	s_nop 0
	global_load_lds_dwordx4 v[202:203], off
	v_lshl_add_u64 v[202:203], v[234:235], 0, s[34:35]
	s_mov_b32 m0, s79
	s_nop 0
	global_load_lds_dwordx4 v[202:203], off
	v_lshl_add_u64 v[202:203], v[234:235], 0, s[38:39]
	s_mov_b32 m0, s88
	s_nop 0
	global_load_lds_dwordx4 v[202:203], off
	s_waitcnt vmcnt(8)
	s_waitcnt lgkmcnt(0)
	s_barrier
	s_waitcnt lgkmcnt(0)
	v_mfma_f32_16x16x32_bf16 v[62:65], v[134:137], v[190:193], v[62:65]
	v_mfma_f32_16x16x32_bf16 v[62:65], v[144:147], v[194:197], v[62:65]
	v_mfma_f32_16x16x32_bf16 v[50:53], v[148:151], v[190:193], v[50:53]
	v_mfma_f32_16x16x32_bf16 v[50:53], v[152:155], v[194:197], v[50:53]
	v_mfma_f32_16x16x32_bf16 v[46:49], v[134:137], v[198:201], v[46:49]
	v_mfma_f32_16x16x32_bf16 v[46:49], v[144:147], v[214:217], v[46:49]
	v_mfma_f32_16x16x32_bf16 v[34:37], v[148:151], v[198:201], v[34:37]
	v_mfma_f32_16x16x32_bf16 v[34:37], v[152:155], v[214:217], v[34:37]
	v_mfma_f32_16x16x32_bf16 v[30:33], v[134:137], v[218:221], v[30:33]
	v_mfma_f32_16x16x32_bf16 v[30:33], v[144:147], v[222:225], v[30:33]
	v_mfma_f32_16x16x32_bf16 v[18:21], v[148:151], v[218:221], v[18:21]
	v_mfma_f32_16x16x32_bf16 v[18:21], v[152:155], v[222:225], v[18:21]
	v_mfma_f32_16x16x32_bf16 v[14:17], v[134:137], v[226:229], v[14:17]
	v_mfma_f32_16x16x32_bf16 v[14:17], v[144:147], v[230:233], v[14:17]
	v_mfma_f32_16x16x32_bf16 v[6:9], v[148:151], v[226:229], v[6:9]
	v_mfma_f32_16x16x32_bf16 v[6:9], v[152:155], v[230:233], v[6:9]
	s_add_i32 s97, s97, 2
	s_add_u32 s68, s68, 0x100
	s_addc_u32 s69, s69, 0
	s_add_u32 s91, s91, 0x100
	s_addc_u32 s96, s96, 0
	v_mfma_f32_16x16x32_bf16 v[58:61], v[156:159], v[190:193], v[58:61]
	v_mfma_f32_16x16x32_bf16 v[58:61], v[160:163], v[194:197], v[58:61]
	v_mfma_f32_16x16x32_bf16 v[54:57], v[182:185], v[190:193], v[54:57]
	v_mfma_f32_16x16x32_bf16 v[54:57], v[186:189], v[194:197], v[54:57]
	v_mfma_f32_16x16x32_bf16 v[42:45], v[156:159], v[198:201], v[42:45]
	v_mfma_f32_16x16x32_bf16 v[42:45], v[160:163], v[214:217], v[42:45]
	v_mfma_f32_16x16x32_bf16 v[38:41], v[182:185], v[198:201], v[38:41]
	v_mfma_f32_16x16x32_bf16 v[38:41], v[186:189], v[214:217], v[38:41]
	v_mfma_f32_16x16x32_bf16 v[26:29], v[156:159], v[218:221], v[26:29]
	v_mfma_f32_16x16x32_bf16 v[26:29], v[160:163], v[222:225], v[26:29]
	v_mfma_f32_16x16x32_bf16 v[22:25], v[182:185], v[218:221], v[22:25]
	v_mfma_f32_16x16x32_bf16 v[22:25], v[186:189], v[222:225], v[22:25]
	v_mfma_f32_16x16x32_bf16 v[10:13], v[156:159], v[226:229], v[10:13]
	v_mfma_f32_16x16x32_bf16 v[10:13], v[160:163], v[230:233], v[10:13]
	v_mfma_f32_16x16x32_bf16 v[2:5], v[182:185], v[226:229], v[2:5]
	v_mfma_f32_16x16x32_bf16 v[2:5], v[186:189], v[230:233], v[2:5]
	s_barrier
	s_branch .LBB0_488
	.p2alignl 6, 3212836864
.LBB0_488:
	s_add_i32 s22, 0, 0x10000
	v_add_u32_e32 v143, s22, v139
	s_add_i32 s23, 0, 0x14000
	ds_read_b128 v[134:137], v143
	ds_read_b128 v[144:147], v143 offset:1024
	ds_read_b128 v[148:151], v143 offset:2048
	ds_read_b128 v[152:155], v143 offset:3072
	v_add_u32_e32 v143, s23, v139
	ds_read_b128 v[156:159], v143
	ds_read_b128 v[160:163], v143 offset:1024
	ds_read_b128 v[182:185], v143 offset:2048
	ds_read_b128 v[186:189], v143 offset:3072
	ds_read_b128 v[190:193], v142
	ds_read_b128 v[194:197], v142 offset:1024
	ds_read_b128 v[198:201], v142 offset:2048
	ds_read_b128 v[214:217], v142 offset:3072
	ds_read_b128 v[218:221], v142 offset:4096
	ds_read_b128 v[222:225], v142 offset:5120
	ds_read_b128 v[226:229], v142 offset:6144
	ds_read_b128 v[230:233], v142 offset:7168
	s_add_u32 s20, s68, 0xfffc0080
	s_addc_u32 s21, s69, -1
	s_cmp_eq_u32 s97, 12
	s_cselect_b32 s77, s57, s21
	s_cselect_b32 s76, s86, s20
	s_cselect_b32 s21, s51, s96
	s_cselect_b32 s20, s87, s91
	s_add_i32 m0, s43, 0xc000
	v_lshl_add_u64 v[202:203], s[68:69], 0, v[132:133]
	global_load_lds_dwordx4 v[202:203], off
	v_lshl_add_u64 v[202:203], v[202:203], 0, s[72:73]
	s_add_i32 m0, s43, 0xe000
	s_nop 0
	global_load_lds_dwordx4 v[202:203], off
	s_waitcnt vmcnt(8)
	s_waitcnt lgkmcnt(0)
	s_barrier
	s_waitcnt lgkmcnt(0)
	v_mfma_f32_16x16x32_bf16 v[126:129], v[134:137], v[190:193], v[126:129]
	v_mfma_f32_16x16x32_bf16 v[126:129], v[144:147], v[194:197], v[126:129]
	v_mfma_f32_16x16x32_bf16 v[114:117], v[148:151], v[190:193], v[114:117]
	v_mfma_f32_16x16x32_bf16 v[114:117], v[152:155], v[194:197], v[114:117]
	v_mfma_f32_16x16x32_bf16 v[110:113], v[134:137], v[198:201], v[110:113]
	v_mfma_f32_16x16x32_bf16 v[110:113], v[144:147], v[214:217], v[110:113]
	v_mfma_f32_16x16x32_bf16 v[98:101], v[148:151], v[198:201], v[98:101]
	v_mfma_f32_16x16x32_bf16 v[98:101], v[152:155], v[214:217], v[98:101]
	v_mfma_f32_16x16x32_bf16 v[94:97], v[134:137], v[218:221], v[94:97]
	v_mfma_f32_16x16x32_bf16 v[94:97], v[144:147], v[222:225], v[94:97]
	v_mfma_f32_16x16x32_bf16 v[82:85], v[148:151], v[218:221], v[82:85]
	v_mfma_f32_16x16x32_bf16 v[82:85], v[152:155], v[222:225], v[82:85]
	v_mfma_f32_16x16x32_bf16 v[78:81], v[134:137], v[226:229], v[78:81]
	v_mfma_f32_16x16x32_bf16 v[78:81], v[144:147], v[230:233], v[78:81]
	v_mfma_f32_16x16x32_bf16 v[66:69], v[148:151], v[226:229], v[66:69]
	v_mfma_f32_16x16x32_bf16 v[66:69], v[152:155], v[230:233], v[66:69]
	v_mfma_f32_16x16x32_bf16 v[122:125], v[156:159], v[190:193], v[122:125]
	v_mfma_f32_16x16x32_bf16 v[122:125], v[160:163], v[194:197], v[122:125]
	v_mfma_f32_16x16x32_bf16 v[118:121], v[182:185], v[190:193], v[118:121]
	v_mfma_f32_16x16x32_bf16 v[118:121], v[186:189], v[194:197], v[118:121]
	v_mfma_f32_16x16x32_bf16 v[106:109], v[156:159], v[198:201], v[106:109]
	v_mfma_f32_16x16x32_bf16 v[106:109], v[160:163], v[214:217], v[106:109]
	v_mfma_f32_16x16x32_bf16 v[102:105], v[182:185], v[198:201], v[102:105]
	v_mfma_f32_16x16x32_bf16 v[102:105], v[186:189], v[214:217], v[102:105]
	v_mfma_f32_16x16x32_bf16 v[90:93], v[156:159], v[218:221], v[90:93]
	v_mfma_f32_16x16x32_bf16 v[90:93], v[160:163], v[222:225], v[90:93]
	v_mfma_f32_16x16x32_bf16 v[86:89], v[182:185], v[218:221], v[86:89]
	v_mfma_f32_16x16x32_bf16 v[86:89], v[186:189], v[222:225], v[86:89]
	v_mfma_f32_16x16x32_bf16 v[74:77], v[156:159], v[226:229], v[74:77]
	v_mfma_f32_16x16x32_bf16 v[74:77], v[160:163], v[230:233], v[74:77]
	v_mfma_f32_16x16x32_bf16 v[70:73], v[182:185], v[226:229], v[70:73]
	v_mfma_f32_16x16x32_bf16 v[70:73], v[186:189], v[230:233], v[70:73]
	s_barrier
	ds_read_b128 v[190:193], v142 offset:16384
	ds_read_b128 v[194:197], v142 offset:17408
	ds_read_b128 v[198:201], v142 offset:18432
	ds_read_b128 v[214:217], v142 offset:19456
	ds_read_b128 v[218:221], v142 offset:20480
	ds_read_b128 v[222:225], v142 offset:21504
	ds_read_b128 v[226:229], v142 offset:22528
	ds_read_b128 v[230:233], v142 offset:23552
	v_lshl_add_u64 v[202:203], s[20:21], 0, v[0:1]
	s_add_i32 s20, s22, s14
	s_mov_b32 m0, s20
	s_nop 0
	s_nop 0
	global_load_lds_dwordx4 v[202:203], off
	v_lshl_add_u64 v[234:235], v[202:203], 0, s[72:73]
	s_add_i32 m0, s20, 0x2000
	s_add_i32 s20, s23, s14
	global_load_lds_dwordx4 v[234:235], off
	v_lshl_add_u64 v[234:235], v[202:203], 0, s[28:29]
	s_mov_b32 m0, s20
	s_nop 0
	global_load_lds_dwordx4 v[234:235], off
	v_lshl_add_u64 v[234:235], v[202:203], 0, s[82:83]
	s_add_i32 m0, s20, 0x2000
	s_nop 0
	global_load_lds_dwordx4 v[234:235], off
	v_lshl_add_u64 v[234:235], s[76:77], 0, v[130:131]
	s_mov_b32 m0, s43
	v_lshl_add_u64 v[236:237], v[234:235], 0, s[72:73]
	global_load_lds_dwordx4 v[234:235], off
	s_mov_b32 m0, s46
	s_nop 0
	global_load_lds_dwordx4 v[236:237], off
	s_waitcnt vmcnt(8)
	s_waitcnt lgkmcnt(0)
	s_barrier
	s_waitcnt lgkmcnt(0)
	v_mfma_f32_16x16x32_bf16 v[62:65], v[134:137], v[190:193], v[62:65]
	v_mfma_f32_16x16x32_bf16 v[62:65], v[144:147], v[194:197], v[62:65]
	v_mfma_f32_16x16x32_bf16 v[50:53], v[148:151], v[190:193], v[50:53]
	v_mfma_f32_16x16x32_bf16 v[50:53], v[152:155], v[194:197], v[50:53]
	v_mfma_f32_16x16x32_bf16 v[46:49], v[134:137], v[198:201], v[46:49]
	v_mfma_f32_16x16x32_bf16 v[46:49], v[144:147], v[214:217], v[46:49]
	v_mfma_f32_16x16x32_bf16 v[34:37], v[148:151], v[198:201], v[34:37]
	v_mfma_f32_16x16x32_bf16 v[34:37], v[152:155], v[214:217], v[34:37]
	v_mfma_f32_16x16x32_bf16 v[30:33], v[134:137], v[218:221], v[30:33]
	v_mfma_f32_16x16x32_bf16 v[30:33], v[144:147], v[222:225], v[30:33]
	v_mfma_f32_16x16x32_bf16 v[18:21], v[148:151], v[218:221], v[18:21]
	v_mfma_f32_16x16x32_bf16 v[18:21], v[152:155], v[222:225], v[18:21]
	v_mfma_f32_16x16x32_bf16 v[14:17], v[134:137], v[226:229], v[14:17]
	v_mfma_f32_16x16x32_bf16 v[14:17], v[144:147], v[230:233], v[14:17]
	v_mfma_f32_16x16x32_bf16 v[6:9], v[148:151], v[226:229], v[6:9]
	v_mfma_f32_16x16x32_bf16 v[6:9], v[152:155], v[230:233], v[6:9]
	v_mfma_f32_16x16x32_bf16 v[58:61], v[156:159], v[190:193], v[58:61]
	v_mfma_f32_16x16x32_bf16 v[58:61], v[160:163], v[194:197], v[58:61]
	v_mfma_f32_16x16x32_bf16 v[54:57], v[182:185], v[190:193], v[54:57]
	v_mfma_f32_16x16x32_bf16 v[54:57], v[186:189], v[194:197], v[54:57]
	v_mfma_f32_16x16x32_bf16 v[42:45], v[156:159], v[198:201], v[42:45]
	v_mfma_f32_16x16x32_bf16 v[42:45], v[160:163], v[214:217], v[42:45]
	v_mfma_f32_16x16x32_bf16 v[38:41], v[182:185], v[198:201], v[38:41]
	v_mfma_f32_16x16x32_bf16 v[38:41], v[186:189], v[214:217], v[38:41]
	v_mfma_f32_16x16x32_bf16 v[26:29], v[156:159], v[218:221], v[26:29]
	v_mfma_f32_16x16x32_bf16 v[26:29], v[160:163], v[222:225], v[26:29]
	v_mfma_f32_16x16x32_bf16 v[22:25], v[182:185], v[218:221], v[22:25]
	v_mfma_f32_16x16x32_bf16 v[22:25], v[186:189], v[222:225], v[22:25]
	v_mfma_f32_16x16x32_bf16 v[10:13], v[156:159], v[226:229], v[10:13]
	v_mfma_f32_16x16x32_bf16 v[10:13], v[160:163], v[230:233], v[10:13]
	v_mfma_f32_16x16x32_bf16 v[2:5], v[182:185], v[226:229], v[2:5]
	v_mfma_f32_16x16x32_bf16 v[2:5], v[186:189], v[230:233], v[2:5]
	s_barrier
	s_add_i32 s20, 0, 0x18000
	v_add_u32_e32 v143, s20, v139
	s_add_i32 s21, 0, 0x1c000
	ds_read_b128 v[134:137], v143
	ds_read_b128 v[144:147], v143 offset:1024
	ds_read_b128 v[148:151], v143 offset:2048
	ds_read_b128 v[152:155], v143 offset:3072
	v_add_u32_e32 v143, s21, v139
	ds_read_b128 v[156:159], v143
	ds_read_b128 v[160:163], v143 offset:1024
	ds_read_b128 v[182:185], v143 offset:2048
	ds_read_b128 v[186:189], v143 offset:3072
	ds_read_b128 v[190:193], v142 offset:32768
	ds_read_b128 v[194:197], v142 offset:33792
	ds_read_b128 v[198:201], v142 offset:34816
	ds_read_b128 v[214:217], v142 offset:35840
	ds_read_b128 v[218:221], v142 offset:36864
	ds_read_b128 v[222:225], v142 offset:37888
	ds_read_b128 v[226:229], v142 offset:38912
	ds_read_b128 v[230:233], v142 offset:39936
	s_mov_b32 m0, s47
	v_lshl_add_u64 v[236:237], v[234:235], 0, s[28:29]
	global_load_lds_dwordx4 v[236:237], off
	v_lshl_add_u64 v[236:237], v[234:235], 0, s[82:83]
	s_mov_b32 m0, s78
	s_nop 0
	global_load_lds_dwordx4 v[236:237], off
	s_waitcnt vmcnt(8)
	s_waitcnt lgkmcnt(0)
	s_barrier
	s_waitcnt lgkmcnt(0)
	v_mfma_f32_16x16x32_bf16 v[126:129], v[134:137], v[190:193], v[126:129]
	v_mfma_f32_16x16x32_bf16 v[126:129], v[144:147], v[194:197], v[126:129]
	v_mfma_f32_16x16x32_bf16 v[114:117], v[148:151], v[190:193], v[114:117]
	v_mfma_f32_16x16x32_bf16 v[114:117], v[152:155], v[194:197], v[114:117]
	v_mfma_f32_16x16x32_bf16 v[110:113], v[134:137], v[198:201], v[110:113]
	v_mfma_f32_16x16x32_bf16 v[110:113], v[144:147], v[214:217], v[110:113]
	v_mfma_f32_16x16x32_bf16 v[98:101], v[148:151], v[198:201], v[98:101]
	v_mfma_f32_16x16x32_bf16 v[98:101], v[152:155], v[214:217], v[98:101]
	v_mfma_f32_16x16x32_bf16 v[94:97], v[134:137], v[218:221], v[94:97]
	v_mfma_f32_16x16x32_bf16 v[94:97], v[144:147], v[222:225], v[94:97]
	v_mfma_f32_16x16x32_bf16 v[82:85], v[148:151], v[218:221], v[82:85]
	v_mfma_f32_16x16x32_bf16 v[82:85], v[152:155], v[222:225], v[82:85]
	v_mfma_f32_16x16x32_bf16 v[78:81], v[134:137], v[226:229], v[78:81]
	v_mfma_f32_16x16x32_bf16 v[78:81], v[144:147], v[230:233], v[78:81]
	v_mfma_f32_16x16x32_bf16 v[66:69], v[148:151], v[226:229], v[66:69]
	v_mfma_f32_16x16x32_bf16 v[66:69], v[152:155], v[230:233], v[66:69]
	v_mfma_f32_16x16x32_bf16 v[122:125], v[156:159], v[190:193], v[122:125]
	v_mfma_f32_16x16x32_bf16 v[122:125], v[160:163], v[194:197], v[122:125]
	v_mfma_f32_16x16x32_bf16 v[118:121], v[182:185], v[190:193], v[118:121]
	v_mfma_f32_16x16x32_bf16 v[118:121], v[186:189], v[194:197], v[118:121]
	v_mfma_f32_16x16x32_bf16 v[106:109], v[156:159], v[198:201], v[106:109]
	v_mfma_f32_16x16x32_bf16 v[106:109], v[160:163], v[214:217], v[106:109]
	v_mfma_f32_16x16x32_bf16 v[102:105], v[182:185], v[198:201], v[102:105]
	v_mfma_f32_16x16x32_bf16 v[102:105], v[186:189], v[214:217], v[102:105]
	v_mfma_f32_16x16x32_bf16 v[90:93], v[156:159], v[218:221], v[90:93]
	v_mfma_f32_16x16x32_bf16 v[90:93], v[160:163], v[222:225], v[90:93]
	v_mfma_f32_16x16x32_bf16 v[86:89], v[182:185], v[218:221], v[86:89]
	v_mfma_f32_16x16x32_bf16 v[86:89], v[186:189], v[222:225], v[86:89]
	v_mfma_f32_16x16x32_bf16 v[74:77], v[156:159], v[226:229], v[74:77]
	v_mfma_f32_16x16x32_bf16 v[74:77], v[160:163], v[230:233], v[74:77]
	v_mfma_f32_16x16x32_bf16 v[70:73], v[182:185], v[226:229], v[70:73]
	v_mfma_f32_16x16x32_bf16 v[70:73], v[186:189], v[230:233], v[70:73]
	s_barrier
	ds_read_b128 v[190:193], v142 offset:49152
	ds_read_b128 v[194:197], v142 offset:50176
	ds_read_b128 v[198:201], v142 offset:51200
	ds_read_b128 v[214:217], v142 offset:52224
	ds_read_b128 v[218:221], v142 offset:53248
	ds_read_b128 v[222:225], v142 offset:54272
	ds_read_b128 v[226:229], v142 offset:55296
	ds_read_b128 v[230:233], v142 offset:56320
	s_add_i32 s20, s20, s14
	s_mov_b32 m0, s20
	v_lshl_add_u64 v[236:237], v[202:203], 0, s[34:35]
	global_load_lds_dwordx4 v[236:237], off
	v_lshl_add_u64 v[236:237], v[202:203], 0, s[38:39]
	s_add_i32 m0, s20, 0x2000
	s_add_i32 s20, s21, s14
	global_load_lds_dwordx4 v[236:237], off
	v_lshl_add_u64 v[236:237], v[202:203], 0, s[44:45]
	s_mov_b32 m0, s20
	v_lshl_add_u64 v[202:203], v[202:203], 0, s[10:11]
	global_load_lds_dwordx4 v[236:237], off
	s_add_i32 m0, s20, 0x2000
	s_nop 0
	global_load_lds_dwordx4 v[202:203], off
	v_lshl_add_u64 v[202:203], v[234:235], 0, s[34:35]
	s_mov_b32 m0, s79
	s_nop 0
	global_load_lds_dwordx4 v[202:203], off
	v_lshl_add_u64 v[202:203], v[234:235], 0, s[38:39]
	s_mov_b32 m0, s88
	s_nop 0
	global_load_lds_dwordx4 v[202:203], off
	s_waitcnt vmcnt(8)
	s_waitcnt lgkmcnt(0)
	s_barrier
	s_waitcnt lgkmcnt(0)
	v_mfma_f32_16x16x32_bf16 v[62:65], v[134:137], v[190:193], v[62:65]
	v_mfma_f32_16x16x32_bf16 v[62:65], v[144:147], v[194:197], v[62:65]
	v_mfma_f32_16x16x32_bf16 v[50:53], v[148:151], v[190:193], v[50:53]
	v_mfma_f32_16x16x32_bf16 v[50:53], v[152:155], v[194:197], v[50:53]
	v_mfma_f32_16x16x32_bf16 v[46:49], v[134:137], v[198:201], v[46:49]
	v_mfma_f32_16x16x32_bf16 v[46:49], v[144:147], v[214:217], v[46:49]
	v_mfma_f32_16x16x32_bf16 v[34:37], v[148:151], v[198:201], v[34:37]
	v_mfma_f32_16x16x32_bf16 v[34:37], v[152:155], v[214:217], v[34:37]
	v_mfma_f32_16x16x32_bf16 v[30:33], v[134:137], v[218:221], v[30:33]
	v_mfma_f32_16x16x32_bf16 v[30:33], v[144:147], v[222:225], v[30:33]
	v_mfma_f32_16x16x32_bf16 v[18:21], v[148:151], v[218:221], v[18:21]
	v_mfma_f32_16x16x32_bf16 v[18:21], v[152:155], v[222:225], v[18:21]
	v_mfma_f32_16x16x32_bf16 v[14:17], v[134:137], v[226:229], v[14:17]
	v_mfma_f32_16x16x32_bf16 v[14:17], v[144:147], v[230:233], v[14:17]
	v_mfma_f32_16x16x32_bf16 v[6:9], v[148:151], v[226:229], v[6:9]
	v_mfma_f32_16x16x32_bf16 v[6:9], v[152:155], v[230:233], v[6:9]
	s_add_i32 s97, s97, 2
	s_add_u32 s68, s68, 0x100
	s_addc_u32 s69, s69, 0
	s_add_u32 s91, s91, 0x100
	s_addc_u32 s96, s96, 0
	v_mfma_f32_16x16x32_bf16 v[58:61], v[156:159], v[190:193], v[58:61]
	v_mfma_f32_16x16x32_bf16 v[58:61], v[160:163], v[194:197], v[58:61]
	v_mfma_f32_16x16x32_bf16 v[54:57], v[182:185], v[190:193], v[54:57]
	v_mfma_f32_16x16x32_bf16 v[54:57], v[186:189], v[194:197], v[54:57]
	v_mfma_f32_16x16x32_bf16 v[42:45], v[156:159], v[198:201], v[42:45]
	v_mfma_f32_16x16x32_bf16 v[42:45], v[160:163], v[214:217], v[42:45]
	v_mfma_f32_16x16x32_bf16 v[38:41], v[182:185], v[198:201], v[38:41]
	v_mfma_f32_16x16x32_bf16 v[38:41], v[186:189], v[214:217], v[38:41]
	v_mfma_f32_16x16x32_bf16 v[26:29], v[156:159], v[218:221], v[26:29]
	v_mfma_f32_16x16x32_bf16 v[26:29], v[160:163], v[222:225], v[26:29]
	v_mfma_f32_16x16x32_bf16 v[22:25], v[182:185], v[218:221], v[22:25]
	v_mfma_f32_16x16x32_bf16 v[22:25], v[186:189], v[222:225], v[22:25]
	v_mfma_f32_16x16x32_bf16 v[10:13], v[156:159], v[226:229], v[10:13]
	v_mfma_f32_16x16x32_bf16 v[10:13], v[160:163], v[230:233], v[10:13]
	v_mfma_f32_16x16x32_bf16 v[2:5], v[182:185], v[226:229], v[2:5]
	v_mfma_f32_16x16x32_bf16 v[2:5], v[186:189], v[230:233], v[2:5]
	s_barrier
	s_cmp_gt_u32 s97, 13
	s_cbranch_scc0 .LBB0_488
	s_setprio 0
	s_and_b64 vcc, exec, s[48:49]
	s_cbranch_vccz .LBB0_491
	s_barrier

.LBB0_603:
	s_ashr_i32 s51, s50, 31
	s_lshl_b64 s[20:21], s[50:51], 18
	s_add_u32 s78, s0, s20
	s_addc_u32 s79, s1, s21
	s_and_b64 s[20:21], s[56:57], exec
	s_cselect_b32 s42, s79, s7
	s_cselect_b32 s43, s78, s6
	s_ashr_i32 s49, s48, 31
	s_lshl_b64 s[20:21], s[48:49], 18
	s_add_u32 s40, s76, s20
	s_addc_u32 s41, s77, s21
	s_and_b64 s[20:21], s[56:57], exec
	s_cselect_b32 s46, s41, s69
	s_cselect_b32 s47, s40, s68
	s_add_u32 s6, s6, 0x20080
	s_addc_u32 s7, s7, 0
	s_add_u32 s49, s68, 0x100
	v_mov_b32_e32 v2, 0
	s_addc_u32 s51, s69, 0
	s_mov_b32 s84, -2
	s_waitcnt lgkmcnt(0)
	s_add_i32 s22, 0, 0x10000
	s_add_i32 s23, 0, 0x14000
	v_add_u32_e32 v150, s22, v139
	v_add_u32_e32 v186, s23, v139
	ds_read_b128 v[134:137], v150
	ds_read_b128 v[142:145], v150 offset:1024
	ds_read_b128 v[146:149], v150 offset:2048
	ds_read_b128 v[150:153], v150 offset:3072
	ds_read_b128 v[154:157], v186
	ds_read_b128 v[158:161], v186 offset:1024
	ds_read_b128 v[182:185], v186 offset:2048
	ds_read_b128 v[186:189], v186 offset:3072
	ds_read_b128 v[190:193], v141
	ds_read_b128 v[194:197], v141 offset:1024
	ds_read_b128 v[198:201], v141 offset:2048
	ds_read_b128 v[214:217], v141 offset:3072
	ds_read_b128 v[218:221], v141 offset:4096
	ds_read_b128 v[222:225], v141 offset:5120
	ds_read_b128 v[226:229], v141 offset:6144
	ds_read_b128 v[230:233], v141 offset:7168
	s_cmp_eq_u64 s[52:53], 0
	s_cbranch_scc0 .Lpr_604
	s_setprio 1

.Lmid1_604:
	s_add_i32 s22, 0, 0x10000
	s_add_i32 s23, 0, 0x14000
	s_add_u32 s20, s6, 0xfffe0080
	s_addc_u32 s21, s7, -1
	s_cmp_eq_u32 s84, 4
	s_cselect_b32 s69, s42, s21
	s_cselect_b32 s68, s43, s20
	s_cselect_b32 s21, s46, s51
	s_cselect_b32 s20, s47, s49
	s_add_i32 m0, s89, 0xc000
	v_lshl_add_u64 v[162:163], s[6:7], 0, v[132:133]
	global_load_lds_dwordx4 v[162:163], off
	v_lshl_add_u64 v[162:163], v[162:163], 0, s[64:65]
	s_add_i32 m0, s89, 0xe000
	s_nop 0
	global_load_lds_dwordx4 v[162:163], off
	s_waitcnt vmcnt(8)
	s_waitcnt lgkmcnt(0)
	s_barrier
	s_waitcnt lgkmcnt(0)
	v_mfma_f32_16x16x32_bf16 v[126:129], v[134:137], v[190:193], 0
	v_mfma_f32_16x16x32_bf16 v[126:129], v[142:145], v[194:197], v[126:129]
	v_mfma_f32_16x16x32_bf16 v[122:125], v[146:149], v[190:193], 0
	v_mfma_f32_16x16x32_bf16 v[122:125], v[150:153], v[194:197], v[122:125]
	v_mfma_f32_16x16x32_bf16 v[110:113], v[134:137], v[198:201], 0
	v_mfma_f32_16x16x32_bf16 v[110:113], v[142:145], v[214:217], v[110:113]
	v_mfma_f32_16x16x32_bf16 v[106:109], v[146:149], v[198:201], 0
	v_mfma_f32_16x16x32_bf16 v[106:109], v[150:153], v[214:217], v[106:109]
	v_mfma_f32_16x16x32_bf16 v[94:97], v[134:137], v[218:221], 0
	v_mfma_f32_16x16x32_bf16 v[94:97], v[142:145], v[222:225], v[94:97]
	v_mfma_f32_16x16x32_bf16 v[90:93], v[146:149], v[218:221], 0
	v_mfma_f32_16x16x32_bf16 v[90:93], v[150:153], v[222:225], v[90:93]
	v_mfma_f32_16x16x32_bf16 v[78:81], v[134:137], v[226:229], 0
	v_mfma_f32_16x16x32_bf16 v[78:81], v[142:145], v[230:233], v[78:81]
	v_mfma_f32_16x16x32_bf16 v[74:77], v[146:149], v[226:229], 0
	v_mfma_f32_16x16x32_bf16 v[74:77], v[150:153], v[230:233], v[74:77]
	v_mfma_f32_16x16x32_bf16 v[118:121], v[154:157], v[190:193], 0
	v_mfma_f32_16x16x32_bf16 v[118:121], v[158:161], v[194:197], v[118:121]
	v_mfma_f32_16x16x32_bf16 v[114:117], v[182:185], v[190:193], 0
	v_mfma_f32_16x16x32_bf16 v[114:117], v[186:189], v[194:197], v[114:117]
	v_mfma_f32_16x16x32_bf16 v[102:105], v[154:157], v[198:201], 0
	v_mfma_f32_16x16x32_bf16 v[102:105], v[158:161], v[214:217], v[102:105]
	v_mfma_f32_16x16x32_bf16 v[98:101], v[182:185], v[198:201], 0
	v_mfma_f32_16x16x32_bf16 v[98:101], v[186:189], v[214:217], v[98:101]
	v_mfma_f32_16x16x32_bf16 v[86:89], v[154:157], v[218:221], 0
	v_mfma_f32_16x16x32_bf16 v[86:89], v[158:161], v[222:225], v[86:89]
	v_mfma_f32_16x16x32_bf16 v[82:85], v[182:185], v[218:221], 0
	v_mfma_f32_16x16x32_bf16 v[82:85], v[186:189], v[222:225], v[82:85]
	v_mfma_f32_16x16x32_bf16 v[70:73], v[154:157], v[226:229], 0
	v_mfma_f32_16x16x32_bf16 v[70:73], v[158:161], v[230:233], v[70:73]
	v_mfma_f32_16x16x32_bf16 v[66:69], v[182:185], v[226:229], 0
	v_mfma_f32_16x16x32_bf16 v[66:69], v[186:189], v[230:233], v[66:69]
	s_barrier
	ds_read_b128 v[190:193], v141 offset:16384
	ds_read_b128 v[194:197], v141 offset:17408
	ds_read_b128 v[198:201], v141 offset:18432
	ds_read_b128 v[214:217], v141 offset:19456
	ds_read_b128 v[218:221], v141 offset:20480
	ds_read_b128 v[222:225], v141 offset:21504
	ds_read_b128 v[226:229], v141 offset:22528
	ds_read_b128 v[230:233], v141 offset:23552
	v_lshl_add_u64 v[162:163], s[20:21], 0, v[0:1]
	s_add_i32 s20, s22, s88
	s_mov_b32 m0, s20
	s_nop 0
	s_nop 0
	global_load_lds_dwordx4 v[162:163], off
	v_lshl_add_u64 v[202:203], v[162:163], 0, s[64:65]
	s_add_i32 m0, s20, 0x2000
	s_add_i32 s20, s23, s88
	global_load_lds_dwordx4 v[202:203], off
	v_lshl_add_u64 v[202:203], v[162:163], 0, s[72:73]
	s_mov_b32 m0, s20
	s_nop 0
	global_load_lds_dwordx4 v[202:203], off
	v_lshl_add_u64 v[202:203], v[162:163], 0, s[74:75]
	s_add_i32 m0, s20, 0x2000
	s_nop 0
	global_load_lds_dwordx4 v[202:203], off
	v_lshl_add_u64 v[202:203], s[68:69], 0, v[130:131]
	s_mov_b32 m0, s89
	v_lshl_add_u64 v[234:235], v[202:203], 0, s[64:65]
	global_load_lds_dwordx4 v[202:203], off
	s_mov_b32 m0, s90
	s_nop 0
	global_load_lds_dwordx4 v[234:235], off
	s_waitcnt vmcnt(8)
	s_waitcnt lgkmcnt(0)
	s_barrier
	s_waitcnt lgkmcnt(0)
	v_mfma_f32_16x16x32_bf16 v[62:65], v[134:137], v[190:193], 0
	v_mfma_f32_16x16x32_bf16 v[62:65], v[142:145], v[194:197], v[62:65]
	v_mfma_f32_16x16x32_bf16 v[58:61], v[146:149], v[190:193], 0
	v_mfma_f32_16x16x32_bf16 v[58:61], v[150:153], v[194:197], v[58:61]
	v_mfma_f32_16x16x32_bf16 v[46:49], v[134:137], v[198:201], 0
	v_mfma_f32_16x16x32_bf16 v[46:49], v[142:145], v[214:217], v[46:49]
	v_mfma_f32_16x16x32_bf16 v[42:45], v[146:149], v[198:201], 0
	v_mfma_f32_16x16x32_bf16 v[42:45], v[150:153], v[214:217], v[42:45]
	v_mfma_f32_16x16x32_bf16 v[30:33], v[134:137], v[218:221], 0
	v_mfma_f32_16x16x32_bf16 v[30:33], v[142:145], v[222:225], v[30:33]
	v_mfma_f32_16x16x32_bf16 v[26:29], v[146:149], v[218:221], 0
	v_mfma_f32_16x16x32_bf16 v[26:29], v[150:153], v[222:225], v[26:29]
	v_mfma_f32_16x16x32_bf16 v[14:17], v[134:137], v[226:229], 0
	v_mfma_f32_16x16x32_bf16 v[14:17], v[142:145], v[230:233], v[14:17]
	v_mfma_f32_16x16x32_bf16 v[10:13], v[146:149], v[226:229], 0
	v_mfma_f32_16x16x32_bf16 v[10:13], v[150:153], v[230:233], v[10:13]
	v_mfma_f32_16x16x32_bf16 v[54:57], v[154:157], v[190:193], 0
	v_mfma_f32_16x16x32_bf16 v[54:57], v[158:161], v[194:197], v[54:57]
	v_mfma_f32_16x16x32_bf16 v[50:53], v[182:185], v[190:193], 0
	v_mfma_f32_16x16x32_bf16 v[50:53], v[186:189], v[194:197], v[50:53]
	v_mfma_f32_16x16x32_bf16 v[38:41], v[154:157], v[198:201], 0
	v_mfma_f32_16x16x32_bf16 v[38:41], v[158:161], v[214:217], v[38:41]
	v_mfma_f32_16x16x32_bf16 v[34:37], v[182:185], v[198:201], 0
	v_mfma_f32_16x16x32_bf16 v[34:37], v[186:189], v[214:217], v[34:37]
	v_mfma_f32_16x16x32_bf16 v[22:25], v[154:157], v[218:221], 0
	v_mfma_f32_16x16x32_bf16 v[22:25], v[158:161], v[222:225], v[22:25]
	v_mfma_f32_16x16x32_bf16 v[18:21], v[182:185], v[218:221], 0
	v_mfma_f32_16x16x32_bf16 v[18:21], v[186:189], v[222:225], v[18:21]
	v_mfma_f32_16x16x32_bf16 v[6:9], v[154:157], v[226:229], 0
	v_mfma_f32_16x16x32_bf16 v[6:9], v[158:161], v[230:233], v[6:9]
	v_mfma_f32_16x16x32_bf16 v[2:5], v[182:185], v[226:229], 0
	v_mfma_f32_16x16x32_bf16 v[2:5], v[186:189], v[230:233], v[2:5]
	s_barrier
	s_add_i32 s20, 0, 0x18000
	s_add_i32 s21, 0, 0x1c000
	v_add_u32_e32 v150, s20, v139
	v_add_u32_e32 v186, s21, v139
	ds_read_b128 v[134:137], v150
	ds_read_b128 v[142:145], v150 offset:1024
	ds_read_b128 v[146:149], v150 offset:2048
	ds_read_b128 v[150:153], v150 offset:3072
	ds_read_b128 v[154:157], v186
	ds_read_b128 v[158:161], v186 offset:1024
	ds_read_b128 v[182:185], v186 offset:2048
	ds_read_b128 v[186:189], v186 offset:3072
	ds_read_b128 v[190:193], v141 offset:32768
	ds_read_b128 v[194:197], v141 offset:33792
	ds_read_b128 v[198:201], v141 offset:34816
	ds_read_b128 v[214:217], v141 offset:35840
	ds_read_b128 v[218:221], v141 offset:36864
	ds_read_b128 v[222:225], v141 offset:37888
	ds_read_b128 v[226:229], v141 offset:38912
	ds_read_b128 v[230:233], v141 offset:39936
	s_mov_b32 m0, s91
	v_lshl_add_u64 v[234:235], v[202:203], 0, s[72:73]
	global_load_lds_dwordx4 v[234:235], off
	v_lshl_add_u64 v[234:235], v[202:203], 0, s[74:75]
	s_mov_b32 m0, s96
	s_nop 0
	global_load_lds_dwordx4 v[234:235], off
	s_waitcnt vmcnt(8)
	s_waitcnt lgkmcnt(0)
	s_barrier
	s_waitcnt lgkmcnt(0)
	v_mfma_f32_16x16x32_bf16 v[126:129], v[134:137], v[190:193], v[126:129]
	v_mfma_f32_16x16x32_bf16 v[126:129], v[142:145], v[194:197], v[126:129]
	v_mfma_f32_16x16x32_bf16 v[122:125], v[146:149], v[190:193], v[122:125]
	v_mfma_f32_16x16x32_bf16 v[122:125], v[150:153], v[194:197], v[122:125]
	v_mfma_f32_16x16x32_bf16 v[110:113], v[134:137], v[198:201], v[110:113]
	v_mfma_f32_16x16x32_bf16 v[110:113], v[142:145], v[214:217], v[110:113]
	v_mfma_f32_16x16x32_bf16 v[106:109], v[146:149], v[198:201], v[106:109]
	v_mfma_f32_16x16x32_bf16 v[106:109], v[150:153], v[214:217], v[106:109]
	v_mfma_f32_16x16x32_bf16 v[94:97], v[134:137], v[218:221], v[94:97]
	v_mfma_f32_16x16x32_bf16 v[94:97], v[142:145], v[222:225], v[94:97]
	v_mfma_f32_16x16x32_bf16 v[90:93], v[146:149], v[218:221], v[90:93]
	v_mfma_f32_16x16x32_bf16 v[90:93], v[150:153], v[222:225], v[90:93]
	v_mfma_f32_16x16x32_bf16 v[78:81], v[134:137], v[226:229], v[78:81]
	v_mfma_f32_16x16x32_bf16 v[78:81], v[142:145], v[230:233], v[78:81]
	v_mfma_f32_16x16x32_bf16 v[74:77], v[146:149], v[226:229], v[74:77]
	v_mfma_f32_16x16x32_bf16 v[74:77], v[150:153], v[230:233], v[74:77]
	v_mfma_f32_16x16x32_bf16 v[118:121], v[154:157], v[190:193], v[118:121]
	v_mfma_f32_16x16x32_bf16 v[118:121], v[158:161], v[194:197], v[118:121]
	v_mfma_f32_16x16x32_bf16 v[114:117], v[182:185], v[190:193], v[114:117]
	v_mfma_f32_16x16x32_bf16 v[114:117], v[186:189], v[194:197], v[114:117]
	v_mfma_f32_16x16x32_bf16 v[102:105], v[154:157], v[198:201], v[102:105]
	v_mfma_f32_16x16x32_bf16 v[102:105], v[158:161], v[214:217], v[102:105]
	v_mfma_f32_16x16x32_bf16 v[98:101], v[182:185], v[198:201], v[98:101]
	v_mfma_f32_16x16x32_bf16 v[98:101], v[186:189], v[214:217], v[98:101]
	v_mfma_f32_16x16x32_bf16 v[86:89], v[154:157], v[218:221], v[86:89]
	v_mfma_f32_16x16x32_bf16 v[86:89], v[158:161], v[222:225], v[86:89]
	v_mfma_f32_16x16x32_bf16 v[82:85], v[182:185], v[218:221], v[82:85]
	v_mfma_f32_16x16x32_bf16 v[82:85], v[186:189], v[222:225], v[82:85]
	v_mfma_f32_16x16x32_bf16 v[70:73], v[154:157], v[226:229], v[70:73]
	v_mfma_f32_16x16x32_bf16 v[70:73], v[158:161], v[230:233], v[70:73]
	v_mfma_f32_16x16x32_bf16 v[66:69], v[182:185], v[226:229], v[66:69]
	v_mfma_f32_16x16x32_bf16 v[66:69], v[186:189], v[230:233], v[66:69]
	s_barrier
	ds_read_b128 v[190:193], v141 offset:49152
	ds_read_b128 v[194:197], v141 offset:50176
	ds_read_b128 v[198:201], v141 offset:51200
	ds_read_b128 v[214:217], v141 offset:52224
	ds_read_b128 v[218:221], v141 offset:53248
	ds_read_b128 v[222:225], v141 offset:54272
	ds_read_b128 v[226:229], v141 offset:55296
	ds_read_b128 v[230:233], v141 offset:56320
	s_add_i32 s20, s20, s88
	s_mov_b32 m0, s20
	v_lshl_add_u64 v[234:235], v[162:163], 0, s[34:35]
	global_load_lds_dwordx4 v[234:235], off
	v_lshl_add_u64 v[234:235], v[162:163], 0, s[80:81]
	s_add_i32 m0, s20, 0x2000
	s_add_i32 s20, s21, s88
	global_load_lds_dwordx4 v[234:235], off
	v_lshl_add_u64 v[234:235], v[162:163], 0, s[38:39]
	s_mov_b32 m0, s20
	v_lshl_add_u64 v[162:163], v[162:163], 0, s[86:87]
	global_load_lds_dwordx4 v[234:235], off
	s_add_i32 m0, s20, 0x2000
	s_nop 0
	global_load_lds_dwordx4 v[162:163], off
	v_lshl_add_u64 v[162:163], v[202:203], 0, s[34:35]
	s_mov_b32 m0, s97
	s_nop 0
	global_load_lds_dwordx4 v[162:163], off
	v_lshl_add_u64 v[162:163], v[202:203], 0, s[80:81]
	s_mov_b32 m0, s58
	s_nop 0
	global_load_lds_dwordx4 v[162:163], off
	s_waitcnt vmcnt(8)
	s_waitcnt lgkmcnt(0)
	s_barrier
	s_waitcnt lgkmcnt(0)
	v_mfma_f32_16x16x32_bf16 v[62:65], v[134:137], v[190:193], v[62:65]
	v_mfma_f32_16x16x32_bf16 v[62:65], v[142:145], v[194:197], v[62:65]
	v_mfma_f32_16x16x32_bf16 v[58:61], v[146:149], v[190:193], v[58:61]
	v_mfma_f32_16x16x32_bf16 v[58:61], v[150:153], v[194:197], v[58:61]
	v_mfma_f32_16x16x32_bf16 v[46:49], v[134:137], v[198:201], v[46:49]
	v_mfma_f32_16x16x32_bf16 v[46:49], v[142:145], v[214:217], v[46:49]
	v_mfma_f32_16x16x32_bf16 v[42:45], v[146:149], v[198:201], v[42:45]
	v_mfma_f32_16x16x32_bf16 v[42:45], v[150:153], v[214:217], v[42:45]
	v_mfma_f32_16x16x32_bf16 v[30:33], v[134:137], v[218:221], v[30:33]
	v_mfma_f32_16x16x32_bf16 v[30:33], v[142:145], v[222:225], v[30:33]
	v_mfma_f32_16x16x32_bf16 v[26:29], v[146:149], v[218:221], v[26:29]
	v_mfma_f32_16x16x32_bf16 v[26:29], v[150:153], v[222:225], v[26:29]
	v_mfma_f32_16x16x32_bf16 v[14:17], v[134:137], v[226:229], v[14:17]
	v_mfma_f32_16x16x32_bf16 v[14:17], v[142:145], v[230:233], v[14:17]
	v_mfma_f32_16x16x32_bf16 v[10:13], v[146:149], v[226:229], v[10:13]
	v_mfma_f32_16x16x32_bf16 v[10:13], v[150:153], v[230:233], v[10:13]
	s_add_i32 s84, s84, 2
	s_add_u32 s6, s6, 0x100
	s_addc_u32 s7, s7, 0
	s_add_u32 s49, s49, 0x100
	s_addc_u32 s51, s51, 0
	v_mfma_f32_16x16x32_bf16 v[54:57], v[154:157], v[190:193], v[54:57]
	v_mfma_f32_16x16x32_bf16 v[54:57], v[158:161], v[194:197], v[54:57]
	v_mfma_f32_16x16x32_bf16 v[50:53], v[182:185], v[190:193], v[50:53]
	v_mfma_f32_16x16x32_bf16 v[50:53], v[186:189], v[194:197], v[50:53]
	v_mfma_f32_16x16x32_bf16 v[38:41], v[154:157], v[198:201], v[38:41]
	v_mfma_f32_16x16x32_bf16 v[38:41], v[158:161], v[214:217], v[38:41]
	v_mfma_f32_16x16x32_bf16 v[34:37], v[182:185], v[198:201], v[34:37]
	v_mfma_f32_16x16x32_bf16 v[34:37], v[186:189], v[214:217], v[34:37]
	v_mfma_f32_16x16x32_bf16 v[22:25], v[154:157], v[218:221], v[22:25]
	v_mfma_f32_16x16x32_bf16 v[22:25], v[158:161], v[222:225], v[22:25]
	v_mfma_f32_16x16x32_bf16 v[18:21], v[182:185], v[218:221], v[18:21]
	v_mfma_f32_16x16x32_bf16 v[18:21], v[186:189], v[222:225], v[18:21]
	v_mfma_f32_16x16x32_bf16 v[6:9], v[154:157], v[226:229], v[6:9]
	v_mfma_f32_16x16x32_bf16 v[6:9], v[158:161], v[230:233], v[6:9]
	v_mfma_f32_16x16x32_bf16 v[2:5], v[182:185], v[226:229], v[2:5]
	v_mfma_f32_16x16x32_bf16 v[2:5], v[186:189], v[230:233], v[2:5]
	s_barrier
	s_branch .LBB0_604
	.p2alignl 6, 3212836864
.LBB0_604:
	s_add_i32 s22, 0, 0x10000
	s_add_i32 s23, 0, 0x14000
	v_add_u32_e32 v150, s22, v139
	v_add_u32_e32 v162, s23, v139
	ds_read_b128 v[134:137], v150
	ds_read_b128 v[142:145], v150 offset:1024
	ds_read_b128 v[146:149], v150 offset:2048
	ds_read_b128 v[150:153], v150 offset:3072
	ds_read_b128 v[154:157], v162
	ds_read_b128 v[158:161], v162 offset:1024
	ds_read_b128 v[182:185], v162 offset:2048
	ds_read_b128 v[186:189], v162 offset:3072
	ds_read_b128 v[190:193], v141
	ds_read_b128 v[194:197], v141 offset:1024
	ds_read_b128 v[198:201], v141 offset:2048
	ds_read_b128 v[214:217], v141 offset:3072
	ds_read_b128 v[218:221], v141 offset:4096
	ds_read_b128 v[222:225], v141 offset:5120
	ds_read_b128 v[226:229], v141 offset:6144
	ds_read_b128 v[230:233], v141 offset:7168
	s_add_u32 s20, s6, 0xfffe0080
	s_addc_u32 s21, s7, -1
	s_cmp_eq_u32 s84, 4
	s_cselect_b32 s69, s42, s21
	s_cselect_b32 s68, s43, s20
	s_cselect_b32 s21, s46, s51
	s_cselect_b32 s20, s47, s49
	s_add_i32 m0, s89, 0xc000
	v_lshl_add_u64 v[162:163], s[6:7], 0, v[132:133]
	global_load_lds_dwordx4 v[162:163], off
	v_lshl_add_u64 v[162:163], v[162:163], 0, s[64:65]
	s_add_i32 m0, s89, 0xe000
	s_nop 0
	global_load_lds_dwordx4 v[162:163], off
	s_waitcnt vmcnt(8)
	s_waitcnt lgkmcnt(0)
	s_barrier
	s_waitcnt lgkmcnt(0)
	v_mfma_f32_16x16x32_bf16 v[126:129], v[134:137], v[190:193], v[126:129]
	v_mfma_f32_16x16x32_bf16 v[126:129], v[142:145], v[194:197], v[126:129]
	v_mfma_f32_16x16x32_bf16 v[122:125], v[146:149], v[190:193], v[122:125]
	v_mfma_f32_16x16x32_bf16 v[122:125], v[150:153], v[194:197], v[122:125]
	v_mfma_f32_16x16x32_bf16 v[110:113], v[134:137], v[198:201], v[110:113]
	v_mfma_f32_16x16x32_bf16 v[110:113], v[142:145], v[214:217], v[110:113]
	v_mfma_f32_16x16x32_bf16 v[106:109], v[146:149], v[198:201], v[106:109]
	v_mfma_f32_16x16x32_bf16 v[106:109], v[150:153], v[214:217], v[106:109]
	v_mfma_f32_16x16x32_bf16 v[94:97], v[134:137], v[218:221], v[94:97]
	v_mfma_f32_16x16x32_bf16 v[94:97], v[142:145], v[222:225], v[94:97]
	v_mfma_f32_16x16x32_bf16 v[90:93], v[146:149], v[218:221], v[90:93]
	v_mfma_f32_16x16x32_bf16 v[90:93], v[150:153], v[222:225], v[90:93]
	v_mfma_f32_16x16x32_bf16 v[78:81], v[134:137], v[226:229], v[78:81]
	v_mfma_f32_16x16x32_bf16 v[78:81], v[142:145], v[230:233], v[78:81]
	v_mfma_f32_16x16x32_bf16 v[74:77], v[146:149], v[226:229], v[74:77]
	v_mfma_f32_16x16x32_bf16 v[74:77], v[150:153], v[230:233], v[74:77]
	v_mfma_f32_16x16x32_bf16 v[118:121], v[154:157], v[190:193], v[118:121]
	v_mfma_f32_16x16x32_bf16 v[118:121], v[158:161], v[194:197], v[118:121]
	v_mfma_f32_16x16x32_bf16 v[114:117], v[182:185], v[190:193], v[114:117]
	v_mfma_f32_16x16x32_bf16 v[114:117], v[186:189], v[194:197], v[114:117]
	v_mfma_f32_16x16x32_bf16 v[102:105], v[154:157], v[198:201], v[102:105]
	v_mfma_f32_16x16x32_bf16 v[102:105], v[158:161], v[214:217], v[102:105]
	v_mfma_f32_16x16x32_bf16 v[98:101], v[182:185], v[198:201], v[98:101]
	v_mfma_f32_16x16x32_bf16 v[98:101], v[186:189], v[214:217], v[98:101]
	v_mfma_f32_16x16x32_bf16 v[86:89], v[154:157], v[218:221], v[86:89]
	v_mfma_f32_16x16x32_bf16 v[86:89], v[158:161], v[222:225], v[86:89]
	v_mfma_f32_16x16x32_bf16 v[82:85], v[182:185], v[218:221], v[82:85]
	v_mfma_f32_16x16x32_bf16 v[82:85], v[186:189], v[222:225], v[82:85]
	v_mfma_f32_16x16x32_bf16 v[70:73], v[154:157], v[226:229], v[70:73]
	v_mfma_f32_16x16x32_bf16 v[70:73], v[158:161], v[230:233], v[70:73]
	v_mfma_f32_16x16x32_bf16 v[66:69], v[182:185], v[226:229], v[66:69]
	v_mfma_f32_16x16x32_bf16 v[66:69], v[186:189], v[230:233], v[66:69]
	s_barrier
	ds_read_b128 v[190:193], v141 offset:16384
	ds_read_b128 v[194:197], v141 offset:17408
	ds_read_b128 v[198:201], v141 offset:18432
	ds_read_b128 v[214:217], v141 offset:19456
	ds_read_b128 v[218:221], v141 offset:20480
	ds_read_b128 v[222:225], v141 offset:21504
	ds_read_b128 v[226:229], v141 offset:22528
	ds_read_b128 v[230:233], v141 offset:23552
	v_lshl_add_u64 v[162:163], s[20:21], 0, v[0:1]
	s_add_i32 s20, s22, s88
	s_mov_b32 m0, s20
	s_nop 0
	s_nop 0
	global_load_lds_dwordx4 v[162:163], off
	v_lshl_add_u64 v[202:203], v[162:163], 0, s[64:65]
	s_add_i32 m0, s20, 0x2000
	s_add_i32 s20, s23, s88
	global_load_lds_dwordx4 v[202:203], off
	v_lshl_add_u64 v[202:203], v[162:163], 0, s[72:73]
	s_mov_b32 m0, s20
	s_nop 0
	global_load_lds_dwordx4 v[202:203], off
	v_lshl_add_u64 v[202:203], v[162:163], 0, s[74:75]
	s_add_i32 m0, s20, 0x2000
	s_nop 0
	global_load_lds_dwordx4 v[202:203], off
	v_lshl_add_u64 v[202:203], s[68:69], 0, v[130:131]
	s_mov_b32 m0, s89
	v_lshl_add_u64 v[234:235], v[202:203], 0, s[64:65]
	global_load_lds_dwordx4 v[202:203], off
	s_mov_b32 m0, s90
	s_nop 0
	global_load_lds_dwordx4 v[234:235], off
	s_waitcnt vmcnt(8)
	s_waitcnt lgkmcnt(0)
	s_barrier
	s_waitcnt lgkmcnt(0)
	v_mfma_f32_16x16x32_bf16 v[62:65], v[134:137], v[190:193], v[62:65]
	v_mfma_f32_16x16x32_bf16 v[62:65], v[142:145], v[194:197], v[62:65]
	v_mfma_f32_16x16x32_bf16 v[58:61], v[146:149], v[190:193], v[58:61]
	v_mfma_f32_16x16x32_bf16 v[58:61], v[150:153], v[194:197], v[58:61]
	v_mfma_f32_16x16x32_bf16 v[46:49], v[134:137], v[198:201], v[46:49]
	v_mfma_f32_16x16x32_bf16 v[46:49], v[142:145], v[214:217], v[46:49]
	v_mfma_f32_16x16x32_bf16 v[42:45], v[146:149], v[198:201], v[42:45]
	v_mfma_f32_16x16x32_bf16 v[42:45], v[150:153], v[214:217], v[42:45]
	v_mfma_f32_16x16x32_bf16 v[30:33], v[134:137], v[218:221], v[30:33]
	v_mfma_f32_16x16x32_bf16 v[30:33], v[142:145], v[222:225], v[30:33]
	v_mfma_f32_16x16x32_bf16 v[26:29], v[146:149], v[218:221], v[26:29]
	v_mfma_f32_16x16x32_bf16 v[26:29], v[150:153], v[222:225], v[26:29]
	v_mfma_f32_16x16x32_bf16 v[14:17], v[134:137], v[226:229], v[14:17]
	v_mfma_f32_16x16x32_bf16 v[14:17], v[142:145], v[230:233], v[14:17]
	v_mfma_f32_16x16x32_bf16 v[10:13], v[146:149], v[226:229], v[10:13]
	v_mfma_f32_16x16x32_bf16 v[10:13], v[150:153], v[230:233], v[10:13]
	v_mfma_f32_16x16x32_bf16 v[54:57], v[154:157], v[190:193], v[54:57]
	v_mfma_f32_16x16x32_bf16 v[54:57], v[158:161], v[194:197], v[54:57]
	v_mfma_f32_16x16x32_bf16 v[50:53], v[182:185], v[190:193], v[50:53]
	v_mfma_f32_16x16x32_bf16 v[50:53], v[186:189], v[194:197], v[50:53]
	v_mfma_f32_16x16x32_bf16 v[38:41], v[154:157], v[198:201], v[38:41]
	v_mfma_f32_16x16x32_bf16 v[38:41], v[158:161], v[214:217], v[38:41]
	v_mfma_f32_16x16x32_bf16 v[34:37], v[182:185], v[198:201], v[34:37]
	v_mfma_f32_16x16x32_bf16 v[34:37], v[186:189], v[214:217], v[34:37]
	v_mfma_f32_16x16x32_bf16 v[22:25], v[154:157], v[218:221], v[22:25]
	v_mfma_f32_16x16x32_bf16 v[22:25], v[158:161], v[222:225], v[22:25]
	v_mfma_f32_16x16x32_bf16 v[18:21], v[182:185], v[218:221], v[18:21]
	v_mfma_f32_16x16x32_bf16 v[18:21], v[186:189], v[222:225], v[18:21]
	v_mfma_f32_16x16x32_bf16 v[6:9], v[154:157], v[226:229], v[6:9]
	v_mfma_f32_16x16x32_bf16 v[6:9], v[158:161], v[230:233], v[6:9]
	v_mfma_f32_16x16x32_bf16 v[2:5], v[182:185], v[226:229], v[2:5]
	v_mfma_f32_16x16x32_bf16 v[2:5], v[186:189], v[230:233], v[2:5]
	s_barrier
	s_add_i32 s20, 0, 0x18000
	s_add_i32 s21, 0, 0x1c000
	v_add_u32_e32 v150, s20, v139
	v_add_u32_e32 v186, s21, v139
	ds_read_b128 v[134:137], v150
	ds_read_b128 v[142:145], v150 offset:1024
	ds_read_b128 v[146:149], v150 offset:2048
	ds_read_b128 v[150:153], v150 offset:3072
	ds_read_b128 v[154:157], v186
	ds_read_b128 v[158:161], v186 offset:1024
	ds_read_b128 v[182:185], v186 offset:2048
	ds_read_b128 v[186:189], v186 offset:3072
	ds_read_b128 v[190:193], v141 offset:32768
	ds_read_b128 v[194:197], v141 offset:33792
	ds_read_b128 v[198:201], v141 offset:34816
	ds_read_b128 v[214:217], v141 offset:35840
	ds_read_b128 v[218:221], v141 offset:36864
	ds_read_b128 v[222:225], v141 offset:37888
	ds_read_b128 v[226:229], v141 offset:38912
	ds_read_b128 v[230:233], v141 offset:39936
	s_mov_b32 m0, s91
	v_lshl_add_u64 v[234:235], v[202:203], 0, s[72:73]
	global_load_lds_dwordx4 v[234:235], off
	v_lshl_add_u64 v[234:235], v[202:203], 0, s[74:75]
	s_mov_b32 m0, s96
	s_nop 0
	global_load_lds_dwordx4 v[234:235], off
	s_waitcnt vmcnt(8)
	s_waitcnt lgkmcnt(0)
	s_barrier
	s_waitcnt lgkmcnt(0)
	v_mfma_f32_16x16x32_bf16 v[126:129], v[134:137], v[190:193], v[126:129]
	v_mfma_f32_16x16x32_bf16 v[126:129], v[142:145], v[194:197], v[126:129]
	v_mfma_f32_16x16x32_bf16 v[122:125], v[146:149], v[190:193], v[122:125]
	v_mfma_f32_16x16x32_bf16 v[122:125], v[150:153], v[194:197], v[122:125]
	v_mfma_f32_16x16x32_bf16 v[110:113], v[134:137], v[198:201], v[110:113]
	v_mfma_f32_16x16x32_bf16 v[110:113], v[142:145], v[214:217], v[110:113]
	v_mfma_f32_16x16x32_bf16 v[106:109], v[146:149], v[198:201], v[106:109]
	v_mfma_f32_16x16x32_bf16 v[106:109], v[150:153], v[214:217], v[106:109]
	v_mfma_f32_16x16x32_bf16 v[94:97], v[134:137], v[218:221], v[94:97]
	v_mfma_f32_16x16x32_bf16 v[94:97], v[142:145], v[222:225], v[94:97]
	v_mfma_f32_16x16x32_bf16 v[90:93], v[146:149], v[218:221], v[90:93]
	v_mfma_f32_16x16x32_bf16 v[90:93], v[150:153], v[222:225], v[90:93]
	v_mfma_f32_16x16x32_bf16 v[78:81], v[134:137], v[226:229], v[78:81]
	v_mfma_f32_16x16x32_bf16 v[78:81], v[142:145], v[230:233], v[78:81]
	v_mfma_f32_16x16x32_bf16 v[74:77], v[146:149], v[226:229], v[74:77]
	v_mfma_f32_16x16x32_bf16 v[74:77], v[150:153], v[230:233], v[74:77]
	v_mfma_f32_16x16x32_bf16 v[118:121], v[154:157], v[190:193], v[118:121]
	v_mfma_f32_16x16x32_bf16 v[118:121], v[158:161], v[194:197], v[118:121]
	v_mfma_f32_16x16x32_bf16 v[114:117], v[182:185], v[190:193], v[114:117]
	v_mfma_f32_16x16x32_bf16 v[114:117], v[186:189], v[194:197], v[114:117]
	v_mfma_f32_16x16x32_bf16 v[102:105], v[154:157], v[198:201], v[102:105]
	v_mfma_f32_16x16x32_bf16 v[102:105], v[158:161], v[214:217], v[102:105]
	v_mfma_f32_16x16x32_bf16 v[98:101], v[182:185], v[198:201], v[98:101]
	v_mfma_f32_16x16x32_bf16 v[98:101], v[186:189], v[214:217], v[98:101]
	v_mfma_f32_16x16x32_bf16 v[86:89], v[154:157], v[218:221], v[86:89]
	v_mfma_f32_16x16x32_bf16 v[86:89], v[158:161], v[222:225], v[86:89]
	v_mfma_f32_16x16x32_bf16 v[82:85], v[182:185], v[218:221], v[82:85]
	v_mfma_f32_16x16x32_bf16 v[82:85], v[186:189], v[222:225], v[82:85]
	v_mfma_f32_16x16x32_bf16 v[70:73], v[154:157], v[226:229], v[70:73]
	v_mfma_f32_16x16x32_bf16 v[70:73], v[158:161], v[230:233], v[70:73]
	v_mfma_f32_16x16x32_bf16 v[66:69], v[182:185], v[226:229], v[66:69]
	v_mfma_f32_16x16x32_bf16 v[66:69], v[186:189], v[230:233], v[66:69]
	s_barrier
	ds_read_b128 v[190:193], v141 offset:49152
	ds_read_b128 v[194:197], v141 offset:50176
	ds_read_b128 v[198:201], v141 offset:51200
	ds_read_b128 v[214:217], v141 offset:52224
	ds_read_b128 v[218:221], v141 offset:53248
	ds_read_b128 v[222:225], v141 offset:54272
	ds_read_b128 v[226:229], v141 offset:55296
	ds_read_b128 v[230:233], v141 offset:56320
	s_add_i32 s20, s20, s88
	s_mov_b32 m0, s20
	v_lshl_add_u64 v[234:235], v[162:163], 0, s[34:35]
	global_load_lds_dwordx4 v[234:235], off
	v_lshl_add_u64 v[234:235], v[162:163], 0, s[80:81]
	s_add_i32 m0, s20, 0x2000
	s_add_i32 s20, s21, s88
	global_load_lds_dwordx4 v[234:235], off
	v_lshl_add_u64 v[234:235], v[162:163], 0, s[38:39]
	s_mov_b32 m0, s20
	v_lshl_add_u64 v[162:163], v[162:163], 0, s[86:87]
	global_load_lds_dwordx4 v[234:235], off
	s_add_i32 m0, s20, 0x2000
	s_nop 0
	global_load_lds_dwordx4 v[162:163], off
	v_lshl_add_u64 v[162:163], v[202:203], 0, s[34:35]
	s_mov_b32 m0, s97
	s_nop 0
	global_load_lds_dwordx4 v[162:163], off
	v_lshl_add_u64 v[162:163], v[202:203], 0, s[80:81]
	s_mov_b32 m0, s58
	s_nop 0
	global_load_lds_dwordx4 v[162:163], off
	s_waitcnt vmcnt(8)
	s_waitcnt lgkmcnt(0)
	s_barrier
	s_waitcnt lgkmcnt(0)
	v_mfma_f32_16x16x32_bf16 v[62:65], v[134:137], v[190:193], v[62:65]
	v_mfma_f32_16x16x32_bf16 v[62:65], v[142:145], v[194:197], v[62:65]
	v_mfma_f32_16x16x32_bf16 v[58:61], v[146:149], v[190:193], v[58:61]
	v_mfma_f32_16x16x32_bf16 v[58:61], v[150:153], v[194:197], v[58:61]
	v_mfma_f32_16x16x32_bf16 v[46:49], v[134:137], v[198:201], v[46:49]
	v_mfma_f32_16x16x32_bf16 v[46:49], v[142:145], v[214:217], v[46:49]
	v_mfma_f32_16x16x32_bf16 v[42:45], v[146:149], v[198:201], v[42:45]
	v_mfma_f32_16x16x32_bf16 v[42:45], v[150:153], v[214:217], v[42:45]
	v_mfma_f32_16x16x32_bf16 v[30:33], v[134:137], v[218:221], v[30:33]
	v_mfma_f32_16x16x32_bf16 v[30:33], v[142:145], v[222:225], v[30:33]
	v_mfma_f32_16x16x32_bf16 v[26:29], v[146:149], v[218:221], v[26:29]
	v_mfma_f32_16x16x32_bf16 v[26:29], v[150:153], v[222:225], v[26:29]
	v_mfma_f32_16x16x32_bf16 v[14:17], v[134:137], v[226:229], v[14:17]
	v_mfma_f32_16x16x32_bf16 v[14:17], v[142:145], v[230:233], v[14:17]
	v_mfma_f32_16x16x32_bf16 v[10:13], v[146:149], v[226:229], v[10:13]
	v_mfma_f32_16x16x32_bf16 v[10:13], v[150:153], v[230:233], v[10:13]
	s_add_i32 s84, s84, 2
	s_add_u32 s6, s6, 0x100
	s_addc_u32 s7, s7, 0
	s_add_u32 s49, s49, 0x100
	s_addc_u32 s51, s51, 0
	v_mfma_f32_16x16x32_bf16 v[54:57], v[154:157], v[190:193], v[54:57]
	v_mfma_f32_16x16x32_bf16 v[54:57], v[158:161], v[194:197], v[54:57]
	v_mfma_f32_16x16x32_bf16 v[50:53], v[182:185], v[190:193], v[50:53]
	v_mfma_f32_16x16x32_bf16 v[50:53], v[186:189], v[194:197], v[50:53]
	v_mfma_f32_16x16x32_bf16 v[38:41], v[154:157], v[198:201], v[38:41]
	v_mfma_f32_16x16x32_bf16 v[38:41], v[158:161], v[214:217], v[38:41]
	v_mfma_f32_16x16x32_bf16 v[34:37], v[182:185], v[198:201], v[34:37]
	v_mfma_f32_16x16x32_bf16 v[34:37], v[186:189], v[214:217], v[34:37]
	v_mfma_f32_16x16x32_bf16 v[22:25], v[154:157], v[218:221], v[22:25]
	v_mfma_f32_16x16x32_bf16 v[22:25], v[158:161], v[222:225], v[22:25]
	v_mfma_f32_16x16x32_bf16 v[18:21], v[182:185], v[218:221], v[18:21]
	v_mfma_f32_16x16x32_bf16 v[18:21], v[186:189], v[222:225], v[18:21]
	v_mfma_f32_16x16x32_bf16 v[6:9], v[154:157], v[226:229], v[6:9]
	v_mfma_f32_16x16x32_bf16 v[6:9], v[158:161], v[230:233], v[6:9]
	v_mfma_f32_16x16x32_bf16 v[2:5], v[182:185], v[226:229], v[2:5]
	v_mfma_f32_16x16x32_bf16 v[2:5], v[186:189], v[230:233], v[2:5]
	s_barrier
	s_cmp_gt_u32 s84, 5
	s_cbranch_scc0 .LBB0_604
	s_setprio 0
	s_and_b64 vcc, exec, s[52:53]
	s_cbranch_vccz .LBB0_607
	s_barrier

.LBB0_777:
	s_ashr_i32 s61, s60, 31
	s_lshl_b64 s[20:21], s[60:61], 19
	s_add_u32 s62, s94, s20
	s_addc_u32 s63, s95, s21
	s_and_b64 s[20:21], s[56:57], exec
	s_cselect_b32 s61, s63, s77
	s_cselect_b32 s85, s62, s76
	s_ashr_i32 s59, s58, 31
	s_lshl_b64 s[20:21], s[58:59], 19
	s_add_u32 s68, s15, s20
	s_addc_u32 s69, s42, s21
	s_and_b64 s[20:21], s[56:57], exec
	s_cselect_b32 s59, s69, s79
	s_cselect_b32 s86, s68, s78
	s_add_u32 s76, s76, 0x40080
	s_addc_u32 s77, s77, 0
	s_add_u32 s87, s78, 0x100
	v_mov_b32_e32 v2, 0
	s_addc_u32 vcc_lo, s79, 0
	s_mov_b32 vcc_hi, -2
	s_waitcnt lgkmcnt(0)
	s_add_i32 s22, 0, 0x10000
	s_add_i32 s23, 0, 0x14000
	v_add_u32_e32 v142, s22, v193
	v_add_u32_e32 v158, s23, v193
	ds_read_b128 v[130:133], v142
	ds_read_b128 v[134:137], v142 offset:1024
	ds_read_b128 v[138:141], v142 offset:2048
	ds_read_b128 v[142:145], v142 offset:3072
	ds_read_b128 v[146:149], v158
	ds_read_b128 v[150:153], v158 offset:1024
	ds_read_b128 v[154:157], v158 offset:2048
	ds_read_b128 v[158:161], v158 offset:3072
	ds_read_b128 v[184:187], v196
	ds_read_b128 v[188:191], v196 offset:1024
	ds_read_b128 v[198:201], v196 offset:2048
	ds_read_b128 v[214:217], v196 offset:3072
	ds_read_b128 v[218:221], v196 offset:4096
	ds_read_b128 v[222:225], v196 offset:5120
	ds_read_b128 v[226:229], v196 offset:6144
	ds_read_b128 v[230:233], v196 offset:7168
	s_cmp_eq_u64 s[50:51], 0
	s_cbranch_scc0 .Lpr_778
	s_setprio 1

.Lmid1_778:
	s_add_i32 s22, 0, 0x10000
	s_add_i32 s23, 0, 0x14000
	s_add_u32 s20, s76, 0xfffc0080
	s_addc_u32 s21, s77, -1
	s_cmp_eq_u32 vcc_hi, 12
	s_cselect_b32 s79, s61, s21
	s_cselect_b32 s78, s85, s20
	s_cselect_b32 s21, s59, vcc_lo
	s_cselect_b32 s20, s86, s87
	s_add_i32 m0, s43, 0xc000
	v_lshl_add_u64 v[202:203], s[76:77], 0, v[182:183]
	global_load_lds_dwordx4 v[202:203], off
	v_lshl_add_u64 v[202:203], v[202:203], 0, s[72:73]
	s_add_i32 m0, s43, 0xe000
	s_nop 0
	global_load_lds_dwordx4 v[202:203], off
	s_waitcnt vmcnt(8)
	s_waitcnt lgkmcnt(0)
	s_barrier
	s_waitcnt lgkmcnt(0)
	v_mfma_f32_16x16x32_bf16 v[126:129], v[130:133], v[184:187], 0
	v_mfma_f32_16x16x32_bf16 v[126:129], v[134:137], v[188:191], v[126:129]
	v_mfma_f32_16x16x32_bf16 v[122:125], v[138:141], v[184:187], 0
	v_mfma_f32_16x16x32_bf16 v[122:125], v[142:145], v[188:191], v[122:125]
	v_mfma_f32_16x16x32_bf16 v[110:113], v[130:133], v[198:201], 0
	v_mfma_f32_16x16x32_bf16 v[110:113], v[134:137], v[214:217], v[110:113]
	v_mfma_f32_16x16x32_bf16 v[106:109], v[138:141], v[198:201], 0
	v_mfma_f32_16x16x32_bf16 v[106:109], v[142:145], v[214:217], v[106:109]
	v_mfma_f32_16x16x32_bf16 v[94:97], v[130:133], v[218:221], 0
	v_mfma_f32_16x16x32_bf16 v[94:97], v[134:137], v[222:225], v[94:97]
	v_mfma_f32_16x16x32_bf16 v[90:93], v[138:141], v[218:221], 0
	v_mfma_f32_16x16x32_bf16 v[90:93], v[142:145], v[222:225], v[90:93]
	v_mfma_f32_16x16x32_bf16 v[78:81], v[130:133], v[226:229], 0
	v_mfma_f32_16x16x32_bf16 v[78:81], v[134:137], v[230:233], v[78:81]
	v_mfma_f32_16x16x32_bf16 v[74:77], v[138:141], v[226:229], 0
	v_mfma_f32_16x16x32_bf16 v[74:77], v[142:145], v[230:233], v[74:77]
	v_mfma_f32_16x16x32_bf16 v[118:121], v[146:149], v[184:187], 0
	v_mfma_f32_16x16x32_bf16 v[118:121], v[150:153], v[188:191], v[118:121]
	v_mfma_f32_16x16x32_bf16 v[114:117], v[154:157], v[184:187], 0
	v_mfma_f32_16x16x32_bf16 v[114:117], v[158:161], v[188:191], v[114:117]
	v_mfma_f32_16x16x32_bf16 v[102:105], v[146:149], v[198:201], 0
	v_mfma_f32_16x16x32_bf16 v[102:105], v[150:153], v[214:217], v[102:105]
	v_mfma_f32_16x16x32_bf16 v[98:101], v[154:157], v[198:201], 0
	v_mfma_f32_16x16x32_bf16 v[98:101], v[158:161], v[214:217], v[98:101]
	v_mfma_f32_16x16x32_bf16 v[86:89], v[146:149], v[218:221], 0
	v_mfma_f32_16x16x32_bf16 v[86:89], v[150:153], v[222:225], v[86:89]
	v_mfma_f32_16x16x32_bf16 v[82:85], v[154:157], v[218:221], 0
	v_mfma_f32_16x16x32_bf16 v[82:85], v[158:161], v[222:225], v[82:85]
	v_mfma_f32_16x16x32_bf16 v[70:73], v[146:149], v[226:229], 0
	v_mfma_f32_16x16x32_bf16 v[70:73], v[150:153], v[230:233], v[70:73]
	v_mfma_f32_16x16x32_bf16 v[66:69], v[154:157], v[226:229], 0
	v_mfma_f32_16x16x32_bf16 v[66:69], v[158:161], v[230:233], v[66:69]
	s_barrier
	ds_read_b128 v[184:187], v196 offset:16384
	ds_read_b128 v[188:191], v196 offset:17408
	ds_read_b128 v[198:201], v196 offset:18432
	ds_read_b128 v[214:217], v196 offset:19456
	ds_read_b128 v[218:221], v196 offset:20480
	ds_read_b128 v[222:225], v196 offset:21504
	ds_read_b128 v[226:229], v196 offset:22528
	ds_read_b128 v[230:233], v196 offset:23552
	v_lshl_add_u64 v[202:203], s[20:21], 0, v[0:1]
	s_add_i32 s20, s22, s14
	s_mov_b32 m0, s20
	s_nop 0
	s_nop 0
	global_load_lds_dwordx4 v[202:203], off
	v_lshl_add_u64 v[234:235], v[202:203], 0, s[72:73]
	s_add_i32 m0, s20, 0x2000
	s_add_i32 s20, s23, s14
	global_load_lds_dwordx4 v[234:235], off
	v_lshl_add_u64 v[234:235], v[202:203], 0, s[28:29]
	s_mov_b32 m0, s20
	s_nop 0
	global_load_lds_dwordx4 v[234:235], off
	v_lshl_add_u64 v[234:235], v[202:203], 0, s[82:83]
	s_add_i32 m0, s20, 0x2000
	s_nop 0
	global_load_lds_dwordx4 v[234:235], off
	v_lshl_add_u64 v[234:235], s[78:79], 0, v[162:163]
	s_mov_b32 m0, s43
	v_lshl_add_u64 v[236:237], v[234:235], 0, s[72:73]
	global_load_lds_dwordx4 v[234:235], off
	s_mov_b32 m0, s46
	s_nop 0
	global_load_lds_dwordx4 v[236:237], off
	s_waitcnt vmcnt(8)
	s_waitcnt lgkmcnt(0)
	s_barrier
	s_waitcnt lgkmcnt(0)
	v_mfma_f32_16x16x32_bf16 v[62:65], v[130:133], v[184:187], 0
	v_mfma_f32_16x16x32_bf16 v[62:65], v[134:137], v[188:191], v[62:65]
	v_mfma_f32_16x16x32_bf16 v[58:61], v[138:141], v[184:187], 0
	v_mfma_f32_16x16x32_bf16 v[58:61], v[142:145], v[188:191], v[58:61]
	v_mfma_f32_16x16x32_bf16 v[46:49], v[130:133], v[198:201], 0
	v_mfma_f32_16x16x32_bf16 v[46:49], v[134:137], v[214:217], v[46:49]
	v_mfma_f32_16x16x32_bf16 v[42:45], v[138:141], v[198:201], 0
	v_mfma_f32_16x16x32_bf16 v[42:45], v[142:145], v[214:217], v[42:45]
	v_mfma_f32_16x16x32_bf16 v[30:33], v[130:133], v[218:221], 0
	v_mfma_f32_16x16x32_bf16 v[30:33], v[134:137], v[222:225], v[30:33]
	v_mfma_f32_16x16x32_bf16 v[26:29], v[138:141], v[218:221], 0
	v_mfma_f32_16x16x32_bf16 v[26:29], v[142:145], v[222:225], v[26:29]
	v_mfma_f32_16x16x32_bf16 v[14:17], v[130:133], v[226:229], 0
	v_mfma_f32_16x16x32_bf16 v[14:17], v[134:137], v[230:233], v[14:17]
	v_mfma_f32_16x16x32_bf16 v[10:13], v[138:141], v[226:229], 0
	v_mfma_f32_16x16x32_bf16 v[10:13], v[142:145], v[230:233], v[10:13]
	v_mfma_f32_16x16x32_bf16 v[54:57], v[146:149], v[184:187], 0
	v_mfma_f32_16x16x32_bf16 v[54:57], v[150:153], v[188:191], v[54:57]
	v_mfma_f32_16x16x32_bf16 v[50:53], v[154:157], v[184:187], 0
	v_mfma_f32_16x16x32_bf16 v[50:53], v[158:161], v[188:191], v[50:53]
	v_mfma_f32_16x16x32_bf16 v[38:41], v[146:149], v[198:201], 0
	v_mfma_f32_16x16x32_bf16 v[38:41], v[150:153], v[214:217], v[38:41]
	v_mfma_f32_16x16x32_bf16 v[34:37], v[154:157], v[198:201], 0
	v_mfma_f32_16x16x32_bf16 v[34:37], v[158:161], v[214:217], v[34:37]
	v_mfma_f32_16x16x32_bf16 v[22:25], v[146:149], v[218:221], 0
	v_mfma_f32_16x16x32_bf16 v[22:25], v[150:153], v[222:225], v[22:25]
	v_mfma_f32_16x16x32_bf16 v[18:21], v[154:157], v[218:221], 0
	v_mfma_f32_16x16x32_bf16 v[18:21], v[158:161], v[222:225], v[18:21]
	v_mfma_f32_16x16x32_bf16 v[6:9], v[146:149], v[226:229], 0
	v_mfma_f32_16x16x32_bf16 v[6:9], v[150:153], v[230:233], v[6:9]
	v_mfma_f32_16x16x32_bf16 v[2:5], v[154:157], v[226:229], 0
	v_mfma_f32_16x16x32_bf16 v[2:5], v[158:161], v[230:233], v[2:5]
	s_barrier
	s_add_i32 s20, 0, 0x18000
	s_add_i32 s21, 0, 0x1c000
	v_add_u32_e32 v142, s20, v193
	v_add_u32_e32 v158, s21, v193
	ds_read_b128 v[130:133], v142
	ds_read_b128 v[134:137], v142 offset:1024
	ds_read_b128 v[138:141], v142 offset:2048
	ds_read_b128 v[142:145], v142 offset:3072
	ds_read_b128 v[146:149], v158
	ds_read_b128 v[150:153], v158 offset:1024
	ds_read_b128 v[154:157], v158 offset:2048
	ds_read_b128 v[158:161], v158 offset:3072
	ds_read_b128 v[184:187], v196 offset:32768
	ds_read_b128 v[188:191], v196 offset:33792
	ds_read_b128 v[198:201], v196 offset:34816
	ds_read_b128 v[214:217], v196 offset:35840
	ds_read_b128 v[218:221], v196 offset:36864
	ds_read_b128 v[222:225], v196 offset:37888
	ds_read_b128 v[226:229], v196 offset:38912
	ds_read_b128 v[230:233], v196 offset:39936
	s_mov_b32 m0, s47
	v_lshl_add_u64 v[236:237], v[234:235], 0, s[28:29]
	global_load_lds_dwordx4 v[236:237], off
	v_lshl_add_u64 v[236:237], v[234:235], 0, s[82:83]
	s_mov_b32 m0, s88
	s_nop 0
	global_load_lds_dwordx4 v[236:237], off
	s_waitcnt vmcnt(8)
	s_waitcnt lgkmcnt(0)
	s_barrier
	s_waitcnt lgkmcnt(0)
	v_mfma_f32_16x16x32_bf16 v[126:129], v[130:133], v[184:187], v[126:129]
	v_mfma_f32_16x16x32_bf16 v[126:129], v[134:137], v[188:191], v[126:129]
	v_mfma_f32_16x16x32_bf16 v[122:125], v[138:141], v[184:187], v[122:125]
	v_mfma_f32_16x16x32_bf16 v[122:125], v[142:145], v[188:191], v[122:125]
	v_mfma_f32_16x16x32_bf16 v[110:113], v[130:133], v[198:201], v[110:113]
	v_mfma_f32_16x16x32_bf16 v[110:113], v[134:137], v[214:217], v[110:113]
	v_mfma_f32_16x16x32_bf16 v[106:109], v[138:141], v[198:201], v[106:109]
	v_mfma_f32_16x16x32_bf16 v[106:109], v[142:145], v[214:217], v[106:109]
	v_mfma_f32_16x16x32_bf16 v[94:97], v[130:133], v[218:221], v[94:97]
	v_mfma_f32_16x16x32_bf16 v[94:97], v[134:137], v[222:225], v[94:97]
	v_mfma_f32_16x16x32_bf16 v[90:93], v[138:141], v[218:221], v[90:93]
	v_mfma_f32_16x16x32_bf16 v[90:93], v[142:145], v[222:225], v[90:93]
	v_mfma_f32_16x16x32_bf16 v[78:81], v[130:133], v[226:229], v[78:81]
	v_mfma_f32_16x16x32_bf16 v[78:81], v[134:137], v[230:233], v[78:81]
	v_mfma_f32_16x16x32_bf16 v[74:77], v[138:141], v[226:229], v[74:77]
	v_mfma_f32_16x16x32_bf16 v[74:77], v[142:145], v[230:233], v[74:77]
	v_mfma_f32_16x16x32_bf16 v[118:121], v[146:149], v[184:187], v[118:121]
	v_mfma_f32_16x16x32_bf16 v[118:121], v[150:153], v[188:191], v[118:121]
	v_mfma_f32_16x16x32_bf16 v[114:117], v[154:157], v[184:187], v[114:117]
	v_mfma_f32_16x16x32_bf16 v[114:117], v[158:161], v[188:191], v[114:117]
	v_mfma_f32_16x16x32_bf16 v[102:105], v[146:149], v[198:201], v[102:105]
	v_mfma_f32_16x16x32_bf16 v[102:105], v[150:153], v[214:217], v[102:105]
	v_mfma_f32_16x16x32_bf16 v[98:101], v[154:157], v[198:201], v[98:101]
	v_mfma_f32_16x16x32_bf16 v[98:101], v[158:161], v[214:217], v[98:101]
	v_mfma_f32_16x16x32_bf16 v[86:89], v[146:149], v[218:221], v[86:89]
	v_mfma_f32_16x16x32_bf16 v[86:89], v[150:153], v[222:225], v[86:89]
	v_mfma_f32_16x16x32_bf16 v[82:85], v[154:157], v[218:221], v[82:85]
	v_mfma_f32_16x16x32_bf16 v[82:85], v[158:161], v[222:225], v[82:85]
	v_mfma_f32_16x16x32_bf16 v[70:73], v[146:149], v[226:229], v[70:73]
	v_mfma_f32_16x16x32_bf16 v[70:73], v[150:153], v[230:233], v[70:73]
	v_mfma_f32_16x16x32_bf16 v[66:69], v[154:157], v[226:229], v[66:69]
	v_mfma_f32_16x16x32_bf16 v[66:69], v[158:161], v[230:233], v[66:69]
	s_barrier
	ds_read_b128 v[184:187], v196 offset:49152
	ds_read_b128 v[188:191], v196 offset:50176
	ds_read_b128 v[198:201], v196 offset:51200
	ds_read_b128 v[214:217], v196 offset:52224
	ds_read_b128 v[218:221], v196 offset:53248
	ds_read_b128 v[222:225], v196 offset:54272
	ds_read_b128 v[226:229], v196 offset:55296
	ds_read_b128 v[230:233], v196 offset:56320
	s_add_i32 s20, s20, s14
	s_mov_b32 m0, s20
	v_lshl_add_u64 v[236:237], v[202:203], 0, s[34:35]
	global_load_lds_dwordx4 v[236:237], off
	v_lshl_add_u64 v[236:237], v[202:203], 0, s[38:39]
	s_add_i32 m0, s20, 0x2000
	s_add_i32 s20, s21, s14
	global_load_lds_dwordx4 v[236:237], off
	v_lshl_add_u64 v[236:237], v[202:203], 0, s[44:45]
	s_mov_b32 m0, s20
	v_lshl_add_u64 v[202:203], v[202:203], 0, s[10:11]
	global_load_lds_dwordx4 v[236:237], off
	s_add_i32 m0, s20, 0x2000
	s_nop 0
	global_load_lds_dwordx4 v[202:203], off
	v_lshl_add_u64 v[202:203], v[234:235], 0, s[34:35]
	s_mov_b32 m0, s89
	s_nop 0
	global_load_lds_dwordx4 v[202:203], off
	v_lshl_add_u64 v[202:203], v[234:235], 0, s[38:39]
	s_mov_b32 m0, s90
	s_nop 0
	global_load_lds_dwordx4 v[202:203], off
	s_waitcnt vmcnt(8)
	s_waitcnt lgkmcnt(0)
	s_barrier
	s_waitcnt lgkmcnt(0)
	v_mfma_f32_16x16x32_bf16 v[62:65], v[130:133], v[184:187], v[62:65]
	v_mfma_f32_16x16x32_bf16 v[62:65], v[134:137], v[188:191], v[62:65]
	v_mfma_f32_16x16x32_bf16 v[58:61], v[138:141], v[184:187], v[58:61]
	v_mfma_f32_16x16x32_bf16 v[58:61], v[142:145], v[188:191], v[58:61]
	v_mfma_f32_16x16x32_bf16 v[46:49], v[130:133], v[198:201], v[46:49]
	v_mfma_f32_16x16x32_bf16 v[46:49], v[134:137], v[214:217], v[46:49]
	v_mfma_f32_16x16x32_bf16 v[42:45], v[138:141], v[198:201], v[42:45]
	v_mfma_f32_16x16x32_bf16 v[42:45], v[142:145], v[214:217], v[42:45]
	v_mfma_f32_16x16x32_bf16 v[30:33], v[130:133], v[218:221], v[30:33]
	v_mfma_f32_16x16x32_bf16 v[30:33], v[134:137], v[222:225], v[30:33]
	v_mfma_f32_16x16x32_bf16 v[26:29], v[138:141], v[218:221], v[26:29]
	v_mfma_f32_16x16x32_bf16 v[26:29], v[142:145], v[222:225], v[26:29]
	v_mfma_f32_16x16x32_bf16 v[14:17], v[130:133], v[226:229], v[14:17]
	v_mfma_f32_16x16x32_bf16 v[14:17], v[134:137], v[230:233], v[14:17]
	v_mfma_f32_16x16x32_bf16 v[10:13], v[138:141], v[226:229], v[10:13]
	v_mfma_f32_16x16x32_bf16 v[10:13], v[142:145], v[230:233], v[10:13]
	s_add_i32 vcc_hi, vcc_hi, 2
	s_add_u32 s76, s76, 0x100
	s_addc_u32 s77, s77, 0
	s_add_u32 s87, s87, 0x100
	s_addc_u32 vcc_lo, vcc_lo, 0
	v_mfma_f32_16x16x32_bf16 v[54:57], v[146:149], v[184:187], v[54:57]
	v_mfma_f32_16x16x32_bf16 v[54:57], v[150:153], v[188:191], v[54:57]
	v_mfma_f32_16x16x32_bf16 v[50:53], v[154:157], v[184:187], v[50:53]
	v_mfma_f32_16x16x32_bf16 v[50:53], v[158:161], v[188:191], v[50:53]
	v_mfma_f32_16x16x32_bf16 v[38:41], v[146:149], v[198:201], v[38:41]
	v_mfma_f32_16x16x32_bf16 v[38:41], v[150:153], v[214:217], v[38:41]
	v_mfma_f32_16x16x32_bf16 v[34:37], v[154:157], v[198:201], v[34:37]
	v_mfma_f32_16x16x32_bf16 v[34:37], v[158:161], v[214:217], v[34:37]
	v_mfma_f32_16x16x32_bf16 v[22:25], v[146:149], v[218:221], v[22:25]
	v_mfma_f32_16x16x32_bf16 v[22:25], v[150:153], v[222:225], v[22:25]
	v_mfma_f32_16x16x32_bf16 v[18:21], v[154:157], v[218:221], v[18:21]
	v_mfma_f32_16x16x32_bf16 v[18:21], v[158:161], v[222:225], v[18:21]
	v_mfma_f32_16x16x32_bf16 v[6:9], v[146:149], v[226:229], v[6:9]
	v_mfma_f32_16x16x32_bf16 v[6:9], v[150:153], v[230:233], v[6:9]
	v_mfma_f32_16x16x32_bf16 v[2:5], v[154:157], v[226:229], v[2:5]
	v_mfma_f32_16x16x32_bf16 v[2:5], v[158:161], v[230:233], v[2:5]
	s_barrier
	s_branch .LBB0_778
	.p2alignl 6, 3212836864
.LBB0_778:
	s_add_i32 s22, 0, 0x10000
	s_add_i32 s23, 0, 0x14000
	v_add_u32_e32 v142, s22, v193
	v_add_u32_e32 v158, s23, v193
	ds_read_b128 v[130:133], v142
	ds_read_b128 v[134:137], v142 offset:1024
	ds_read_b128 v[138:141], v142 offset:2048
	ds_read_b128 v[142:145], v142 offset:3072
	ds_read_b128 v[146:149], v158
	ds_read_b128 v[150:153], v158 offset:1024
	ds_read_b128 v[154:157], v158 offset:2048
	ds_read_b128 v[158:161], v158 offset:3072
	ds_read_b128 v[184:187], v196
	ds_read_b128 v[188:191], v196 offset:1024
	ds_read_b128 v[198:201], v196 offset:2048
	ds_read_b128 v[214:217], v196 offset:3072
	ds_read_b128 v[218:221], v196 offset:4096
	ds_read_b128 v[222:225], v196 offset:5120
	ds_read_b128 v[226:229], v196 offset:6144
	ds_read_b128 v[230:233], v196 offset:7168
	s_add_u32 s20, s76, 0xfffc0080
	s_addc_u32 s21, s77, -1
	s_cmp_eq_u32 vcc_hi, 12
	s_cselect_b32 s79, s61, s21
	s_cselect_b32 s78, s85, s20
	s_cselect_b32 s21, s59, vcc_lo
	s_cselect_b32 s20, s86, s87
	s_add_i32 m0, s43, 0xc000
	v_lshl_add_u64 v[202:203], s[76:77], 0, v[182:183]
	global_load_lds_dwordx4 v[202:203], off
	v_lshl_add_u64 v[202:203], v[202:203], 0, s[72:73]
	s_add_i32 m0, s43, 0xe000
	s_nop 0
	global_load_lds_dwordx4 v[202:203], off
	s_waitcnt vmcnt(8)
	s_waitcnt lgkmcnt(0)
	s_barrier
	s_waitcnt lgkmcnt(0)
	v_mfma_f32_16x16x32_bf16 v[126:129], v[130:133], v[184:187], v[126:129]
	v_mfma_f32_16x16x32_bf16 v[126:129], v[134:137], v[188:191], v[126:129]
	v_mfma_f32_16x16x32_bf16 v[122:125], v[138:141], v[184:187], v[122:125]
	v_mfma_f32_16x16x32_bf16 v[122:125], v[142:145], v[188:191], v[122:125]
	v_mfma_f32_16x16x32_bf16 v[110:113], v[130:133], v[198:201], v[110:113]
	v_mfma_f32_16x16x32_bf16 v[110:113], v[134:137], v[214:217], v[110:113]
	v_mfma_f32_16x16x32_bf16 v[106:109], v[138:141], v[198:201], v[106:109]
	v_mfma_f32_16x16x32_bf16 v[106:109], v[142:145], v[214:217], v[106:109]
	v_mfma_f32_16x16x32_bf16 v[94:97], v[130:133], v[218:221], v[94:97]
	v_mfma_f32_16x16x32_bf16 v[94:97], v[134:137], v[222:225], v[94:97]
	v_mfma_f32_16x16x32_bf16 v[90:93], v[138:141], v[218:221], v[90:93]
	v_mfma_f32_16x16x32_bf16 v[90:93], v[142:145], v[222:225], v[90:93]
	v_mfma_f32_16x16x32_bf16 v[78:81], v[130:133], v[226:229], v[78:81]
	v_mfma_f32_16x16x32_bf16 v[78:81], v[134:137], v[230:233], v[78:81]
	v_mfma_f32_16x16x32_bf16 v[74:77], v[138:141], v[226:229], v[74:77]
	v_mfma_f32_16x16x32_bf16 v[74:77], v[142:145], v[230:233], v[74:77]
	v_mfma_f32_16x16x32_bf16 v[118:121], v[146:149], v[184:187], v[118:121]
	v_mfma_f32_16x16x32_bf16 v[118:121], v[150:153], v[188:191], v[118:121]
	v_mfma_f32_16x16x32_bf16 v[114:117], v[154:157], v[184:187], v[114:117]
	v_mfma_f32_16x16x32_bf16 v[114:117], v[158:161], v[188:191], v[114:117]
	v_mfma_f32_16x16x32_bf16 v[102:105], v[146:149], v[198:201], v[102:105]
	v_mfma_f32_16x16x32_bf16 v[102:105], v[150:153], v[214:217], v[102:105]
	v_mfma_f32_16x16x32_bf16 v[98:101], v[154:157], v[198:201], v[98:101]
	v_mfma_f32_16x16x32_bf16 v[98:101], v[158:161], v[214:217], v[98:101]
	v_mfma_f32_16x16x32_bf16 v[86:89], v[146:149], v[218:221], v[86:89]
	v_mfma_f32_16x16x32_bf16 v[86:89], v[150:153], v[222:225], v[86:89]
	v_mfma_f32_16x16x32_bf16 v[82:85], v[154:157], v[218:221], v[82:85]
	v_mfma_f32_16x16x32_bf16 v[82:85], v[158:161], v[222:225], v[82:85]
	v_mfma_f32_16x16x32_bf16 v[70:73], v[146:149], v[226:229], v[70:73]
	v_mfma_f32_16x16x32_bf16 v[70:73], v[150:153], v[230:233], v[70:73]
	v_mfma_f32_16x16x32_bf16 v[66:69], v[154:157], v[226:229], v[66:69]
	v_mfma_f32_16x16x32_bf16 v[66:69], v[158:161], v[230:233], v[66:69]
	s_barrier
	ds_read_b128 v[184:187], v196 offset:16384
	ds_read_b128 v[188:191], v196 offset:17408
	ds_read_b128 v[198:201], v196 offset:18432
	ds_read_b128 v[214:217], v196 offset:19456
	ds_read_b128 v[218:221], v196 offset:20480
	ds_read_b128 v[222:225], v196 offset:21504
	ds_read_b128 v[226:229], v196 offset:22528
	ds_read_b128 v[230:233], v196 offset:23552
	v_lshl_add_u64 v[202:203], s[20:21], 0, v[0:1]
	s_add_i32 s20, s22, s14
	s_mov_b32 m0, s20
	s_nop 0
	s_nop 0
	global_load_lds_dwordx4 v[202:203], off
	v_lshl_add_u64 v[234:235], v[202:203], 0, s[72:73]
	s_add_i32 m0, s20, 0x2000
	s_add_i32 s20, s23, s14
	global_load_lds_dwordx4 v[234:235], off
	v_lshl_add_u64 v[234:235], v[202:203], 0, s[28:29]
	s_mov_b32 m0, s20
	s_nop 0
	global_load_lds_dwordx4 v[234:235], off
	v_lshl_add_u64 v[234:235], v[202:203], 0, s[82:83]
	s_add_i32 m0, s20, 0x2000
	s_nop 0
	global_load_lds_dwordx4 v[234:235], off
	v_lshl_add_u64 v[234:235], s[78:79], 0, v[162:163]
	s_mov_b32 m0, s43
	v_lshl_add_u64 v[236:237], v[234:235], 0, s[72:73]
	global_load_lds_dwordx4 v[234:235], off
	s_mov_b32 m0, s46
	s_nop 0
	global_load_lds_dwordx4 v[236:237], off
	s_waitcnt vmcnt(8)
	s_waitcnt lgkmcnt(0)
	s_barrier
	s_waitcnt lgkmcnt(0)
	v_mfma_f32_16x16x32_bf16 v[62:65], v[130:133], v[184:187], v[62:65]
	v_mfma_f32_16x16x32_bf16 v[62:65], v[134:137], v[188:191], v[62:65]
	v_mfma_f32_16x16x32_bf16 v[58:61], v[138:141], v[184:187], v[58:61]
	v_mfma_f32_16x16x32_bf16 v[58:61], v[142:145], v[188:191], v[58:61]
	v_mfma_f32_16x16x32_bf16 v[46:49], v[130:133], v[198:201], v[46:49]
	v_mfma_f32_16x16x32_bf16 v[46:49], v[134:137], v[214:217], v[46:49]
	v_mfma_f32_16x16x32_bf16 v[42:45], v[138:141], v[198:201], v[42:45]
	v_mfma_f32_16x16x32_bf16 v[42:45], v[142:145], v[214:217], v[42:45]
	v_mfma_f32_16x16x32_bf16 v[30:33], v[130:133], v[218:221], v[30:33]
	v_mfma_f32_16x16x32_bf16 v[30:33], v[134:137], v[222:225], v[30:33]
	v_mfma_f32_16x16x32_bf16 v[26:29], v[138:141], v[218:221], v[26:29]
	v_mfma_f32_16x16x32_bf16 v[26:29], v[142:145], v[222:225], v[26:29]
	v_mfma_f32_16x16x32_bf16 v[14:17], v[130:133], v[226:229], v[14:17]
	v_mfma_f32_16x16x32_bf16 v[14:17], v[134:137], v[230:233], v[14:17]
	v_mfma_f32_16x16x32_bf16 v[10:13], v[138:141], v[226:229], v[10:13]
	v_mfma_f32_16x16x32_bf16 v[10:13], v[142:145], v[230:233], v[10:13]
	v_mfma_f32_16x16x32_bf16 v[54:57], v[146:149], v[184:187], v[54:57]
	v_mfma_f32_16x16x32_bf16 v[54:57], v[150:153], v[188:191], v[54:57]
	v_mfma_f32_16x16x32_bf16 v[50:53], v[154:157], v[184:187], v[50:53]
	v_mfma_f32_16x16x32_bf16 v[50:53], v[158:161], v[188:191], v[50:53]
	v_mfma_f32_16x16x32_bf16 v[38:41], v[146:149], v[198:201], v[38:41]
	v_mfma_f32_16x16x32_bf16 v[38:41], v[150:153], v[214:217], v[38:41]
	v_mfma_f32_16x16x32_bf16 v[34:37], v[154:157], v[198:201], v[34:37]
	v_mfma_f32_16x16x32_bf16 v[34:37], v[158:161], v[214:217], v[34:37]
	v_mfma_f32_16x16x32_bf16 v[22:25], v[146:149], v[218:221], v[22:25]
	v_mfma_f32_16x16x32_bf16 v[22:25], v[150:153], v[222:225], v[22:25]
	v_mfma_f32_16x16x32_bf16 v[18:21], v[154:157], v[218:221], v[18:21]
	v_mfma_f32_16x16x32_bf16 v[18:21], v[158:161], v[222:225], v[18:21]
	v_mfma_f32_16x16x32_bf16 v[6:9], v[146:149], v[226:229], v[6:9]
	v_mfma_f32_16x16x32_bf16 v[6:9], v[150:153], v[230:233], v[6:9]
	v_mfma_f32_16x16x32_bf16 v[2:5], v[154:157], v[226:229], v[2:5]
	v_mfma_f32_16x16x32_bf16 v[2:5], v[158:161], v[230:233], v[2:5]
	s_barrier
	s_add_i32 s20, 0, 0x18000
	s_add_i32 s21, 0, 0x1c000
	v_add_u32_e32 v142, s20, v193
	v_add_u32_e32 v158, s21, v193
	ds_read_b128 v[130:133], v142
	ds_read_b128 v[134:137], v142 offset:1024
	ds_read_b128 v[138:141], v142 offset:2048
	ds_read_b128 v[142:145], v142 offset:3072
	ds_read_b128 v[146:149], v158
	ds_read_b128 v[150:153], v158 offset:1024
	ds_read_b128 v[154:157], v158 offset:2048
	ds_read_b128 v[158:161], v158 offset:3072
	ds_read_b128 v[184:187], v196 offset:32768
	ds_read_b128 v[188:191], v196 offset:33792
	ds_read_b128 v[198:201], v196 offset:34816
	ds_read_b128 v[214:217], v196 offset:35840
	ds_read_b128 v[218:221], v196 offset:36864
	ds_read_b128 v[222:225], v196 offset:37888
	ds_read_b128 v[226:229], v196 offset:38912
	ds_read_b128 v[230:233], v196 offset:39936
	s_mov_b32 m0, s47
	v_lshl_add_u64 v[236:237], v[234:235], 0, s[28:29]
	global_load_lds_dwordx4 v[236:237], off
	v_lshl_add_u64 v[236:237], v[234:235], 0, s[82:83]
	s_mov_b32 m0, s88
	s_nop 0
	global_load_lds_dwordx4 v[236:237], off
	s_waitcnt vmcnt(8)
	s_waitcnt lgkmcnt(0)
	s_barrier
	s_waitcnt lgkmcnt(0)
	v_mfma_f32_16x16x32_bf16 v[126:129], v[130:133], v[184:187], v[126:129]
	v_mfma_f32_16x16x32_bf16 v[126:129], v[134:137], v[188:191], v[126:129]
	v_mfma_f32_16x16x32_bf16 v[122:125], v[138:141], v[184:187], v[122:125]
	v_mfma_f32_16x16x32_bf16 v[122:125], v[142:145], v[188:191], v[122:125]
	v_mfma_f32_16x16x32_bf16 v[110:113], v[130:133], v[198:201], v[110:113]
	v_mfma_f32_16x16x32_bf16 v[110:113], v[134:137], v[214:217], v[110:113]
	v_mfma_f32_16x16x32_bf16 v[106:109], v[138:141], v[198:201], v[106:109]
	v_mfma_f32_16x16x32_bf16 v[106:109], v[142:145], v[214:217], v[106:109]
	v_mfma_f32_16x16x32_bf16 v[94:97], v[130:133], v[218:221], v[94:97]
	v_mfma_f32_16x16x32_bf16 v[94:97], v[134:137], v[222:225], v[94:97]
	v_mfma_f32_16x16x32_bf16 v[90:93], v[138:141], v[218:221], v[90:93]
	v_mfma_f32_16x16x32_bf16 v[90:93], v[142:145], v[222:225], v[90:93]
	v_mfma_f32_16x16x32_bf16 v[78:81], v[130:133], v[226:229], v[78:81]
	v_mfma_f32_16x16x32_bf16 v[78:81], v[134:137], v[230:233], v[78:81]
	v_mfma_f32_16x16x32_bf16 v[74:77], v[138:141], v[226:229], v[74:77]
	v_mfma_f32_16x16x32_bf16 v[74:77], v[142:145], v[230:233], v[74:77]
	v_mfma_f32_16x16x32_bf16 v[118:121], v[146:149], v[184:187], v[118:121]
	v_mfma_f32_16x16x32_bf16 v[118:121], v[150:153], v[188:191], v[118:121]
	v_mfma_f32_16x16x32_bf16 v[114:117], v[154:157], v[184:187], v[114:117]
	v_mfma_f32_16x16x32_bf16 v[114:117], v[158:161], v[188:191], v[114:117]
	v_mfma_f32_16x16x32_bf16 v[102:105], v[146:149], v[198:201], v[102:105]
	v_mfma_f32_16x16x32_bf16 v[102:105], v[150:153], v[214:217], v[102:105]
	v_mfma_f32_16x16x32_bf16 v[98:101], v[154:157], v[198:201], v[98:101]
	v_mfma_f32_16x16x32_bf16 v[98:101], v[158:161], v[214:217], v[98:101]
	v_mfma_f32_16x16x32_bf16 v[86:89], v[146:149], v[218:221], v[86:89]
	v_mfma_f32_16x16x32_bf16 v[86:89], v[150:153], v[222:225], v[86:89]
	v_mfma_f32_16x16x32_bf16 v[82:85], v[154:157], v[218:221], v[82:85]
	v_mfma_f32_16x16x32_bf16 v[82:85], v[158:161], v[222:225], v[82:85]
	v_mfma_f32_16x16x32_bf16 v[70:73], v[146:149], v[226:229], v[70:73]
	v_mfma_f32_16x16x32_bf16 v[70:73], v[150:153], v[230:233], v[70:73]
	v_mfma_f32_16x16x32_bf16 v[66:69], v[154:157], v[226:229], v[66:69]
	v_mfma_f32_16x16x32_bf16 v[66:69], v[158:161], v[230:233], v[66:69]
	s_barrier
	ds_read_b128 v[184:187], v196 offset:49152
	ds_read_b128 v[188:191], v196 offset:50176
	ds_read_b128 v[198:201], v196 offset:51200
	ds_read_b128 v[214:217], v196 offset:52224
	ds_read_b128 v[218:221], v196 offset:53248
	ds_read_b128 v[222:225], v196 offset:54272
	ds_read_b128 v[226:229], v196 offset:55296
	ds_read_b128 v[230:233], v196 offset:56320
	s_add_i32 s20, s20, s14
	s_mov_b32 m0, s20
	v_lshl_add_u64 v[236:237], v[202:203], 0, s[34:35]
	global_load_lds_dwordx4 v[236:237], off
	v_lshl_add_u64 v[236:237], v[202:203], 0, s[38:39]
	s_add_i32 m0, s20, 0x2000
	s_add_i32 s20, s21, s14
	global_load_lds_dwordx4 v[236:237], off
	v_lshl_add_u64 v[236:237], v[202:203], 0, s[44:45]
	s_mov_b32 m0, s20
	v_lshl_add_u64 v[202:203], v[202:203], 0, s[10:11]
	global_load_lds_dwordx4 v[236:237], off
	s_add_i32 m0, s20, 0x2000
	s_nop 0
	global_load_lds_dwordx4 v[202:203], off
	v_lshl_add_u64 v[202:203], v[234:235], 0, s[34:35]
	s_mov_b32 m0, s89
	s_nop 0
	global_load_lds_dwordx4 v[202:203], off
	v_lshl_add_u64 v[202:203], v[234:235], 0, s[38:39]
	s_mov_b32 m0, s90
	s_nop 0
	global_load_lds_dwordx4 v[202:203], off
	s_waitcnt vmcnt(8)
	s_waitcnt lgkmcnt(0)
	s_barrier
	s_waitcnt lgkmcnt(0)
	v_mfma_f32_16x16x32_bf16 v[62:65], v[130:133], v[184:187], v[62:65]
	v_mfma_f32_16x16x32_bf16 v[62:65], v[134:137], v[188:191], v[62:65]
	v_mfma_f32_16x16x32_bf16 v[58:61], v[138:141], v[184:187], v[58:61]
	v_mfma_f32_16x16x32_bf16 v[58:61], v[142:145], v[188:191], v[58:61]
	v_mfma_f32_16x16x32_bf16 v[46:49], v[130:133], v[198:201], v[46:49]
	v_mfma_f32_16x16x32_bf16 v[46:49], v[134:137], v[214:217], v[46:49]
	v_mfma_f32_16x16x32_bf16 v[42:45], v[138:141], v[198:201], v[42:45]
	v_mfma_f32_16x16x32_bf16 v[42:45], v[142:145], v[214:217], v[42:45]
	v_mfma_f32_16x16x32_bf16 v[30:33], v[130:133], v[218:221], v[30:33]
	v_mfma_f32_16x16x32_bf16 v[30:33], v[134:137], v[222:225], v[30:33]
	v_mfma_f32_16x16x32_bf16 v[26:29], v[138:141], v[218:221], v[26:29]
	v_mfma_f32_16x16x32_bf16 v[26:29], v[142:145], v[222:225], v[26:29]
	v_mfma_f32_16x16x32_bf16 v[14:17], v[130:133], v[226:229], v[14:17]
	v_mfma_f32_16x16x32_bf16 v[14:17], v[134:137], v[230:233], v[14:17]
	v_mfma_f32_16x16x32_bf16 v[10:13], v[138:141], v[226:229], v[10:13]
	v_mfma_f32_16x16x32_bf16 v[10:13], v[142:145], v[230:233], v[10:13]
	s_add_i32 vcc_hi, vcc_hi, 2
	s_add_u32 s76, s76, 0x100
	s_addc_u32 s77, s77, 0
	s_add_u32 s87, s87, 0x100
	s_addc_u32 vcc_lo, vcc_lo, 0
	v_mfma_f32_16x16x32_bf16 v[54:57], v[146:149], v[184:187], v[54:57]
	v_mfma_f32_16x16x32_bf16 v[54:57], v[150:153], v[188:191], v[54:57]
	v_mfma_f32_16x16x32_bf16 v[50:53], v[154:157], v[184:187], v[50:53]
	v_mfma_f32_16x16x32_bf16 v[50:53], v[158:161], v[188:191], v[50:53]
	v_mfma_f32_16x16x32_bf16 v[38:41], v[146:149], v[198:201], v[38:41]
	v_mfma_f32_16x16x32_bf16 v[38:41], v[150:153], v[214:217], v[38:41]
	v_mfma_f32_16x16x32_bf16 v[34:37], v[154:157], v[198:201], v[34:37]
	v_mfma_f32_16x16x32_bf16 v[34:37], v[158:161], v[214:217], v[34:37]
	v_mfma_f32_16x16x32_bf16 v[22:25], v[146:149], v[218:221], v[22:25]
	v_mfma_f32_16x16x32_bf16 v[22:25], v[150:153], v[222:225], v[22:25]
	v_mfma_f32_16x16x32_bf16 v[18:21], v[154:157], v[218:221], v[18:21]
	v_mfma_f32_16x16x32_bf16 v[18:21], v[158:161], v[222:225], v[18:21]
	v_mfma_f32_16x16x32_bf16 v[6:9], v[146:149], v[226:229], v[6:9]
	v_mfma_f32_16x16x32_bf16 v[6:9], v[150:153], v[230:233], v[6:9]
	v_mfma_f32_16x16x32_bf16 v[2:5], v[154:157], v[226:229], v[2:5]
	v_mfma_f32_16x16x32_bf16 v[2:5], v[158:161], v[230:233], v[2:5]
	s_barrier
	s_cmp_gt_u32 vcc_hi, 13
	s_cbranch_scc0 .LBB0_778
	s_setprio 0
	s_and_b64 vcc, exec, s[50:51]
	s_cbranch_vccz .LBB0_781
	s_barrier

.LBB0_849:
	s_ashr_i32 s79, s78, 31
	s_lshl_b64 s[20:21], s[78:79], 19
	s_add_u32 s88, s4, s20
	s_addc_u32 s89, s5, s21
	s_and_b64 s[20:21], s[54:55], exec
	s_cselect_b32 s76, s89, s57
	s_cselect_b32 s77, s88, s56
	s_ashr_i32 s69, s68, 31
	s_lshl_b64 s[20:21], s[68:69], 19
	v_readlane_b32 s12, v247, 42
	s_add_u32 s94, s12, s20
	v_readlane_b32 s12, v245, 61
	s_addc_u32 s95, s12, s21
	s_and_b64 s[20:21], s[54:55], exec
	s_cselect_b32 s69, s95, s59
	s_cselect_b32 s79, s94, s58
	s_add_u32 s56, s56, 0x40080
	s_addc_u32 s57, s57, 0
	s_add_u32 s86, s58, 0x100
	v_mov_b32_e32 v2, 0
	s_addc_u32 s87, s59, 0
	s_mov_b32 s91, -2
	s_add_i32 vcc_lo, 0, 0x10000
	v_add_u32_e32 v158, vcc_lo, v145
	s_add_i32 vcc_hi, 0, 0x14000
	ds_read_b128 v[138:141], v158
	ds_read_b128 v[146:149], v158 offset:1024
	ds_read_b128 v[150:153], v158 offset:2048
	ds_read_b128 v[158:161], v158 offset:3072
	v_add_u32_e32 v194, vcc_hi, v145
	ds_read_b128 v[182:185], v194
	ds_read_b128 v[186:189], v194 offset:1024
	ds_read_b128 v[190:193], v194 offset:2048
	ds_read_b128 v[194:197], v194 offset:3072
	ds_read_b128 v[198:201], v157
	ds_read_b128 v[214:217], v157 offset:1024
	ds_read_b128 v[218:221], v157 offset:2048
	ds_read_b128 v[222:225], v157 offset:3072
	ds_read_b128 v[226:229], v157 offset:4096
	ds_read_b128 v[230:233], v157 offset:5120
	ds_read_b128 v[234:237], v157 offset:6144
	ds_read_b128 v[238:241], v157 offset:7168
	s_cmp_eq_u64 s[62:63], 0
	s_cbranch_scc0 .Lpr_850
	s_setprio 1

.Lmid1_850:
	s_add_i32 vcc_lo, 0, 0x10000
	s_add_i32 vcc_hi, 0, 0x14000
	s_add_u32 s20, s56, 0xfffc0080
	s_addc_u32 s21, s57, -1
	s_cmp_eq_u32 s91, 12
	s_cselect_b32 s59, s76, s21
	s_cselect_b32 s58, s77, s20
	s_cselect_b32 s21, s69, s87
	s_cselect_b32 s20, s79, s86
	s_add_i32 m0, s15, 0xc000
	v_lshl_add_u64 v[142:143], s[56:57], 0, v[136:137]
	global_load_lds_dwordx4 v[142:143], off
	v_lshl_add_u64 v[142:143], v[142:143], 0, s[72:73]
	s_add_i32 m0, s15, 0xe000
	s_nop 0
	global_load_lds_dwordx4 v[142:143], off
	s_waitcnt vmcnt(8)
	s_waitcnt lgkmcnt(0)
	s_barrier
	s_waitcnt lgkmcnt(0)
	v_mfma_f32_16x16x32_bf16 v[126:129], v[138:141], v[198:201], 0
	v_mfma_f32_16x16x32_bf16 v[126:129], v[146:149], v[214:217], v[126:129]
	v_mfma_f32_16x16x32_bf16 v[122:125], v[150:153], v[198:201], 0
	v_mfma_f32_16x16x32_bf16 v[122:125], v[158:161], v[214:217], v[122:125]
	v_mfma_f32_16x16x32_bf16 v[110:113], v[138:141], v[218:221], 0
	v_mfma_f32_16x16x32_bf16 v[110:113], v[146:149], v[222:225], v[110:113]
	v_mfma_f32_16x16x32_bf16 v[106:109], v[150:153], v[218:221], 0
	v_mfma_f32_16x16x32_bf16 v[106:109], v[158:161], v[222:225], v[106:109]
	v_mfma_f32_16x16x32_bf16 v[94:97], v[138:141], v[226:229], 0
	v_mfma_f32_16x16x32_bf16 v[94:97], v[146:149], v[230:233], v[94:97]
	v_mfma_f32_16x16x32_bf16 v[90:93], v[150:153], v[226:229], 0
	v_mfma_f32_16x16x32_bf16 v[90:93], v[158:161], v[230:233], v[90:93]
	v_mfma_f32_16x16x32_bf16 v[78:81], v[138:141], v[234:237], 0
	v_mfma_f32_16x16x32_bf16 v[78:81], v[146:149], v[238:241], v[78:81]
	v_mfma_f32_16x16x32_bf16 v[74:77], v[150:153], v[234:237], 0
	v_mfma_f32_16x16x32_bf16 v[74:77], v[158:161], v[238:241], v[74:77]
	v_mfma_f32_16x16x32_bf16 v[118:121], v[182:185], v[198:201], 0
	v_mfma_f32_16x16x32_bf16 v[118:121], v[186:189], v[214:217], v[118:121]
	v_mfma_f32_16x16x32_bf16 v[114:117], v[190:193], v[198:201], 0
	v_mfma_f32_16x16x32_bf16 v[114:117], v[194:197], v[214:217], v[114:117]
	v_mfma_f32_16x16x32_bf16 v[102:105], v[182:185], v[218:221], 0
	v_mfma_f32_16x16x32_bf16 v[102:105], v[186:189], v[222:225], v[102:105]
	v_mfma_f32_16x16x32_bf16 v[98:101], v[190:193], v[218:221], 0
	v_mfma_f32_16x16x32_bf16 v[98:101], v[194:197], v[222:225], v[98:101]
	v_mfma_f32_16x16x32_bf16 v[86:89], v[182:185], v[226:229], 0
	v_mfma_f32_16x16x32_bf16 v[86:89], v[186:189], v[230:233], v[86:89]
	v_mfma_f32_16x16x32_bf16 v[82:85], v[190:193], v[226:229], 0
	v_mfma_f32_16x16x32_bf16 v[82:85], v[194:197], v[230:233], v[82:85]
	v_mfma_f32_16x16x32_bf16 v[70:73], v[182:185], v[234:237], 0
	v_mfma_f32_16x16x32_bf16 v[70:73], v[186:189], v[238:241], v[70:73]
	v_mfma_f32_16x16x32_bf16 v[66:69], v[190:193], v[234:237], 0
	v_mfma_f32_16x16x32_bf16 v[66:69], v[194:197], v[238:241], v[66:69]
	s_barrier
	ds_read_b128 v[198:201], v157 offset:16384
	ds_read_b128 v[214:217], v157 offset:17408
	ds_read_b128 v[218:221], v157 offset:18432
	ds_read_b128 v[222:225], v157 offset:19456
	ds_read_b128 v[226:229], v157 offset:20480
	ds_read_b128 v[230:233], v157 offset:21504
	ds_read_b128 v[234:237], v157 offset:22528
	ds_read_b128 v[238:241], v157 offset:23552
	v_lshl_add_u64 v[142:143], s[20:21], 0, v[130:131]
	s_add_i32 s20, vcc_lo, s14
	s_mov_b32 m0, s20
	s_nop 0
	s_nop 0
	global_load_lds_dwordx4 v[142:143], off
	v_lshl_add_u64 v[162:163], v[142:143], 0, s[72:73]
	s_add_i32 m0, s20, 0x2000
	s_add_i32 s20, vcc_hi, s14
	global_load_lds_dwordx4 v[162:163], off
	v_lshl_add_u64 v[162:163], v[142:143], 0, s[28:29]
	s_mov_b32 m0, s20
	s_nop 0
	global_load_lds_dwordx4 v[162:163], off
	v_lshl_add_u64 v[162:163], v[142:143], 0, s[82:83]
	s_add_i32 m0, s20, 0x2000
	s_nop 0
	global_load_lds_dwordx4 v[162:163], off
	v_lshl_add_u64 v[162:163], s[58:59], 0, v[132:133]
	s_mov_b32 m0, s15
	v_lshl_add_u64 v[202:203], v[162:163], 0, s[72:73]
	global_load_lds_dwordx4 v[162:163], off
	s_mov_b32 m0, s42
	s_nop 0
	global_load_lds_dwordx4 v[202:203], off
	s_waitcnt vmcnt(8)
	s_waitcnt lgkmcnt(0)
	s_barrier
	s_waitcnt lgkmcnt(0)
	v_mfma_f32_16x16x32_bf16 v[62:65], v[138:141], v[198:201], 0
	v_mfma_f32_16x16x32_bf16 v[62:65], v[146:149], v[214:217], v[62:65]
	v_mfma_f32_16x16x32_bf16 v[58:61], v[150:153], v[198:201], 0
	v_mfma_f32_16x16x32_bf16 v[58:61], v[158:161], v[214:217], v[58:61]
	v_mfma_f32_16x16x32_bf16 v[46:49], v[138:141], v[218:221], 0
	v_mfma_f32_16x16x32_bf16 v[46:49], v[146:149], v[222:225], v[46:49]
	v_mfma_f32_16x16x32_bf16 v[42:45], v[150:153], v[218:221], 0
	v_mfma_f32_16x16x32_bf16 v[42:45], v[158:161], v[222:225], v[42:45]
	v_mfma_f32_16x16x32_bf16 v[30:33], v[138:141], v[226:229], 0
	v_mfma_f32_16x16x32_bf16 v[30:33], v[146:149], v[230:233], v[30:33]
	v_mfma_f32_16x16x32_bf16 v[26:29], v[150:153], v[226:229], 0
	v_mfma_f32_16x16x32_bf16 v[26:29], v[158:161], v[230:233], v[26:29]
	v_mfma_f32_16x16x32_bf16 v[14:17], v[138:141], v[234:237], 0
	v_mfma_f32_16x16x32_bf16 v[14:17], v[146:149], v[238:241], v[14:17]
	v_mfma_f32_16x16x32_bf16 v[10:13], v[150:153], v[234:237], 0
	v_mfma_f32_16x16x32_bf16 v[10:13], v[158:161], v[238:241], v[10:13]
	v_mfma_f32_16x16x32_bf16 v[54:57], v[182:185], v[198:201], 0
	v_mfma_f32_16x16x32_bf16 v[54:57], v[186:189], v[214:217], v[54:57]
	v_mfma_f32_16x16x32_bf16 v[50:53], v[190:193], v[198:201], 0
	v_mfma_f32_16x16x32_bf16 v[50:53], v[194:197], v[214:217], v[50:53]
	v_mfma_f32_16x16x32_bf16 v[38:41], v[182:185], v[218:221], 0
	v_mfma_f32_16x16x32_bf16 v[38:41], v[186:189], v[222:225], v[38:41]
	v_mfma_f32_16x16x32_bf16 v[34:37], v[190:193], v[218:221], 0
	v_mfma_f32_16x16x32_bf16 v[34:37], v[194:197], v[222:225], v[34:37]
	v_mfma_f32_16x16x32_bf16 v[22:25], v[182:185], v[226:229], 0
	v_mfma_f32_16x16x32_bf16 v[22:25], v[186:189], v[230:233], v[22:25]
	v_mfma_f32_16x16x32_bf16 v[18:21], v[190:193], v[226:229], 0
	v_mfma_f32_16x16x32_bf16 v[18:21], v[194:197], v[230:233], v[18:21]
	v_mfma_f32_16x16x32_bf16 v[6:9], v[182:185], v[234:237], 0
	v_mfma_f32_16x16x32_bf16 v[6:9], v[186:189], v[238:241], v[6:9]
	v_mfma_f32_16x16x32_bf16 v[2:5], v[190:193], v[234:237], 0
	v_mfma_f32_16x16x32_bf16 v[2:5], v[194:197], v[238:241], v[2:5]
	s_barrier
	s_add_i32 s20, 0, 0x18000
	v_add_u32_e32 v0, s20, v145
	s_add_i32 s21, 0, 0x1c000
	ds_read_b128 v[138:141], v0
	ds_read_b128 v[146:149], v0 offset:1024
	ds_read_b128 v[150:153], v0 offset:2048
	ds_read_b128 v[158:161], v0 offset:3072
	v_add_u32_e32 v0, s21, v145
	ds_read_b128 v[182:185], v0
	ds_read_b128 v[186:189], v0 offset:1024
	ds_read_b128 v[190:193], v0 offset:2048
	ds_read_b128 v[194:197], v0 offset:3072
	ds_read_b128 v[198:201], v157 offset:32768
	ds_read_b128 v[214:217], v157 offset:33792
	ds_read_b128 v[218:221], v157 offset:34816
	ds_read_b128 v[222:225], v157 offset:35840
	ds_read_b128 v[226:229], v157 offset:36864
	ds_read_b128 v[230:233], v157 offset:37888
	ds_read_b128 v[234:237], v157 offset:38912
	ds_read_b128 v[238:241], v157 offset:39936
	s_mov_b32 m0, s43
	v_lshl_add_u64 v[202:203], v[162:163], 0, s[28:29]
	global_load_lds_dwordx4 v[202:203], off
	v_lshl_add_u64 v[202:203], v[162:163], 0, s[82:83]
	s_mov_b32 m0, s46
	s_nop 0
	global_load_lds_dwordx4 v[202:203], off
	s_waitcnt vmcnt(8)
	s_waitcnt lgkmcnt(0)
	s_barrier
	s_waitcnt lgkmcnt(0)
	v_mfma_f32_16x16x32_bf16 v[126:129], v[138:141], v[198:201], v[126:129]
	v_mfma_f32_16x16x32_bf16 v[126:129], v[146:149], v[214:217], v[126:129]
	v_mfma_f32_16x16x32_bf16 v[122:125], v[150:153], v[198:201], v[122:125]
	v_mfma_f32_16x16x32_bf16 v[122:125], v[158:161], v[214:217], v[122:125]
	v_mfma_f32_16x16x32_bf16 v[110:113], v[138:141], v[218:221], v[110:113]
	v_mfma_f32_16x16x32_bf16 v[110:113], v[146:149], v[222:225], v[110:113]
	v_mfma_f32_16x16x32_bf16 v[106:109], v[150:153], v[218:221], v[106:109]
	v_mfma_f32_16x16x32_bf16 v[106:109], v[158:161], v[222:225], v[106:109]
	v_mfma_f32_16x16x32_bf16 v[94:97], v[138:141], v[226:229], v[94:97]
	v_mfma_f32_16x16x32_bf16 v[94:97], v[146:149], v[230:233], v[94:97]
	v_mfma_f32_16x16x32_bf16 v[90:93], v[150:153], v[226:229], v[90:93]
	v_mfma_f32_16x16x32_bf16 v[90:93], v[158:161], v[230:233], v[90:93]
	v_mfma_f32_16x16x32_bf16 v[78:81], v[138:141], v[234:237], v[78:81]
	v_mfma_f32_16x16x32_bf16 v[78:81], v[146:149], v[238:241], v[78:81]
	v_mfma_f32_16x16x32_bf16 v[74:77], v[150:153], v[234:237], v[74:77]
	v_mfma_f32_16x16x32_bf16 v[74:77], v[158:161], v[238:241], v[74:77]
	v_mfma_f32_16x16x32_bf16 v[118:121], v[182:185], v[198:201], v[118:121]
	v_mfma_f32_16x16x32_bf16 v[118:121], v[186:189], v[214:217], v[118:121]
	v_mfma_f32_16x16x32_bf16 v[114:117], v[190:193], v[198:201], v[114:117]
	v_mfma_f32_16x16x32_bf16 v[114:117], v[194:197], v[214:217], v[114:117]
	v_mfma_f32_16x16x32_bf16 v[102:105], v[182:185], v[218:221], v[102:105]
	v_mfma_f32_16x16x32_bf16 v[102:105], v[186:189], v[222:225], v[102:105]
	v_mfma_f32_16x16x32_bf16 v[98:101], v[190:193], v[218:221], v[98:101]
	v_mfma_f32_16x16x32_bf16 v[98:101], v[194:197], v[222:225], v[98:101]
	v_mfma_f32_16x16x32_bf16 v[86:89], v[182:185], v[226:229], v[86:89]
	v_mfma_f32_16x16x32_bf16 v[86:89], v[186:189], v[230:233], v[86:89]
	v_mfma_f32_16x16x32_bf16 v[82:85], v[190:193], v[226:229], v[82:85]
	v_mfma_f32_16x16x32_bf16 v[82:85], v[194:197], v[230:233], v[82:85]
	v_mfma_f32_16x16x32_bf16 v[70:73], v[182:185], v[234:237], v[70:73]
	v_mfma_f32_16x16x32_bf16 v[70:73], v[186:189], v[238:241], v[70:73]
	v_mfma_f32_16x16x32_bf16 v[66:69], v[190:193], v[234:237], v[66:69]
	v_mfma_f32_16x16x32_bf16 v[66:69], v[194:197], v[238:241], v[66:69]
	s_barrier
	ds_read_b128 v[198:201], v157 offset:49152
	ds_read_b128 v[214:217], v157 offset:50176
	ds_read_b128 v[218:221], v157 offset:51200
	ds_read_b128 v[222:225], v157 offset:52224
	ds_read_b128 v[226:229], v157 offset:53248
	ds_read_b128 v[230:233], v157 offset:54272
	ds_read_b128 v[234:237], v157 offset:55296
	ds_read_b128 v[238:241], v157 offset:56320
	s_add_i32 s20, s20, s14
	s_mov_b32 m0, s20
	v_lshl_add_u64 v[202:203], v[142:143], 0, s[34:35]
	global_load_lds_dwordx4 v[202:203], off
	v_lshl_add_u64 v[202:203], v[142:143], 0, s[38:39]
	s_add_i32 m0, s20, 0x2000
	s_add_i32 s20, s21, s14
	global_load_lds_dwordx4 v[202:203], off
	v_lshl_add_u64 v[202:203], v[142:143], 0, s[44:45]
	s_mov_b32 m0, s20
	v_lshl_add_u64 v[142:143], v[142:143], 0, s[10:11]
	global_load_lds_dwordx4 v[202:203], off
	s_add_i32 m0, s20, 0x2000
	s_nop 0
	global_load_lds_dwordx4 v[142:143], off
	v_lshl_add_u64 v[142:143], v[162:163], 0, s[34:35]
	s_mov_b32 m0, s47
	s_nop 0
	global_load_lds_dwordx4 v[142:143], off
	v_lshl_add_u64 v[142:143], v[162:163], 0, s[38:39]
	s_mov_b32 m0, s96
	s_nop 0
	global_load_lds_dwordx4 v[142:143], off
	s_waitcnt vmcnt(8)
	s_waitcnt lgkmcnt(0)
	s_barrier
	s_waitcnt lgkmcnt(0)
	v_mfma_f32_16x16x32_bf16 v[62:65], v[138:141], v[198:201], v[62:65]
	v_mfma_f32_16x16x32_bf16 v[62:65], v[146:149], v[214:217], v[62:65]
	v_mfma_f32_16x16x32_bf16 v[58:61], v[150:153], v[198:201], v[58:61]
	v_mfma_f32_16x16x32_bf16 v[58:61], v[158:161], v[214:217], v[58:61]
	v_mfma_f32_16x16x32_bf16 v[46:49], v[138:141], v[218:221], v[46:49]
	v_mfma_f32_16x16x32_bf16 v[46:49], v[146:149], v[222:225], v[46:49]
	v_mfma_f32_16x16x32_bf16 v[42:45], v[150:153], v[218:221], v[42:45]
	v_mfma_f32_16x16x32_bf16 v[42:45], v[158:161], v[222:225], v[42:45]
	v_mfma_f32_16x16x32_bf16 v[30:33], v[138:141], v[226:229], v[30:33]
	v_mfma_f32_16x16x32_bf16 v[30:33], v[146:149], v[230:233], v[30:33]
	v_mfma_f32_16x16x32_bf16 v[26:29], v[150:153], v[226:229], v[26:29]
	v_mfma_f32_16x16x32_bf16 v[26:29], v[158:161], v[230:233], v[26:29]
	v_mfma_f32_16x16x32_bf16 v[14:17], v[138:141], v[234:237], v[14:17]
	v_mfma_f32_16x16x32_bf16 v[14:17], v[146:149], v[238:241], v[14:17]
	v_mfma_f32_16x16x32_bf16 v[10:13], v[150:153], v[234:237], v[10:13]
	v_mfma_f32_16x16x32_bf16 v[10:13], v[158:161], v[238:241], v[10:13]
	s_add_i32 s91, s91, 2
	s_add_u32 s56, s56, 0x100
	s_addc_u32 s57, s57, 0
	s_add_u32 s86, s86, 0x100
	s_addc_u32 s87, s87, 0
	v_mfma_f32_16x16x32_bf16 v[54:57], v[182:185], v[198:201], v[54:57]
	v_mfma_f32_16x16x32_bf16 v[54:57], v[186:189], v[214:217], v[54:57]
	v_mfma_f32_16x16x32_bf16 v[50:53], v[190:193], v[198:201], v[50:53]
	v_mfma_f32_16x16x32_bf16 v[50:53], v[194:197], v[214:217], v[50:53]
	v_mfma_f32_16x16x32_bf16 v[38:41], v[182:185], v[218:221], v[38:41]
	v_mfma_f32_16x16x32_bf16 v[38:41], v[186:189], v[222:225], v[38:41]
	v_mfma_f32_16x16x32_bf16 v[34:37], v[190:193], v[218:221], v[34:37]
	v_mfma_f32_16x16x32_bf16 v[34:37], v[194:197], v[222:225], v[34:37]
	v_mfma_f32_16x16x32_bf16 v[22:25], v[182:185], v[226:229], v[22:25]
	v_mfma_f32_16x16x32_bf16 v[22:25], v[186:189], v[230:233], v[22:25]
	v_mfma_f32_16x16x32_bf16 v[18:21], v[190:193], v[226:229], v[18:21]
	v_mfma_f32_16x16x32_bf16 v[18:21], v[194:197], v[230:233], v[18:21]
	v_mfma_f32_16x16x32_bf16 v[6:9], v[182:185], v[234:237], v[6:9]
	v_mfma_f32_16x16x32_bf16 v[6:9], v[186:189], v[238:241], v[6:9]
	v_mfma_f32_16x16x32_bf16 v[2:5], v[190:193], v[234:237], v[2:5]
	v_mfma_f32_16x16x32_bf16 v[2:5], v[194:197], v[238:241], v[2:5]
	s_barrier
	s_branch .LBB0_850
	.p2alignl 6, 3212836864
.LBB0_850:
	s_add_i32 vcc_lo, 0, 0x10000
	v_add_u32_e32 v0, vcc_lo, v145
	s_add_i32 vcc_hi, 0, 0x14000
	ds_read_b128 v[138:141], v0
	ds_read_b128 v[146:149], v0 offset:1024
	ds_read_b128 v[150:153], v0 offset:2048
	ds_read_b128 v[158:161], v0 offset:3072
	v_add_u32_e32 v0, vcc_hi, v145
	ds_read_b128 v[182:185], v0
	ds_read_b128 v[186:189], v0 offset:1024
	ds_read_b128 v[190:193], v0 offset:2048
	ds_read_b128 v[194:197], v0 offset:3072
	ds_read_b128 v[198:201], v157
	ds_read_b128 v[214:217], v157 offset:1024
	ds_read_b128 v[218:221], v157 offset:2048
	ds_read_b128 v[222:225], v157 offset:3072
	ds_read_b128 v[226:229], v157 offset:4096
	ds_read_b128 v[230:233], v157 offset:5120
	ds_read_b128 v[234:237], v157 offset:6144
	ds_read_b128 v[238:241], v157 offset:7168
	s_add_u32 s20, s56, 0xfffc0080
	s_addc_u32 s21, s57, -1
	s_cmp_eq_u32 s91, 12
	s_cselect_b32 s59, s76, s21
	s_cselect_b32 s58, s77, s20
	s_cselect_b32 s21, s69, s87
	s_cselect_b32 s20, s79, s86
	s_add_i32 m0, s15, 0xc000
	v_lshl_add_u64 v[142:143], s[56:57], 0, v[136:137]
	global_load_lds_dwordx4 v[142:143], off
	v_lshl_add_u64 v[142:143], v[142:143], 0, s[72:73]
	s_add_i32 m0, s15, 0xe000
	s_nop 0
	global_load_lds_dwordx4 v[142:143], off
	s_waitcnt vmcnt(8)
	s_waitcnt lgkmcnt(0)
	s_barrier
	s_waitcnt lgkmcnt(0)
	v_mfma_f32_16x16x32_bf16 v[126:129], v[138:141], v[198:201], v[126:129]
	v_mfma_f32_16x16x32_bf16 v[126:129], v[146:149], v[214:217], v[126:129]
	v_mfma_f32_16x16x32_bf16 v[122:125], v[150:153], v[198:201], v[122:125]
	v_mfma_f32_16x16x32_bf16 v[122:125], v[158:161], v[214:217], v[122:125]
	v_mfma_f32_16x16x32_bf16 v[110:113], v[138:141], v[218:221], v[110:113]
	v_mfma_f32_16x16x32_bf16 v[110:113], v[146:149], v[222:225], v[110:113]
	v_mfma_f32_16x16x32_bf16 v[106:109], v[150:153], v[218:221], v[106:109]
	v_mfma_f32_16x16x32_bf16 v[106:109], v[158:161], v[222:225], v[106:109]
	v_mfma_f32_16x16x32_bf16 v[94:97], v[138:141], v[226:229], v[94:97]
	v_mfma_f32_16x16x32_bf16 v[94:97], v[146:149], v[230:233], v[94:97]
	v_mfma_f32_16x16x32_bf16 v[90:93], v[150:153], v[226:229], v[90:93]
	v_mfma_f32_16x16x32_bf16 v[90:93], v[158:161], v[230:233], v[90:93]
	v_mfma_f32_16x16x32_bf16 v[78:81], v[138:141], v[234:237], v[78:81]
	v_mfma_f32_16x16x32_bf16 v[78:81], v[146:149], v[238:241], v[78:81]
	v_mfma_f32_16x16x32_bf16 v[74:77], v[150:153], v[234:237], v[74:77]
	v_mfma_f32_16x16x32_bf16 v[74:77], v[158:161], v[238:241], v[74:77]
	v_mfma_f32_16x16x32_bf16 v[118:121], v[182:185], v[198:201], v[118:121]
	v_mfma_f32_16x16x32_bf16 v[118:121], v[186:189], v[214:217], v[118:121]
	v_mfma_f32_16x16x32_bf16 v[114:117], v[190:193], v[198:201], v[114:117]
	v_mfma_f32_16x16x32_bf16 v[114:117], v[194:197], v[214:217], v[114:117]
	v_mfma_f32_16x16x32_bf16 v[102:105], v[182:185], v[218:221], v[102:105]
	v_mfma_f32_16x16x32_bf16 v[102:105], v[186:189], v[222:225], v[102:105]
	v_mfma_f32_16x16x32_bf16 v[98:101], v[190:193], v[218:221], v[98:101]
	v_mfma_f32_16x16x32_bf16 v[98:101], v[194:197], v[222:225], v[98:101]
	v_mfma_f32_16x16x32_bf16 v[86:89], v[182:185], v[226:229], v[86:89]
	v_mfma_f32_16x16x32_bf16 v[86:89], v[186:189], v[230:233], v[86:89]
	v_mfma_f32_16x16x32_bf16 v[82:85], v[190:193], v[226:229], v[82:85]
	v_mfma_f32_16x16x32_bf16 v[82:85], v[194:197], v[230:233], v[82:85]
	v_mfma_f32_16x16x32_bf16 v[70:73], v[182:185], v[234:237], v[70:73]
	v_mfma_f32_16x16x32_bf16 v[70:73], v[186:189], v[238:241], v[70:73]
	v_mfma_f32_16x16x32_bf16 v[66:69], v[190:193], v[234:237], v[66:69]
	v_mfma_f32_16x16x32_bf16 v[66:69], v[194:197], v[238:241], v[66:69]
	s_barrier
	ds_read_b128 v[198:201], v157 offset:16384
	ds_read_b128 v[214:217], v157 offset:17408
	ds_read_b128 v[218:221], v157 offset:18432
	ds_read_b128 v[222:225], v157 offset:19456
	ds_read_b128 v[226:229], v157 offset:20480
	ds_read_b128 v[230:233], v157 offset:21504
	ds_read_b128 v[234:237], v157 offset:22528
	ds_read_b128 v[238:241], v157 offset:23552
	v_lshl_add_u64 v[142:143], s[20:21], 0, v[130:131]
	s_add_i32 s20, vcc_lo, s14
	s_mov_b32 m0, s20
	s_nop 0
	s_nop 0
	global_load_lds_dwordx4 v[142:143], off
	v_lshl_add_u64 v[162:163], v[142:143], 0, s[72:73]
	s_add_i32 m0, s20, 0x2000
	s_add_i32 s20, vcc_hi, s14
	global_load_lds_dwordx4 v[162:163], off
	v_lshl_add_u64 v[162:163], v[142:143], 0, s[28:29]
	s_mov_b32 m0, s20
	s_nop 0
	global_load_lds_dwordx4 v[162:163], off
	v_lshl_add_u64 v[162:163], v[142:143], 0, s[82:83]
	s_add_i32 m0, s20, 0x2000
	s_nop 0
	global_load_lds_dwordx4 v[162:163], off
	v_lshl_add_u64 v[162:163], s[58:59], 0, v[132:133]
	s_mov_b32 m0, s15
	v_lshl_add_u64 v[202:203], v[162:163], 0, s[72:73]
	global_load_lds_dwordx4 v[162:163], off
	s_mov_b32 m0, s42
	s_nop 0
	global_load_lds_dwordx4 v[202:203], off
	s_waitcnt vmcnt(8)
	s_waitcnt lgkmcnt(0)
	s_barrier
	s_waitcnt lgkmcnt(0)
	v_mfma_f32_16x16x32_bf16 v[62:65], v[138:141], v[198:201], v[62:65]
	v_mfma_f32_16x16x32_bf16 v[62:65], v[146:149], v[214:217], v[62:65]
	v_mfma_f32_16x16x32_bf16 v[58:61], v[150:153], v[198:201], v[58:61]
	v_mfma_f32_16x16x32_bf16 v[58:61], v[158:161], v[214:217], v[58:61]
	v_mfma_f32_16x16x32_bf16 v[46:49], v[138:141], v[218:221], v[46:49]
	v_mfma_f32_16x16x32_bf16 v[46:49], v[146:149], v[222:225], v[46:49]
	v_mfma_f32_16x16x32_bf16 v[42:45], v[150:153], v[218:221], v[42:45]
	v_mfma_f32_16x16x32_bf16 v[42:45], v[158:161], v[222:225], v[42:45]
	v_mfma_f32_16x16x32_bf16 v[30:33], v[138:141], v[226:229], v[30:33]
	v_mfma_f32_16x16x32_bf16 v[30:33], v[146:149], v[230:233], v[30:33]
	v_mfma_f32_16x16x32_bf16 v[26:29], v[150:153], v[226:229], v[26:29]
	v_mfma_f32_16x16x32_bf16 v[26:29], v[158:161], v[230:233], v[26:29]
	v_mfma_f32_16x16x32_bf16 v[14:17], v[138:141], v[234:237], v[14:17]
	v_mfma_f32_16x16x32_bf16 v[14:17], v[146:149], v[238:241], v[14:17]
	v_mfma_f32_16x16x32_bf16 v[10:13], v[150:153], v[234:237], v[10:13]
	v_mfma_f32_16x16x32_bf16 v[10:13], v[158:161], v[238:241], v[10:13]
	v_mfma_f32_16x16x32_bf16 v[54:57], v[182:185], v[198:201], v[54:57]
	v_mfma_f32_16x16x32_bf16 v[54:57], v[186:189], v[214:217], v[54:57]
	v_mfma_f32_16x16x32_bf16 v[50:53], v[190:193], v[198:201], v[50:53]
	v_mfma_f32_16x16x32_bf16 v[50:53], v[194:197], v[214:217], v[50:53]
	v_mfma_f32_16x16x32_bf16 v[38:41], v[182:185], v[218:221], v[38:41]
	v_mfma_f32_16x16x32_bf16 v[38:41], v[186:189], v[222:225], v[38:41]
	v_mfma_f32_16x16x32_bf16 v[34:37], v[190:193], v[218:221], v[34:37]
	v_mfma_f32_16x16x32_bf16 v[34:37], v[194:197], v[222:225], v[34:37]
	v_mfma_f32_16x16x32_bf16 v[22:25], v[182:185], v[226:229], v[22:25]
	v_mfma_f32_16x16x32_bf16 v[22:25], v[186:189], v[230:233], v[22:25]
	v_mfma_f32_16x16x32_bf16 v[18:21], v[190:193], v[226:229], v[18:21]
	v_mfma_f32_16x16x32_bf16 v[18:21], v[194:197], v[230:233], v[18:21]
	v_mfma_f32_16x16x32_bf16 v[6:9], v[182:185], v[234:237], v[6:9]
	v_mfma_f32_16x16x32_bf16 v[6:9], v[186:189], v[238:241], v[6:9]
	v_mfma_f32_16x16x32_bf16 v[2:5], v[190:193], v[234:237], v[2:5]
	v_mfma_f32_16x16x32_bf16 v[2:5], v[194:197], v[238:241], v[2:5]
	s_barrier
	s_add_i32 s20, 0, 0x18000
	v_add_u32_e32 v0, s20, v145
	s_add_i32 s21, 0, 0x1c000
	ds_read_b128 v[138:141], v0
	ds_read_b128 v[146:149], v0 offset:1024
	ds_read_b128 v[150:153], v0 offset:2048
	ds_read_b128 v[158:161], v0 offset:3072
	v_add_u32_e32 v0, s21, v145
	ds_read_b128 v[182:185], v0
	ds_read_b128 v[186:189], v0 offset:1024
	ds_read_b128 v[190:193], v0 offset:2048
	ds_read_b128 v[194:197], v0 offset:3072
	ds_read_b128 v[198:201], v157 offset:32768
	ds_read_b128 v[214:217], v157 offset:33792
	ds_read_b128 v[218:221], v157 offset:34816
	ds_read_b128 v[222:225], v157 offset:35840
	ds_read_b128 v[226:229], v157 offset:36864
	ds_read_b128 v[230:233], v157 offset:37888
	ds_read_b128 v[234:237], v157 offset:38912
	ds_read_b128 v[238:241], v157 offset:39936
	s_mov_b32 m0, s43
	v_lshl_add_u64 v[202:203], v[162:163], 0, s[28:29]
	global_load_lds_dwordx4 v[202:203], off
	v_lshl_add_u64 v[202:203], v[162:163], 0, s[82:83]
	s_mov_b32 m0, s46
	s_nop 0
	global_load_lds_dwordx4 v[202:203], off
	s_waitcnt vmcnt(8)
	s_waitcnt lgkmcnt(0)
	s_barrier
	s_waitcnt lgkmcnt(0)
	v_mfma_f32_16x16x32_bf16 v[126:129], v[138:141], v[198:201], v[126:129]
	v_mfma_f32_16x16x32_bf16 v[126:129], v[146:149], v[214:217], v[126:129]
	v_mfma_f32_16x16x32_bf16 v[122:125], v[150:153], v[198:201], v[122:125]
	v_mfma_f32_16x16x32_bf16 v[122:125], v[158:161], v[214:217], v[122:125]
	v_mfma_f32_16x16x32_bf16 v[110:113], v[138:141], v[218:221], v[110:113]
	v_mfma_f32_16x16x32_bf16 v[110:113], v[146:149], v[222:225], v[110:113]
	v_mfma_f32_16x16x32_bf16 v[106:109], v[150:153], v[218:221], v[106:109]
	v_mfma_f32_16x16x32_bf16 v[106:109], v[158:161], v[222:225], v[106:109]
	v_mfma_f32_16x16x32_bf16 v[94:97], v[138:141], v[226:229], v[94:97]
	v_mfma_f32_16x16x32_bf16 v[94:97], v[146:149], v[230:233], v[94:97]
	v_mfma_f32_16x16x32_bf16 v[90:93], v[150:153], v[226:229], v[90:93]
	v_mfma_f32_16x16x32_bf16 v[90:93], v[158:161], v[230:233], v[90:93]
	v_mfma_f32_16x16x32_bf16 v[78:81], v[138:141], v[234:237], v[78:81]
	v_mfma_f32_16x16x32_bf16 v[78:81], v[146:149], v[238:241], v[78:81]
	v_mfma_f32_16x16x32_bf16 v[74:77], v[150:153], v[234:237], v[74:77]
	v_mfma_f32_16x16x32_bf16 v[74:77], v[158:161], v[238:241], v[74:77]
	v_mfma_f32_16x16x32_bf16 v[118:121], v[182:185], v[198:201], v[118:121]
	v_mfma_f32_16x16x32_bf16 v[118:121], v[186:189], v[214:217], v[118:121]
	v_mfma_f32_16x16x32_bf16 v[114:117], v[190:193], v[198:201], v[114:117]
	v_mfma_f32_16x16x32_bf16 v[114:117], v[194:197], v[214:217], v[114:117]
	v_mfma_f32_16x16x32_bf16 v[102:105], v[182:185], v[218:221], v[102:105]
	v_mfma_f32_16x16x32_bf16 v[102:105], v[186:189], v[222:225], v[102:105]
	v_mfma_f32_16x16x32_bf16 v[98:101], v[190:193], v[218:221], v[98:101]
	v_mfma_f32_16x16x32_bf16 v[98:101], v[194:197], v[222:225], v[98:101]
	v_mfma_f32_16x16x32_bf16 v[86:89], v[182:185], v[226:229], v[86:89]
	v_mfma_f32_16x16x32_bf16 v[86:89], v[186:189], v[230:233], v[86:89]
	v_mfma_f32_16x16x32_bf16 v[82:85], v[190:193], v[226:229], v[82:85]
	v_mfma_f32_16x16x32_bf16 v[82:85], v[194:197], v[230:233], v[82:85]
	v_mfma_f32_16x16x32_bf16 v[70:73], v[182:185], v[234:237], v[70:73]
	v_mfma_f32_16x16x32_bf16 v[70:73], v[186:189], v[238:241], v[70:73]
	v_mfma_f32_16x16x32_bf16 v[66:69], v[190:193], v[234:237], v[66:69]
	v_mfma_f32_16x16x32_bf16 v[66:69], v[194:197], v[238:241], v[66:69]
	s_barrier
	ds_read_b128 v[198:201], v157 offset:49152
	ds_read_b128 v[214:217], v157 offset:50176
	ds_read_b128 v[218:221], v157 offset:51200
	ds_read_b128 v[222:225], v157 offset:52224
	ds_read_b128 v[226:229], v157 offset:53248
	ds_read_b128 v[230:233], v157 offset:54272
	ds_read_b128 v[234:237], v157 offset:55296
	ds_read_b128 v[238:241], v157 offset:56320
	s_add_i32 s20, s20, s14
	s_mov_b32 m0, s20
	v_lshl_add_u64 v[202:203], v[142:143], 0, s[34:35]
	global_load_lds_dwordx4 v[202:203], off
	v_lshl_add_u64 v[202:203], v[142:143], 0, s[38:39]
	s_add_i32 m0, s20, 0x2000
	s_add_i32 s20, s21, s14
	global_load_lds_dwordx4 v[202:203], off
	v_lshl_add_u64 v[202:203], v[142:143], 0, s[44:45]
	s_mov_b32 m0, s20
	v_lshl_add_u64 v[142:143], v[142:143], 0, s[10:11]
	global_load_lds_dwordx4 v[202:203], off
	s_add_i32 m0, s20, 0x2000
	s_nop 0
	global_load_lds_dwordx4 v[142:143], off
	v_lshl_add_u64 v[142:143], v[162:163], 0, s[34:35]
	s_mov_b32 m0, s47
	s_nop 0
	global_load_lds_dwordx4 v[142:143], off
	v_lshl_add_u64 v[142:143], v[162:163], 0, s[38:39]
	s_mov_b32 m0, s96
	s_nop 0
	global_load_lds_dwordx4 v[142:143], off
	s_waitcnt vmcnt(8)
	s_waitcnt lgkmcnt(0)
	s_barrier
	s_waitcnt lgkmcnt(0)
	v_mfma_f32_16x16x32_bf16 v[62:65], v[138:141], v[198:201], v[62:65]
	v_mfma_f32_16x16x32_bf16 v[62:65], v[146:149], v[214:217], v[62:65]
	v_mfma_f32_16x16x32_bf16 v[58:61], v[150:153], v[198:201], v[58:61]
	v_mfma_f32_16x16x32_bf16 v[58:61], v[158:161], v[214:217], v[58:61]
	v_mfma_f32_16x16x32_bf16 v[46:49], v[138:141], v[218:221], v[46:49]
	v_mfma_f32_16x16x32_bf16 v[46:49], v[146:149], v[222:225], v[46:49]
	v_mfma_f32_16x16x32_bf16 v[42:45], v[150:153], v[218:221], v[42:45]
	v_mfma_f32_16x16x32_bf16 v[42:45], v[158:161], v[222:225], v[42:45]
	v_mfma_f32_16x16x32_bf16 v[30:33], v[138:141], v[226:229], v[30:33]
	v_mfma_f32_16x16x32_bf16 v[30:33], v[146:149], v[230:233], v[30:33]
	v_mfma_f32_16x16x32_bf16 v[26:29], v[150:153], v[226:229], v[26:29]
	v_mfma_f32_16x16x32_bf16 v[26:29], v[158:161], v[230:233], v[26:29]
	v_mfma_f32_16x16x32_bf16 v[14:17], v[138:141], v[234:237], v[14:17]
	v_mfma_f32_16x16x32_bf16 v[14:17], v[146:149], v[238:241], v[14:17]
	v_mfma_f32_16x16x32_bf16 v[10:13], v[150:153], v[234:237], v[10:13]
	v_mfma_f32_16x16x32_bf16 v[10:13], v[158:161], v[238:241], v[10:13]
	s_add_i32 s91, s91, 2
	s_add_u32 s56, s56, 0x100
	s_addc_u32 s57, s57, 0
	s_add_u32 s86, s86, 0x100
	s_addc_u32 s87, s87, 0
	v_mfma_f32_16x16x32_bf16 v[54:57], v[182:185], v[198:201], v[54:57]
	v_mfma_f32_16x16x32_bf16 v[54:57], v[186:189], v[214:217], v[54:57]
	v_mfma_f32_16x16x32_bf16 v[50:53], v[190:193], v[198:201], v[50:53]
	v_mfma_f32_16x16x32_bf16 v[50:53], v[194:197], v[214:217], v[50:53]
	v_mfma_f32_16x16x32_bf16 v[38:41], v[182:185], v[218:221], v[38:41]
	v_mfma_f32_16x16x32_bf16 v[38:41], v[186:189], v[222:225], v[38:41]
	v_mfma_f32_16x16x32_bf16 v[34:37], v[190:193], v[218:221], v[34:37]
	v_mfma_f32_16x16x32_bf16 v[34:37], v[194:197], v[222:225], v[34:37]
	v_mfma_f32_16x16x32_bf16 v[22:25], v[182:185], v[226:229], v[22:25]
	v_mfma_f32_16x16x32_bf16 v[22:25], v[186:189], v[230:233], v[22:25]
	v_mfma_f32_16x16x32_bf16 v[18:21], v[190:193], v[226:229], v[18:21]
	v_mfma_f32_16x16x32_bf16 v[18:21], v[194:197], v[230:233], v[18:21]
	v_mfma_f32_16x16x32_bf16 v[6:9], v[182:185], v[234:237], v[6:9]
	v_mfma_f32_16x16x32_bf16 v[6:9], v[186:189], v[238:241], v[6:9]
	v_mfma_f32_16x16x32_bf16 v[2:5], v[190:193], v[234:237], v[2:5]
	v_mfma_f32_16x16x32_bf16 v[2:5], v[194:197], v[238:241], v[2:5]
	s_barrier
	s_cmp_gt_u32 s91, 13
	s_cbranch_scc0 .LBB0_850
	s_setprio 0
	s_and_b64 vcc, exec, s[62:63]
	s_cbranch_vccz .LBB0_853
	s_barrier
